# pool phase rewritten: wave-uniform window, all row loads in flight; grid barrier after weight conversion replaced by workgroup barrier
# speedup vs baseline: 1.0184x; 1.0067x over previous
; __global__ void __launch_bounds__(NTHR, 2) fwd_kernel(Args a) {
;     ...
;         if (ph + 1 < a.ph_hi) {
;             if (!xb_ready) { grid.sync(); xb = xcd_barrier_post(barw, bst); xb_ready = true; }
;             else { xcd_barrier(xb); if (DUP_K == 100) { xcd_barrier(xb); xcd_barrier(xb); } }
;         }
.Lhop_541:
	s_branch .LBB0_541

; __device__ __forceinline__ int my_tid() { int t = threadIdx.x; asm volatile("" : "+v"(t)); return t; }
; __device__ __forceinline__ void phase_pool(const bf16_t* proj, bf16_t* pooled) {
;     const int tid = my_tid();
;     for (int idx = blockIdx.x * NTHR + tid; idx < (TG / 16) * 128; idx += gridDim.x * NTHR) {
;         const int cgi = idx & 127, seg = idx >> 7, r0 = seg * 16, pos0 = r0 & (SEQ - 1), w = 2 << (cgi >> 5);
;         const bf16_t* src = proj + SEC(C_PU) + (size_t)r0 * PP + cgi * 8;
;         float sum[8];
; #pragma unroll
;         for (int e = 0; e < 8; ++e) sum[e] = 0.f;
;         if (pos0 > 0) for (int j = 1; j < w; ++j) { float f[8]; unpack8(*(const u32x4*)(src - (ptrdiff_t)j * PP), f);
; #pragma unroll
;             for (int e = 0; e < 8; ++e) sum[e] += f[e]; }
.LBB0_311:
	s_or_b64 exec, exec, s[4:5]
	s_mov_b64 s[0:1], exec
	v_readlane_b32 s4, v252, 16
	v_readlane_b32 s5, v252, 17
	s_mov_b32 s6, 0x800
	s_mov_b32 s7, 0
	s_mov_b32 s8, 0xfffff800
	s_mov_b32 s9, -1
	s_mov_b32 s10, s33
	v_readfirstlane_b32 s11, v194
	s_nop 3
	s_lshr_b32 s11, s11, 6
.Lmy_pool_item:
	s_cmp_lt_u32 s10, 0x100
	s_cbranch_scc0 .Lmy_pool_done
	v_and_b32_e32 v0, 63, v194
	v_and_b32_e32 v2, 31, v0
	s_and_b32 s98, s11, 3
	s_lshl_b32 s99, s98, 5
	v_add_u32_e32 v2, s99, v2
	v_lshrrev_b32_e32 v3, 5, v0
	s_lshr_b32 s99, s11, 2
	s_lshl_b32 s99, s99, 1
	s_lshl_b32 s100, s10, 2
	s_add_u32 s99, s99, s100
	v_add_u32_e32 v3, s99, v3
	v_lshlrev_b32_e32 v3, 4, v3
	v_and_b32_e32 v4, 0xfff, v3
	v_cmp_ne_u32_e64 s[2:3], 0, v4
	v_lshlrev_b32_e32 v12, 4, v2
	v_mov_b32_e32 v13, 0
	v_mov_b32_e32 v14, v3
	v_mov_b32_e32 v15, 0
	v_lshlrev_b64 v[14:15], 11, v[14:15]
	v_lshl_add_u64 v[14:15], v[14:15], 0, v[12:13]
	v_lshl_add_u64 v[6:7], v[14:15], 0, s[4:5]
	v_lshl_add_u64 v[8:9], v[14:15], 0, s[72:73]
	s_cmp_eq_u32 s98, 0
	s_cbranch_scc1 .Lmy_pool_w2
	s_cmp_eq_u32 s98, 1
	s_cbranch_scc1 .Lmy_pool_w4
	s_cmp_eq_u32 s98, 2
	s_cbranch_scc1 .Lmy_pool_w8
.Lmy_pool_w16:
	v_lshl_add_u64 v[10:11], v[6:7], 0, s[8:9]
	global_load_dwordx4 v[60:63], v[10:11], off
	v_lshl_add_u64 v[10:11], v[10:11], 0, s[8:9]
	global_load_dwordx4 v[64:67], v[10:11], off
	v_lshl_add_u64 v[10:11], v[10:11], 0, s[8:9]
	global_load_dwordx4 v[68:71], v[10:11], off
	v_lshl_add_u64 v[10:11], v[10:11], 0, s[8:9]
	global_load_dwordx4 v[72:75], v[10:11], off
	v_lshl_add_u64 v[10:11], v[10:11], 0, s[8:9]
	global_load_dwordx4 v[76:79], v[10:11], off
	v_lshl_add_u64 v[10:11], v[10:11], 0, s[8:9]
	global_load_dwordx4 v[80:83], v[10:11], off
	v_lshl_add_u64 v[10:11], v[10:11], 0, s[8:9]
	global_load_dwordx4 v[84:87], v[10:11], off
	v_lshl_add_u64 v[10:11], v[10:11], 0, s[8:9]
	global_load_dwordx4 v[88:91], v[10:11], off
	v_lshl_add_u64 v[10:11], v[10:11], 0, s[8:9]
	global_load_dwordx4 v[92:95], v[10:11], off
	v_lshl_add_u64 v[10:11], v[10:11], 0, s[8:9]
	global_load_dwordx4 v[96:99], v[10:11], off
	v_lshl_add_u64 v[10:11], v[10:11], 0, s[8:9]
	global_load_dwordx4 v[100:103], v[10:11], off
	v_lshl_add_u64 v[10:11], v[10:11], 0, s[8:9]
	global_load_dwordx4 v[104:107], v[10:11], off
	v_lshl_add_u64 v[10:11], v[10:11], 0, s[8:9]
	global_load_dwordx4 v[108:111], v[10:11], off
	v_lshl_add_u64 v[10:11], v[10:11], 0, s[8:9]
	global_load_dwordx4 v[112:115], v[10:11], off
	v_lshl_add_u64 v[10:11], v[10:11], 0, s[8:9]
	global_load_dwordx4 v[116:119], v[10:11], off
	v_mov_b32_e32 v10, v6
	v_mov_b32_e32 v11, v7
	global_load_dwordx4 v[120:123], v[10:11], off
	v_lshl_add_u64 v[10:11], v[10:11], 0, s[6:7]
	global_load_dwordx4 v[124:127], v[10:11], off
	v_lshl_add_u64 v[10:11], v[10:11], 0, s[6:7]
	global_load_dwordx4 v[128:131], v[10:11], off
	v_lshl_add_u64 v[10:11], v[10:11], 0, s[6:7]
	global_load_dwordx4 v[132:135], v[10:11], off
	v_lshl_add_u64 v[10:11], v[10:11], 0, s[6:7]
	global_load_dwordx4 v[136:139], v[10:11], off
	v_lshl_add_u64 v[10:11], v[10:11], 0, s[6:7]
	global_load_dwordx4 v[140:143], v[10:11], off
	v_lshl_add_u64 v[10:11], v[10:11], 0, s[6:7]
	global_load_dwordx4 v[144:147], v[10:11], off
	v_lshl_add_u64 v[10:11], v[10:11], 0, s[6:7]
	global_load_dwordx4 v[148:151], v[10:11], off
	v_lshl_add_u64 v[10:11], v[10:11], 0, s[6:7]
	global_load_dwordx4 v[152:155], v[10:11], off
	v_lshl_add_u64 v[10:11], v[10:11], 0, s[6:7]
	global_load_dwordx4 v[156:159], v[10:11], off
	v_lshl_add_u64 v[10:11], v[10:11], 0, s[6:7]
	global_load_dwordx4 v[160:163], v[10:11], off
	v_lshl_add_u64 v[10:11], v[10:11], 0, s[6:7]
	global_load_dwordx4 v[164:167], v[10:11], off
	v_lshl_add_u64 v[10:11], v[10:11], 0, s[6:7]
	global_load_dwordx4 v[168:171], v[10:11], off
	v_lshl_add_u64 v[10:11], v[10:11], 0, s[6:7]
	global_load_dwordx4 v[172:175], v[10:11], off
	v_lshl_add_u64 v[10:11], v[10:11], 0, s[6:7]
	global_load_dwordx4 v[176:179], v[10:11], off
	v_lshl_add_u64 v[10:11], v[10:11], 0, s[6:7]
	global_load_dwordx4 v[180:183], v[10:11], off
	v_mov_b32_e32 v20, 0
	v_mov_b32_e32 v21, 0
	v_mov_b32_e32 v22, 0
	v_mov_b32_e32 v23, 0
	v_mov_b32_e32 v24, 0
	v_mov_b32_e32 v25, 0
	v_mov_b32_e32 v26, 0
	v_mov_b32_e32 v27, 0
	s_waitcnt vmcnt(30)
	v_lshlrev_b32_e32 v28, 16, v60
	v_and_b32_e32 v29, 0xffff0000, v60
	v_lshlrev_b32_e32 v30, 16, v61
	v_and_b32_e32 v31, 0xffff0000, v61
	v_lshlrev_b32_e32 v32, 16, v62
	v_and_b32_e32 v33, 0xffff0000, v62
	v_lshlrev_b32_e32 v34, 16, v63
	v_and_b32_e32 v35, 0xffff0000, v63
	v_cndmask_b32_e64 v28, 0, v28, s[2:3]
	v_cndmask_b32_e64 v29, 0, v29, s[2:3]
	v_cndmask_b32_e64 v30, 0, v30, s[2:3]
	v_cndmask_b32_e64 v31, 0, v31, s[2:3]
	v_cndmask_b32_e64 v32, 0, v32, s[2:3]
	v_cndmask_b32_e64 v33, 0, v33, s[2:3]
	v_cndmask_b32_e64 v34, 0, v34, s[2:3]
	v_cndmask_b32_e64 v35, 0, v35, s[2:3]
	v_add_f32_e32 v20, v20, v28
	v_add_f32_e32 v21, v21, v29
	v_add_f32_e32 v22, v22, v30
	v_add_f32_e32 v23, v23, v31
	v_add_f32_e32 v24, v24, v32
	v_add_f32_e32 v25, v25, v33
	v_add_f32_e32 v26, v26, v34
	v_add_f32_e32 v27, v27, v35
	s_waitcnt vmcnt(29)
	v_lshlrev_b32_e32 v28, 16, v64
	v_and_b32_e32 v29, 0xffff0000, v64
	v_lshlrev_b32_e32 v30, 16, v65
	v_and_b32_e32 v31, 0xffff0000, v65
	v_lshlrev_b32_e32 v32, 16, v66
	v_and_b32_e32 v33, 0xffff0000, v66
	v_lshlrev_b32_e32 v34, 16, v67
	v_and_b32_e32 v35, 0xffff0000, v67
	v_cndmask_b32_e64 v28, 0, v28, s[2:3]
	v_cndmask_b32_e64 v29, 0, v29, s[2:3]
	v_cndmask_b32_e64 v30, 0, v30, s[2:3]
	v_cndmask_b32_e64 v31, 0, v31, s[2:3]
	v_cndmask_b32_e64 v32, 0, v32, s[2:3]
	v_cndmask_b32_e64 v33, 0, v33, s[2:3]
	v_cndmask_b32_e64 v34, 0, v34, s[2:3]
	v_cndmask_b32_e64 v35, 0, v35, s[2:3]
	v_add_f32_e32 v20, v20, v28
	v_add_f32_e32 v21, v21, v29
	v_add_f32_e32 v22, v22, v30
	v_add_f32_e32 v23, v23, v31
	v_add_f32_e32 v24, v24, v32
	v_add_f32_e32 v25, v25, v33
	v_add_f32_e32 v26, v26, v34
	v_add_f32_e32 v27, v27, v35
	s_waitcnt vmcnt(28)
; __device__ __forceinline__ void phase_pool(const bf16_t* proj, bf16_t* pooled) {
;     ...
;         if (pos0 > 0) for (int j = 1; j < w; ++j) { float f[8]; unpack8(*(const u32x4*)(src - (ptrdiff_t)j * PP), f);
; #pragma unroll
;             for (int e = 0; e < 8; ++e) sum[e] += f[e]; }
	v_lshlrev_b32_e32 v28, 16, v68
	v_and_b32_e32 v29, 0xffff0000, v68
	v_lshlrev_b32_e32 v30, 16, v69
	v_and_b32_e32 v31, 0xffff0000, v69
	v_lshlrev_b32_e32 v32, 16, v70
	v_and_b32_e32 v33, 0xffff0000, v70
	v_lshlrev_b32_e32 v34, 16, v71
	v_and_b32_e32 v35, 0xffff0000, v71
	v_cndmask_b32_e64 v28, 0, v28, s[2:3]
	v_cndmask_b32_e64 v29, 0, v29, s[2:3]
	v_cndmask_b32_e64 v30, 0, v30, s[2:3]
	v_cndmask_b32_e64 v31, 0, v31, s[2:3]
	v_cndmask_b32_e64 v32, 0, v32, s[2:3]
	v_cndmask_b32_e64 v33, 0, v33, s[2:3]
	v_cndmask_b32_e64 v34, 0, v34, s[2:3]
	v_cndmask_b32_e64 v35, 0, v35, s[2:3]
	v_add_f32_e32 v20, v20, v28
	v_add_f32_e32 v21, v21, v29
	v_add_f32_e32 v22, v22, v30
	v_add_f32_e32 v23, v23, v31
	v_add_f32_e32 v24, v24, v32
	v_add_f32_e32 v25, v25, v33
	v_add_f32_e32 v26, v26, v34
	v_add_f32_e32 v27, v27, v35
	s_waitcnt vmcnt(27)
	v_lshlrev_b32_e32 v28, 16, v72
	v_and_b32_e32 v29, 0xffff0000, v72
	v_lshlrev_b32_e32 v30, 16, v73
	v_and_b32_e32 v31, 0xffff0000, v73
	v_lshlrev_b32_e32 v32, 16, v74
	v_and_b32_e32 v33, 0xffff0000, v74
	v_lshlrev_b32_e32 v34, 16, v75
	v_and_b32_e32 v35, 0xffff0000, v75
	v_cndmask_b32_e64 v28, 0, v28, s[2:3]
	v_cndmask_b32_e64 v29, 0, v29, s[2:3]
	v_cndmask_b32_e64 v30, 0, v30, s[2:3]
	v_cndmask_b32_e64 v31, 0, v31, s[2:3]
	v_cndmask_b32_e64 v32, 0, v32, s[2:3]
	v_cndmask_b32_e64 v33, 0, v33, s[2:3]
	v_cndmask_b32_e64 v34, 0, v34, s[2:3]
	v_cndmask_b32_e64 v35, 0, v35, s[2:3]
	v_add_f32_e32 v20, v20, v28
	v_add_f32_e32 v21, v21, v29
	v_add_f32_e32 v22, v22, v30
	v_add_f32_e32 v23, v23, v31
	v_add_f32_e32 v24, v24, v32
	v_add_f32_e32 v25, v25, v33
	v_add_f32_e32 v26, v26, v34
	v_add_f32_e32 v27, v27, v35
	s_waitcnt vmcnt(26)
	v_lshlrev_b32_e32 v28, 16, v76
	v_and_b32_e32 v29, 0xffff0000, v76
	v_lshlrev_b32_e32 v30, 16, v77
	v_and_b32_e32 v31, 0xffff0000, v77
	v_lshlrev_b32_e32 v32, 16, v78
	v_and_b32_e32 v33, 0xffff0000, v78
	v_lshlrev_b32_e32 v34, 16, v79
	v_and_b32_e32 v35, 0xffff0000, v79
	v_cndmask_b32_e64 v28, 0, v28, s[2:3]
	v_cndmask_b32_e64 v29, 0, v29, s[2:3]
	v_cndmask_b32_e64 v30, 0, v30, s[2:3]
	v_cndmask_b32_e64 v31, 0, v31, s[2:3]
	v_cndmask_b32_e64 v32, 0, v32, s[2:3]
	v_cndmask_b32_e64 v33, 0, v33, s[2:3]
	v_cndmask_b32_e64 v34, 0, v34, s[2:3]
	v_cndmask_b32_e64 v35, 0, v35, s[2:3]
	v_add_f32_e32 v20, v20, v28
	v_add_f32_e32 v21, v21, v29
	v_add_f32_e32 v22, v22, v30
	v_add_f32_e32 v23, v23, v31
	v_add_f32_e32 v24, v24, v32
	v_add_f32_e32 v25, v25, v33
	v_add_f32_e32 v26, v26, v34
	v_add_f32_e32 v27, v27, v35
	s_waitcnt vmcnt(25)
	v_lshlrev_b32_e32 v28, 16, v80
	v_and_b32_e32 v29, 0xffff0000, v80
	v_lshlrev_b32_e32 v30, 16, v81
	v_and_b32_e32 v31, 0xffff0000, v81
	v_lshlrev_b32_e32 v32, 16, v82
	v_and_b32_e32 v33, 0xffff0000, v82
	v_lshlrev_b32_e32 v34, 16, v83
	v_and_b32_e32 v35, 0xffff0000, v83
	v_cndmask_b32_e64 v28, 0, v28, s[2:3]
	v_cndmask_b32_e64 v29, 0, v29, s[2:3]
	v_cndmask_b32_e64 v30, 0, v30, s[2:3]
	v_cndmask_b32_e64 v31, 0, v31, s[2:3]
	v_cndmask_b32_e64 v32, 0, v32, s[2:3]
	v_cndmask_b32_e64 v33, 0, v33, s[2:3]
	v_cndmask_b32_e64 v34, 0, v34, s[2:3]
	v_cndmask_b32_e64 v35, 0, v35, s[2:3]
	v_add_f32_e32 v20, v20, v28
	v_add_f32_e32 v21, v21, v29
	v_add_f32_e32 v22, v22, v30
	v_add_f32_e32 v23, v23, v31
	v_add_f32_e32 v24, v24, v32
	v_add_f32_e32 v25, v25, v33
	v_add_f32_e32 v26, v26, v34
	v_add_f32_e32 v27, v27, v35
	s_waitcnt vmcnt(24)
	v_lshlrev_b32_e32 v28, 16, v84
	v_and_b32_e32 v29, 0xffff0000, v84
	v_lshlrev_b32_e32 v30, 16, v85
	v_and_b32_e32 v31, 0xffff0000, v85
	v_lshlrev_b32_e32 v32, 16, v86
	v_and_b32_e32 v33, 0xffff0000, v86
	v_lshlrev_b32_e32 v34, 16, v87
	v_and_b32_e32 v35, 0xffff0000, v87
	v_cndmask_b32_e64 v28, 0, v28, s[2:3]
	v_cndmask_b32_e64 v29, 0, v29, s[2:3]
	v_cndmask_b32_e64 v30, 0, v30, s[2:3]
	v_cndmask_b32_e64 v31, 0, v31, s[2:3]
	v_cndmask_b32_e64 v32, 0, v32, s[2:3]
	v_cndmask_b32_e64 v33, 0, v33, s[2:3]
	v_cndmask_b32_e64 v34, 0, v34, s[2:3]
	v_cndmask_b32_e64 v35, 0, v35, s[2:3]
	v_add_f32_e32 v20, v20, v28
	v_add_f32_e32 v21, v21, v29
	v_add_f32_e32 v22, v22, v30
	v_add_f32_e32 v23, v23, v31
	v_add_f32_e32 v24, v24, v32
	v_add_f32_e32 v25, v25, v33
	v_add_f32_e32 v26, v26, v34
	v_add_f32_e32 v27, v27, v35
	s_waitcnt vmcnt(23)
	v_lshlrev_b32_e32 v28, 16, v88
	v_and_b32_e32 v29, 0xffff0000, v88
	v_lshlrev_b32_e32 v30, 16, v89
	v_and_b32_e32 v31, 0xffff0000, v89
	v_lshlrev_b32_e32 v32, 16, v90
	v_and_b32_e32 v33, 0xffff0000, v90
	v_lshlrev_b32_e32 v34, 16, v91
	v_and_b32_e32 v35, 0xffff0000, v91
	v_cndmask_b32_e64 v28, 0, v28, s[2:3]
	v_cndmask_b32_e64 v29, 0, v29, s[2:3]
	v_cndmask_b32_e64 v30, 0, v30, s[2:3]
	v_cndmask_b32_e64 v31, 0, v31, s[2:3]
	v_cndmask_b32_e64 v32, 0, v32, s[2:3]
	v_cndmask_b32_e64 v33, 0, v33, s[2:3]
	v_cndmask_b32_e64 v34, 0, v34, s[2:3]
	v_cndmask_b32_e64 v35, 0, v35, s[2:3]
	v_add_f32_e32 v20, v20, v28
	v_add_f32_e32 v21, v21, v29
	v_add_f32_e32 v22, v22, v30
	v_add_f32_e32 v23, v23, v31
	v_add_f32_e32 v24, v24, v32
	v_add_f32_e32 v25, v25, v33
	v_add_f32_e32 v26, v26, v34
	v_add_f32_e32 v27, v27, v35
	s_waitcnt vmcnt(22)
	v_lshlrev_b32_e32 v28, 16, v92
	v_and_b32_e32 v29, 0xffff0000, v92
	v_lshlrev_b32_e32 v30, 16, v93
	v_and_b32_e32 v31, 0xffff0000, v93
	v_lshlrev_b32_e32 v32, 16, v94
	v_and_b32_e32 v33, 0xffff0000, v94
	v_lshlrev_b32_e32 v34, 16, v95
	v_and_b32_e32 v35, 0xffff0000, v95
	v_cndmask_b32_e64 v28, 0, v28, s[2:3]
	v_cndmask_b32_e64 v29, 0, v29, s[2:3]
	v_cndmask_b32_e64 v30, 0, v30, s[2:3]
	v_cndmask_b32_e64 v31, 0, v31, s[2:3]
	v_cndmask_b32_e64 v32, 0, v32, s[2:3]
	v_cndmask_b32_e64 v33, 0, v33, s[2:3]
	v_cndmask_b32_e64 v34, 0, v34, s[2:3]
	v_cndmask_b32_e64 v35, 0, v35, s[2:3]
	v_add_f32_e32 v20, v20, v28
	v_add_f32_e32 v21, v21, v29
	v_add_f32_e32 v22, v22, v30
	v_add_f32_e32 v23, v23, v31
	v_add_f32_e32 v24, v24, v32
	v_add_f32_e32 v25, v25, v33
	v_add_f32_e32 v26, v26, v34
	v_add_f32_e32 v27, v27, v35
	s_waitcnt vmcnt(21)
; __device__ __forceinline__ void phase_pool(const bf16_t* proj, bf16_t* pooled) {
;     ...
;         if (pos0 > 0) for (int j = 1; j < w; ++j) { float f[8]; unpack8(*(const u32x4*)(src - (ptrdiff_t)j * PP), f);
; #pragma unroll
;             for (int e = 0; e < 8; ++e) sum[e] += f[e]; }
;         for (int r = 0; r < 16; ++r) {
;             float f[8]; unpack8(*(const u32x4*)(src + (ptrdiff_t)r * PP), f);
;             const int pos = pos0 + r;
;             if (r >= 1 && pos - w >= 0) { float o[8]; unpack8(*(const u32x4*)(src + (ptrdiff_t)(r - w) * PP), o);
; #pragma unroll
;                 for (int e = 0; e < 8; ++e) sum[e] -= o[e]; }
;             const float rc = 1.0f / (float)(pos + 1 < w ? pos + 1 : w);
;             float out[8];
; #pragma unroll
;             for (int e = 0; e < 8; ++e) { sum[e] += f[e]; out[e] = sum[e] * rc - f[e]; }
;             *(u32x4*)(pooled + (size_t)(r0 + r) * DM + cgi * 8) = pack8(out);
	v_lshlrev_b32_e32 v28, 16, v96
	v_and_b32_e32 v29, 0xffff0000, v96
	v_lshlrev_b32_e32 v30, 16, v97
	v_and_b32_e32 v31, 0xffff0000, v97
	v_lshlrev_b32_e32 v32, 16, v98
	v_and_b32_e32 v33, 0xffff0000, v98
	v_lshlrev_b32_e32 v34, 16, v99
	v_and_b32_e32 v35, 0xffff0000, v99
	v_cndmask_b32_e64 v28, 0, v28, s[2:3]
	v_cndmask_b32_e64 v29, 0, v29, s[2:3]
	v_cndmask_b32_e64 v30, 0, v30, s[2:3]
	v_cndmask_b32_e64 v31, 0, v31, s[2:3]
	v_cndmask_b32_e64 v32, 0, v32, s[2:3]
	v_cndmask_b32_e64 v33, 0, v33, s[2:3]
	v_cndmask_b32_e64 v34, 0, v34, s[2:3]
	v_cndmask_b32_e64 v35, 0, v35, s[2:3]
	v_add_f32_e32 v20, v20, v28
	v_add_f32_e32 v21, v21, v29
	v_add_f32_e32 v22, v22, v30
	v_add_f32_e32 v23, v23, v31
	v_add_f32_e32 v24, v24, v32
	v_add_f32_e32 v25, v25, v33
	v_add_f32_e32 v26, v26, v34
	v_add_f32_e32 v27, v27, v35
	s_waitcnt vmcnt(20)
	v_lshlrev_b32_e32 v28, 16, v100
	v_and_b32_e32 v29, 0xffff0000, v100
	v_lshlrev_b32_e32 v30, 16, v101
	v_and_b32_e32 v31, 0xffff0000, v101
	v_lshlrev_b32_e32 v32, 16, v102
	v_and_b32_e32 v33, 0xffff0000, v102
	v_lshlrev_b32_e32 v34, 16, v103
	v_and_b32_e32 v35, 0xffff0000, v103
	v_cndmask_b32_e64 v28, 0, v28, s[2:3]
	v_cndmask_b32_e64 v29, 0, v29, s[2:3]
	v_cndmask_b32_e64 v30, 0, v30, s[2:3]
	v_cndmask_b32_e64 v31, 0, v31, s[2:3]
	v_cndmask_b32_e64 v32, 0, v32, s[2:3]
	v_cndmask_b32_e64 v33, 0, v33, s[2:3]
	v_cndmask_b32_e64 v34, 0, v34, s[2:3]
	v_cndmask_b32_e64 v35, 0, v35, s[2:3]
	v_add_f32_e32 v20, v20, v28
	v_add_f32_e32 v21, v21, v29
	v_add_f32_e32 v22, v22, v30
	v_add_f32_e32 v23, v23, v31
	v_add_f32_e32 v24, v24, v32
	v_add_f32_e32 v25, v25, v33
	v_add_f32_e32 v26, v26, v34
	v_add_f32_e32 v27, v27, v35
	s_waitcnt vmcnt(19)
	v_lshlrev_b32_e32 v28, 16, v104
	v_and_b32_e32 v29, 0xffff0000, v104
	v_lshlrev_b32_e32 v30, 16, v105
	v_and_b32_e32 v31, 0xffff0000, v105
	v_lshlrev_b32_e32 v32, 16, v106
	v_and_b32_e32 v33, 0xffff0000, v106
	v_lshlrev_b32_e32 v34, 16, v107
	v_and_b32_e32 v35, 0xffff0000, v107
	v_cndmask_b32_e64 v28, 0, v28, s[2:3]
	v_cndmask_b32_e64 v29, 0, v29, s[2:3]
	v_cndmask_b32_e64 v30, 0, v30, s[2:3]
	v_cndmask_b32_e64 v31, 0, v31, s[2:3]
	v_cndmask_b32_e64 v32, 0, v32, s[2:3]
	v_cndmask_b32_e64 v33, 0, v33, s[2:3]
	v_cndmask_b32_e64 v34, 0, v34, s[2:3]
	v_cndmask_b32_e64 v35, 0, v35, s[2:3]
	v_add_f32_e32 v20, v20, v28
	v_add_f32_e32 v21, v21, v29
	v_add_f32_e32 v22, v22, v30
	v_add_f32_e32 v23, v23, v31
	v_add_f32_e32 v24, v24, v32
	v_add_f32_e32 v25, v25, v33
	v_add_f32_e32 v26, v26, v34
	v_add_f32_e32 v27, v27, v35
	s_waitcnt vmcnt(18)
	v_lshlrev_b32_e32 v28, 16, v108
	v_and_b32_e32 v29, 0xffff0000, v108
	v_lshlrev_b32_e32 v30, 16, v109
	v_and_b32_e32 v31, 0xffff0000, v109
	v_lshlrev_b32_e32 v32, 16, v110
	v_and_b32_e32 v33, 0xffff0000, v110
	v_lshlrev_b32_e32 v34, 16, v111
	v_and_b32_e32 v35, 0xffff0000, v111
	v_cndmask_b32_e64 v28, 0, v28, s[2:3]
	v_cndmask_b32_e64 v29, 0, v29, s[2:3]
	v_cndmask_b32_e64 v30, 0, v30, s[2:3]
	v_cndmask_b32_e64 v31, 0, v31, s[2:3]
	v_cndmask_b32_e64 v32, 0, v32, s[2:3]
	v_cndmask_b32_e64 v33, 0, v33, s[2:3]
	v_cndmask_b32_e64 v34, 0, v34, s[2:3]
	v_cndmask_b32_e64 v35, 0, v35, s[2:3]
	v_add_f32_e32 v20, v20, v28
	v_add_f32_e32 v21, v21, v29
	v_add_f32_e32 v22, v22, v30
	v_add_f32_e32 v23, v23, v31
	v_add_f32_e32 v24, v24, v32
	v_add_f32_e32 v25, v25, v33
	v_add_f32_e32 v26, v26, v34
	v_add_f32_e32 v27, v27, v35
	s_waitcnt vmcnt(17)
	v_lshlrev_b32_e32 v28, 16, v112
	v_and_b32_e32 v29, 0xffff0000, v112
	v_lshlrev_b32_e32 v30, 16, v113
	v_and_b32_e32 v31, 0xffff0000, v113
	v_lshlrev_b32_e32 v32, 16, v114
	v_and_b32_e32 v33, 0xffff0000, v114
	v_lshlrev_b32_e32 v34, 16, v115
	v_and_b32_e32 v35, 0xffff0000, v115
	v_cndmask_b32_e64 v28, 0, v28, s[2:3]
	v_cndmask_b32_e64 v29, 0, v29, s[2:3]
	v_cndmask_b32_e64 v30, 0, v30, s[2:3]
	v_cndmask_b32_e64 v31, 0, v31, s[2:3]
	v_cndmask_b32_e64 v32, 0, v32, s[2:3]
	v_cndmask_b32_e64 v33, 0, v33, s[2:3]
	v_cndmask_b32_e64 v34, 0, v34, s[2:3]
	v_cndmask_b32_e64 v35, 0, v35, s[2:3]
	v_add_f32_e32 v20, v20, v28
	v_add_f32_e32 v21, v21, v29
	v_add_f32_e32 v22, v22, v30
	v_add_f32_e32 v23, v23, v31
	v_add_f32_e32 v24, v24, v32
	v_add_f32_e32 v25, v25, v33
	v_add_f32_e32 v26, v26, v34
	v_add_f32_e32 v27, v27, v35
	s_waitcnt vmcnt(16)
	v_lshlrev_b32_e32 v28, 16, v116
	v_and_b32_e32 v29, 0xffff0000, v116
	v_lshlrev_b32_e32 v30, 16, v117
	v_and_b32_e32 v31, 0xffff0000, v117
	v_lshlrev_b32_e32 v32, 16, v118
	v_and_b32_e32 v33, 0xffff0000, v118
	v_lshlrev_b32_e32 v34, 16, v119
	v_and_b32_e32 v35, 0xffff0000, v119
	v_cndmask_b32_e64 v28, 0, v28, s[2:3]
	v_cndmask_b32_e64 v29, 0, v29, s[2:3]
	v_cndmask_b32_e64 v30, 0, v30, s[2:3]
	v_cndmask_b32_e64 v31, 0, v31, s[2:3]
	v_cndmask_b32_e64 v32, 0, v32, s[2:3]
	v_cndmask_b32_e64 v33, 0, v33, s[2:3]
	v_cndmask_b32_e64 v34, 0, v34, s[2:3]
	v_cndmask_b32_e64 v35, 0, v35, s[2:3]
	v_add_f32_e32 v20, v20, v28
	v_add_f32_e32 v21, v21, v29
	v_add_f32_e32 v22, v22, v30
	v_add_f32_e32 v23, v23, v31
	v_add_f32_e32 v24, v24, v32
	v_add_f32_e32 v25, v25, v33
	v_add_f32_e32 v26, v26, v34
	v_add_f32_e32 v27, v27, v35
	s_waitcnt vmcnt(15)
	v_lshlrev_b32_e32 v28, 16, v120
	v_and_b32_e32 v29, 0xffff0000, v120
	v_lshlrev_b32_e32 v30, 16, v121
	v_and_b32_e32 v31, 0xffff0000, v121
	v_lshlrev_b32_e32 v32, 16, v122
	v_and_b32_e32 v33, 0xffff0000, v122
	v_lshlrev_b32_e32 v34, 16, v123
	v_and_b32_e32 v35, 0xffff0000, v123
	v_add_f32_e32 v20, v20, v28
	v_add_f32_e32 v21, v21, v29
	v_add_f32_e32 v22, v22, v30
	v_add_f32_e32 v23, v23, v31
	v_add_f32_e32 v24, v24, v32
	v_add_f32_e32 v25, v25, v33
	v_add_f32_e32 v26, v26, v34
	v_add_f32_e32 v27, v27, v35
	v_mov_b32_e32 v56, 0x3f800000
	v_mov_b32_e32 v57, 0x3d800000
	v_cndmask_b32_e64 v56, v56, v57, s[2:3]
	s_nop 0
	v_fma_f32 v44, v56, v20, -v28
	v_fma_f32 v45, v56, v21, -v29
	v_fma_f32 v46, v56, v22, -v30
	v_fma_f32 v47, v56, v23, -v31
	v_fma_f32 v48, v56, v24, -v32
	v_fma_f32 v49, v56, v25, -v33
	v_fma_f32 v50, v56, v26, -v34
	v_fma_f32 v51, v56, v27, -v35
	v_cvt_pk_bf16_f32 v52, v44, v45
	v_cvt_pk_bf16_f32 v53, v46, v47
	v_cvt_pk_bf16_f32 v54, v48, v49
	v_cvt_pk_bf16_f32 v55, v50, v51
	global_store_dwordx4 v[8:9], v[52:55], off
	v_lshl_add_u64 v[8:9], v[8:9], 0, s[6:7]
	s_waitcnt vmcnt(15)
; __device__ __forceinline__ void phase_pool(const bf16_t* proj, bf16_t* pooled) {
;     ...
;         for (int r = 0; r < 16; ++r) {
;             float f[8]; unpack8(*(const u32x4*)(src + (ptrdiff_t)r * PP), f);
;             const int pos = pos0 + r;
;             if (r >= 1 && pos - w >= 0) { float o[8]; unpack8(*(const u32x4*)(src + (ptrdiff_t)(r - w) * PP), o);
; #pragma unroll
;                 for (int e = 0; e < 8; ++e) sum[e] -= o[e]; }
;             const float rc = 1.0f / (float)(pos + 1 < w ? pos + 1 : w);
;             float out[8];
; #pragma unroll
;             for (int e = 0; e < 8; ++e) { sum[e] += f[e]; out[e] = sum[e] * rc - f[e]; }
;             *(u32x4*)(pooled + (size_t)(r0 + r) * DM + cgi * 8) = pack8(out);
	v_lshlrev_b32_e32 v36, 16, v116
	v_and_b32_e32 v37, 0xffff0000, v116
	v_lshlrev_b32_e32 v38, 16, v117
	v_and_b32_e32 v39, 0xffff0000, v117
	v_lshlrev_b32_e32 v40, 16, v118
	v_and_b32_e32 v41, 0xffff0000, v118
	v_lshlrev_b32_e32 v42, 16, v119
	v_and_b32_e32 v43, 0xffff0000, v119
	v_cndmask_b32_e64 v36, 0, v36, s[2:3]
	v_cndmask_b32_e64 v37, 0, v37, s[2:3]
	v_cndmask_b32_e64 v38, 0, v38, s[2:3]
	v_cndmask_b32_e64 v39, 0, v39, s[2:3]
	v_cndmask_b32_e64 v40, 0, v40, s[2:3]
	v_cndmask_b32_e64 v41, 0, v41, s[2:3]
	v_cndmask_b32_e64 v42, 0, v42, s[2:3]
	v_cndmask_b32_e64 v43, 0, v43, s[2:3]
	v_sub_f32_e32 v20, v20, v36
	v_sub_f32_e32 v21, v21, v37
	v_sub_f32_e32 v22, v22, v38
	v_sub_f32_e32 v23, v23, v39
	v_sub_f32_e32 v24, v24, v40
	v_sub_f32_e32 v25, v25, v41
	v_sub_f32_e32 v26, v26, v42
	v_sub_f32_e32 v27, v27, v43
	v_lshlrev_b32_e32 v28, 16, v124
	v_and_b32_e32 v29, 0xffff0000, v124
	v_lshlrev_b32_e32 v30, 16, v125
	v_and_b32_e32 v31, 0xffff0000, v125
	v_lshlrev_b32_e32 v32, 16, v126
	v_and_b32_e32 v33, 0xffff0000, v126
	v_lshlrev_b32_e32 v34, 16, v127
	v_and_b32_e32 v35, 0xffff0000, v127
	v_add_f32_e32 v20, v20, v28
	v_add_f32_e32 v21, v21, v29
	v_add_f32_e32 v22, v22, v30
	v_add_f32_e32 v23, v23, v31
	v_add_f32_e32 v24, v24, v32
	v_add_f32_e32 v25, v25, v33
	v_add_f32_e32 v26, v26, v34
	v_add_f32_e32 v27, v27, v35
	v_mov_b32_e32 v56, 0x3f000000
	v_mov_b32_e32 v57, 0x3d800000
	v_cndmask_b32_e64 v56, v56, v57, s[2:3]
	s_nop 0
	v_fma_f32 v44, v56, v20, -v28
	v_fma_f32 v45, v56, v21, -v29
	v_fma_f32 v46, v56, v22, -v30
	v_fma_f32 v47, v56, v23, -v31
	v_fma_f32 v48, v56, v24, -v32
	v_fma_f32 v49, v56, v25, -v33
	v_fma_f32 v50, v56, v26, -v34
	v_fma_f32 v51, v56, v27, -v35
	v_cvt_pk_bf16_f32 v52, v44, v45
	v_cvt_pk_bf16_f32 v53, v46, v47
	v_cvt_pk_bf16_f32 v54, v48, v49
	v_cvt_pk_bf16_f32 v55, v50, v51
	global_store_dwordx4 v[8:9], v[52:55], off
	v_lshl_add_u64 v[8:9], v[8:9], 0, s[6:7]
	s_waitcnt vmcnt(15)
	v_lshlrev_b32_e32 v36, 16, v112
	v_and_b32_e32 v37, 0xffff0000, v112
	v_lshlrev_b32_e32 v38, 16, v113
	v_and_b32_e32 v39, 0xffff0000, v113
	v_lshlrev_b32_e32 v40, 16, v114
	v_and_b32_e32 v41, 0xffff0000, v114
	v_lshlrev_b32_e32 v42, 16, v115
	v_and_b32_e32 v43, 0xffff0000, v115
	v_cndmask_b32_e64 v36, 0, v36, s[2:3]
	v_cndmask_b32_e64 v37, 0, v37, s[2:3]
	v_cndmask_b32_e64 v38, 0, v38, s[2:3]
	v_cndmask_b32_e64 v39, 0, v39, s[2:3]
	v_cndmask_b32_e64 v40, 0, v40, s[2:3]
	v_cndmask_b32_e64 v41, 0, v41, s[2:3]
	v_cndmask_b32_e64 v42, 0, v42, s[2:3]
	v_cndmask_b32_e64 v43, 0, v43, s[2:3]
	v_sub_f32_e32 v20, v20, v36
	v_sub_f32_e32 v21, v21, v37
	v_sub_f32_e32 v22, v22, v38
	v_sub_f32_e32 v23, v23, v39
	v_sub_f32_e32 v24, v24, v40
	v_sub_f32_e32 v25, v25, v41
	v_sub_f32_e32 v26, v26, v42
	v_sub_f32_e32 v27, v27, v43
	v_lshlrev_b32_e32 v28, 16, v128
	v_and_b32_e32 v29, 0xffff0000, v128
	v_lshlrev_b32_e32 v30, 16, v129
	v_and_b32_e32 v31, 0xffff0000, v129
	v_lshlrev_b32_e32 v32, 16, v130
	v_and_b32_e32 v33, 0xffff0000, v130
	v_lshlrev_b32_e32 v34, 16, v131
	v_and_b32_e32 v35, 0xffff0000, v131
	v_add_f32_e32 v20, v20, v28
	v_add_f32_e32 v21, v21, v29
	v_add_f32_e32 v22, v22, v30
	v_add_f32_e32 v23, v23, v31
	v_add_f32_e32 v24, v24, v32
	v_add_f32_e32 v25, v25, v33
	v_add_f32_e32 v26, v26, v34
	v_add_f32_e32 v27, v27, v35
	v_mov_b32_e32 v56, 0x3eaaaaab
	v_mov_b32_e32 v57, 0x3d800000
	v_cndmask_b32_e64 v56, v56, v57, s[2:3]
	s_nop 0
	v_fma_f32 v44, v56, v20, -v28
	v_fma_f32 v45, v56, v21, -v29
	v_fma_f32 v46, v56, v22, -v30
	v_fma_f32 v47, v56, v23, -v31
	v_fma_f32 v48, v56, v24, -v32
	v_fma_f32 v49, v56, v25, -v33
	v_fma_f32 v50, v56, v26, -v34
	v_fma_f32 v51, v56, v27, -v35
	v_cvt_pk_bf16_f32 v52, v44, v45
	v_cvt_pk_bf16_f32 v53, v46, v47
	v_cvt_pk_bf16_f32 v54, v48, v49
	v_cvt_pk_bf16_f32 v55, v50, v51
	global_store_dwordx4 v[8:9], v[52:55], off
	v_lshl_add_u64 v[8:9], v[8:9], 0, s[6:7]
	s_waitcnt vmcnt(15)
	v_lshlrev_b32_e32 v36, 16, v108
	v_and_b32_e32 v37, 0xffff0000, v108
	v_lshlrev_b32_e32 v38, 16, v109
	v_and_b32_e32 v39, 0xffff0000, v109
	v_lshlrev_b32_e32 v40, 16, v110
	v_and_b32_e32 v41, 0xffff0000, v110
	v_lshlrev_b32_e32 v42, 16, v111
	v_and_b32_e32 v43, 0xffff0000, v111
	v_cndmask_b32_e64 v36, 0, v36, s[2:3]
	v_cndmask_b32_e64 v37, 0, v37, s[2:3]
	v_cndmask_b32_e64 v38, 0, v38, s[2:3]
	v_cndmask_b32_e64 v39, 0, v39, s[2:3]
	v_cndmask_b32_e64 v40, 0, v40, s[2:3]
	v_cndmask_b32_e64 v41, 0, v41, s[2:3]
	v_cndmask_b32_e64 v42, 0, v42, s[2:3]
	v_cndmask_b32_e64 v43, 0, v43, s[2:3]
	v_sub_f32_e32 v20, v20, v36
	v_sub_f32_e32 v21, v21, v37
	v_sub_f32_e32 v22, v22, v38
	v_sub_f32_e32 v23, v23, v39
	v_sub_f32_e32 v24, v24, v40
	v_sub_f32_e32 v25, v25, v41
	v_sub_f32_e32 v26, v26, v42
	v_sub_f32_e32 v27, v27, v43
	v_lshlrev_b32_e32 v28, 16, v132
	v_and_b32_e32 v29, 0xffff0000, v132
	v_lshlrev_b32_e32 v30, 16, v133
	v_and_b32_e32 v31, 0xffff0000, v133
	v_lshlrev_b32_e32 v32, 16, v134
	v_and_b32_e32 v33, 0xffff0000, v134
	v_lshlrev_b32_e32 v34, 16, v135
	v_and_b32_e32 v35, 0xffff0000, v135
	v_add_f32_e32 v20, v20, v28
	v_add_f32_e32 v21, v21, v29
	v_add_f32_e32 v22, v22, v30
	v_add_f32_e32 v23, v23, v31
	v_add_f32_e32 v24, v24, v32
	v_add_f32_e32 v25, v25, v33
	v_add_f32_e32 v26, v26, v34
	v_add_f32_e32 v27, v27, v35
	v_mov_b32_e32 v56, 0x3e800000
	v_mov_b32_e32 v57, 0x3d800000
	v_cndmask_b32_e64 v56, v56, v57, s[2:3]
	s_nop 0
	v_fma_f32 v44, v56, v20, -v28
	v_fma_f32 v45, v56, v21, -v29
	v_fma_f32 v46, v56, v22, -v30
	v_fma_f32 v47, v56, v23, -v31
	v_fma_f32 v48, v56, v24, -v32
	v_fma_f32 v49, v56, v25, -v33
	v_fma_f32 v50, v56, v26, -v34
	v_fma_f32 v51, v56, v27, -v35
	v_cvt_pk_bf16_f32 v52, v44, v45
	v_cvt_pk_bf16_f32 v53, v46, v47
	v_cvt_pk_bf16_f32 v54, v48, v49
	v_cvt_pk_bf16_f32 v55, v50, v51
	global_store_dwordx4 v[8:9], v[52:55], off
	v_lshl_add_u64 v[8:9], v[8:9], 0, s[6:7]
	s_waitcnt vmcnt(15)
; __device__ __forceinline__ void phase_pool(const bf16_t* proj, bf16_t* pooled) {
;     ...
;         for (int r = 0; r < 16; ++r) {
;             float f[8]; unpack8(*(const u32x4*)(src + (ptrdiff_t)r * PP), f);
;             const int pos = pos0 + r;
;             if (r >= 1 && pos - w >= 0) { float o[8]; unpack8(*(const u32x4*)(src + (ptrdiff_t)(r - w) * PP), o);
; #pragma unroll
;                 for (int e = 0; e < 8; ++e) sum[e] -= o[e]; }
;             const float rc = 1.0f / (float)(pos + 1 < w ? pos + 1 : w);
;             float out[8];
; #pragma unroll
;             for (int e = 0; e < 8; ++e) { sum[e] += f[e]; out[e] = sum[e] * rc - f[e]; }
;             *(u32x4*)(pooled + (size_t)(r0 + r) * DM + cgi * 8) = pack8(out);
	v_lshlrev_b32_e32 v36, 16, v104
	v_and_b32_e32 v37, 0xffff0000, v104
	v_lshlrev_b32_e32 v38, 16, v105
	v_and_b32_e32 v39, 0xffff0000, v105
	v_lshlrev_b32_e32 v40, 16, v106
	v_and_b32_e32 v41, 0xffff0000, v106
	v_lshlrev_b32_e32 v42, 16, v107
	v_and_b32_e32 v43, 0xffff0000, v107
	v_cndmask_b32_e64 v36, 0, v36, s[2:3]
	v_cndmask_b32_e64 v37, 0, v37, s[2:3]
	v_cndmask_b32_e64 v38, 0, v38, s[2:3]
	v_cndmask_b32_e64 v39, 0, v39, s[2:3]
	v_cndmask_b32_e64 v40, 0, v40, s[2:3]
	v_cndmask_b32_e64 v41, 0, v41, s[2:3]
	v_cndmask_b32_e64 v42, 0, v42, s[2:3]
	v_cndmask_b32_e64 v43, 0, v43, s[2:3]
	v_sub_f32_e32 v20, v20, v36
	v_sub_f32_e32 v21, v21, v37
	v_sub_f32_e32 v22, v22, v38
	v_sub_f32_e32 v23, v23, v39
	v_sub_f32_e32 v24, v24, v40
	v_sub_f32_e32 v25, v25, v41
	v_sub_f32_e32 v26, v26, v42
	v_sub_f32_e32 v27, v27, v43
	v_lshlrev_b32_e32 v28, 16, v136
	v_and_b32_e32 v29, 0xffff0000, v136
	v_lshlrev_b32_e32 v30, 16, v137
	v_and_b32_e32 v31, 0xffff0000, v137
	v_lshlrev_b32_e32 v32, 16, v138
	v_and_b32_e32 v33, 0xffff0000, v138
	v_lshlrev_b32_e32 v34, 16, v139
	v_and_b32_e32 v35, 0xffff0000, v139
	v_add_f32_e32 v20, v20, v28
	v_add_f32_e32 v21, v21, v29
	v_add_f32_e32 v22, v22, v30
	v_add_f32_e32 v23, v23, v31
	v_add_f32_e32 v24, v24, v32
	v_add_f32_e32 v25, v25, v33
	v_add_f32_e32 v26, v26, v34
	v_add_f32_e32 v27, v27, v35
	v_mov_b32_e32 v56, 0x3e4ccccd
	v_mov_b32_e32 v57, 0x3d800000
	v_cndmask_b32_e64 v56, v56, v57, s[2:3]
	s_nop 0
	v_fma_f32 v44, v56, v20, -v28
	v_fma_f32 v45, v56, v21, -v29
	v_fma_f32 v46, v56, v22, -v30
	v_fma_f32 v47, v56, v23, -v31
	v_fma_f32 v48, v56, v24, -v32
	v_fma_f32 v49, v56, v25, -v33
	v_fma_f32 v50, v56, v26, -v34
	v_fma_f32 v51, v56, v27, -v35
	v_cvt_pk_bf16_f32 v52, v44, v45
	v_cvt_pk_bf16_f32 v53, v46, v47
	v_cvt_pk_bf16_f32 v54, v48, v49
	v_cvt_pk_bf16_f32 v55, v50, v51
	global_store_dwordx4 v[8:9], v[52:55], off
	v_lshl_add_u64 v[8:9], v[8:9], 0, s[6:7]
	s_waitcnt vmcnt(15)
	v_lshlrev_b32_e32 v36, 16, v100
	v_and_b32_e32 v37, 0xffff0000, v100
	v_lshlrev_b32_e32 v38, 16, v101
	v_and_b32_e32 v39, 0xffff0000, v101
	v_lshlrev_b32_e32 v40, 16, v102
	v_and_b32_e32 v41, 0xffff0000, v102
	v_lshlrev_b32_e32 v42, 16, v103
	v_and_b32_e32 v43, 0xffff0000, v103
	v_cndmask_b32_e64 v36, 0, v36, s[2:3]
	v_cndmask_b32_e64 v37, 0, v37, s[2:3]
	v_cndmask_b32_e64 v38, 0, v38, s[2:3]
	v_cndmask_b32_e64 v39, 0, v39, s[2:3]
	v_cndmask_b32_e64 v40, 0, v40, s[2:3]
	v_cndmask_b32_e64 v41, 0, v41, s[2:3]
	v_cndmask_b32_e64 v42, 0, v42, s[2:3]
	v_cndmask_b32_e64 v43, 0, v43, s[2:3]
	v_sub_f32_e32 v20, v20, v36
	v_sub_f32_e32 v21, v21, v37
	v_sub_f32_e32 v22, v22, v38
	v_sub_f32_e32 v23, v23, v39
	v_sub_f32_e32 v24, v24, v40
	v_sub_f32_e32 v25, v25, v41
	v_sub_f32_e32 v26, v26, v42
	v_sub_f32_e32 v27, v27, v43
	v_lshlrev_b32_e32 v28, 16, v140
	v_and_b32_e32 v29, 0xffff0000, v140
	v_lshlrev_b32_e32 v30, 16, v141
	v_and_b32_e32 v31, 0xffff0000, v141
	v_lshlrev_b32_e32 v32, 16, v142
	v_and_b32_e32 v33, 0xffff0000, v142
	v_lshlrev_b32_e32 v34, 16, v143
	v_and_b32_e32 v35, 0xffff0000, v143
	v_add_f32_e32 v20, v20, v28
	v_add_f32_e32 v21, v21, v29
	v_add_f32_e32 v22, v22, v30
	v_add_f32_e32 v23, v23, v31
	v_add_f32_e32 v24, v24, v32
	v_add_f32_e32 v25, v25, v33
	v_add_f32_e32 v26, v26, v34
	v_add_f32_e32 v27, v27, v35
	v_mov_b32_e32 v56, 0x3e2aaaab
	v_mov_b32_e32 v57, 0x3d800000
	v_cndmask_b32_e64 v56, v56, v57, s[2:3]
	s_nop 0
	v_fma_f32 v44, v56, v20, -v28
	v_fma_f32 v45, v56, v21, -v29
	v_fma_f32 v46, v56, v22, -v30
	v_fma_f32 v47, v56, v23, -v31
	v_fma_f32 v48, v56, v24, -v32
	v_fma_f32 v49, v56, v25, -v33
	v_fma_f32 v50, v56, v26, -v34
	v_fma_f32 v51, v56, v27, -v35
	v_cvt_pk_bf16_f32 v52, v44, v45
	v_cvt_pk_bf16_f32 v53, v46, v47
	v_cvt_pk_bf16_f32 v54, v48, v49
	v_cvt_pk_bf16_f32 v55, v50, v51
	global_store_dwordx4 v[8:9], v[52:55], off
	v_lshl_add_u64 v[8:9], v[8:9], 0, s[6:7]
	s_waitcnt vmcnt(15)
	v_lshlrev_b32_e32 v36, 16, v96
	v_and_b32_e32 v37, 0xffff0000, v96
	v_lshlrev_b32_e32 v38, 16, v97
	v_and_b32_e32 v39, 0xffff0000, v97
	v_lshlrev_b32_e32 v40, 16, v98
	v_and_b32_e32 v41, 0xffff0000, v98
	v_lshlrev_b32_e32 v42, 16, v99
	v_and_b32_e32 v43, 0xffff0000, v99
	v_cndmask_b32_e64 v36, 0, v36, s[2:3]
	v_cndmask_b32_e64 v37, 0, v37, s[2:3]
	v_cndmask_b32_e64 v38, 0, v38, s[2:3]
	v_cndmask_b32_e64 v39, 0, v39, s[2:3]
	v_cndmask_b32_e64 v40, 0, v40, s[2:3]
	v_cndmask_b32_e64 v41, 0, v41, s[2:3]
	v_cndmask_b32_e64 v42, 0, v42, s[2:3]
	v_cndmask_b32_e64 v43, 0, v43, s[2:3]
	v_sub_f32_e32 v20, v20, v36
	v_sub_f32_e32 v21, v21, v37
	v_sub_f32_e32 v22, v22, v38
	v_sub_f32_e32 v23, v23, v39
	v_sub_f32_e32 v24, v24, v40
	v_sub_f32_e32 v25, v25, v41
	v_sub_f32_e32 v26, v26, v42
	v_sub_f32_e32 v27, v27, v43
	v_lshlrev_b32_e32 v28, 16, v144
	v_and_b32_e32 v29, 0xffff0000, v144
	v_lshlrev_b32_e32 v30, 16, v145
	v_and_b32_e32 v31, 0xffff0000, v145
	v_lshlrev_b32_e32 v32, 16, v146
	v_and_b32_e32 v33, 0xffff0000, v146
	v_lshlrev_b32_e32 v34, 16, v147
	v_and_b32_e32 v35, 0xffff0000, v147
	v_add_f32_e32 v20, v20, v28
	v_add_f32_e32 v21, v21, v29
	v_add_f32_e32 v22, v22, v30
	v_add_f32_e32 v23, v23, v31
	v_add_f32_e32 v24, v24, v32
	v_add_f32_e32 v25, v25, v33
	v_add_f32_e32 v26, v26, v34
	v_add_f32_e32 v27, v27, v35
	v_mov_b32_e32 v56, 0x3e124925
	v_mov_b32_e32 v57, 0x3d800000
	v_cndmask_b32_e64 v56, v56, v57, s[2:3]
	s_nop 0
	v_fma_f32 v44, v56, v20, -v28
	v_fma_f32 v45, v56, v21, -v29
	v_fma_f32 v46, v56, v22, -v30
	v_fma_f32 v47, v56, v23, -v31
	v_fma_f32 v48, v56, v24, -v32
	v_fma_f32 v49, v56, v25, -v33
	v_fma_f32 v50, v56, v26, -v34
	v_fma_f32 v51, v56, v27, -v35
	v_cvt_pk_bf16_f32 v52, v44, v45
	v_cvt_pk_bf16_f32 v53, v46, v47
	v_cvt_pk_bf16_f32 v54, v48, v49
	v_cvt_pk_bf16_f32 v55, v50, v51
	global_store_dwordx4 v[8:9], v[52:55], off
	v_lshl_add_u64 v[8:9], v[8:9], 0, s[6:7]
	s_waitcnt vmcnt(15)
; __device__ __forceinline__ void phase_pool(const bf16_t* proj, bf16_t* pooled) {
;     ...
;         for (int r = 0; r < 16; ++r) {
;             float f[8]; unpack8(*(const u32x4*)(src + (ptrdiff_t)r * PP), f);
;             const int pos = pos0 + r;
;             if (r >= 1 && pos - w >= 0) { float o[8]; unpack8(*(const u32x4*)(src + (ptrdiff_t)(r - w) * PP), o);
; #pragma unroll
;                 for (int e = 0; e < 8; ++e) sum[e] -= o[e]; }
;             const float rc = 1.0f / (float)(pos + 1 < w ? pos + 1 : w);
;             float out[8];
; #pragma unroll
;             for (int e = 0; e < 8; ++e) { sum[e] += f[e]; out[e] = sum[e] * rc - f[e]; }
;             *(u32x4*)(pooled + (size_t)(r0 + r) * DM + cgi * 8) = pack8(out);
	v_lshlrev_b32_e32 v36, 16, v92
	v_and_b32_e32 v37, 0xffff0000, v92
	v_lshlrev_b32_e32 v38, 16, v93
	v_and_b32_e32 v39, 0xffff0000, v93
	v_lshlrev_b32_e32 v40, 16, v94
	v_and_b32_e32 v41, 0xffff0000, v94
	v_lshlrev_b32_e32 v42, 16, v95
	v_and_b32_e32 v43, 0xffff0000, v95
	v_cndmask_b32_e64 v36, 0, v36, s[2:3]
	v_cndmask_b32_e64 v37, 0, v37, s[2:3]
	v_cndmask_b32_e64 v38, 0, v38, s[2:3]
	v_cndmask_b32_e64 v39, 0, v39, s[2:3]
	v_cndmask_b32_e64 v40, 0, v40, s[2:3]
	v_cndmask_b32_e64 v41, 0, v41, s[2:3]
	v_cndmask_b32_e64 v42, 0, v42, s[2:3]
	v_cndmask_b32_e64 v43, 0, v43, s[2:3]
	v_sub_f32_e32 v20, v20, v36
	v_sub_f32_e32 v21, v21, v37
	v_sub_f32_e32 v22, v22, v38
	v_sub_f32_e32 v23, v23, v39
	v_sub_f32_e32 v24, v24, v40
	v_sub_f32_e32 v25, v25, v41
	v_sub_f32_e32 v26, v26, v42
	v_sub_f32_e32 v27, v27, v43
	v_lshlrev_b32_e32 v28, 16, v148
	v_and_b32_e32 v29, 0xffff0000, v148
	v_lshlrev_b32_e32 v30, 16, v149
	v_and_b32_e32 v31, 0xffff0000, v149
	v_lshlrev_b32_e32 v32, 16, v150
	v_and_b32_e32 v33, 0xffff0000, v150
	v_lshlrev_b32_e32 v34, 16, v151
	v_and_b32_e32 v35, 0xffff0000, v151
	v_add_f32_e32 v20, v20, v28
	v_add_f32_e32 v21, v21, v29
	v_add_f32_e32 v22, v22, v30
	v_add_f32_e32 v23, v23, v31
	v_add_f32_e32 v24, v24, v32
	v_add_f32_e32 v25, v25, v33
	v_add_f32_e32 v26, v26, v34
	v_add_f32_e32 v27, v27, v35
	v_mov_b32_e32 v56, 0x3e000000
	v_mov_b32_e32 v57, 0x3d800000
	v_cndmask_b32_e64 v56, v56, v57, s[2:3]
	s_nop 0
	v_fma_f32 v44, v56, v20, -v28
	v_fma_f32 v45, v56, v21, -v29
	v_fma_f32 v46, v56, v22, -v30
	v_fma_f32 v47, v56, v23, -v31
	v_fma_f32 v48, v56, v24, -v32
	v_fma_f32 v49, v56, v25, -v33
	v_fma_f32 v50, v56, v26, -v34
	v_fma_f32 v51, v56, v27, -v35
	v_cvt_pk_bf16_f32 v52, v44, v45
	v_cvt_pk_bf16_f32 v53, v46, v47
	v_cvt_pk_bf16_f32 v54, v48, v49
	v_cvt_pk_bf16_f32 v55, v50, v51
	global_store_dwordx4 v[8:9], v[52:55], off
	v_lshl_add_u64 v[8:9], v[8:9], 0, s[6:7]
	s_waitcnt vmcnt(15)
	v_lshlrev_b32_e32 v36, 16, v88
	v_and_b32_e32 v37, 0xffff0000, v88
	v_lshlrev_b32_e32 v38, 16, v89
	v_and_b32_e32 v39, 0xffff0000, v89
	v_lshlrev_b32_e32 v40, 16, v90
	v_and_b32_e32 v41, 0xffff0000, v90
	v_lshlrev_b32_e32 v42, 16, v91
	v_and_b32_e32 v43, 0xffff0000, v91
	v_cndmask_b32_e64 v36, 0, v36, s[2:3]
	v_cndmask_b32_e64 v37, 0, v37, s[2:3]
	v_cndmask_b32_e64 v38, 0, v38, s[2:3]
	v_cndmask_b32_e64 v39, 0, v39, s[2:3]
	v_cndmask_b32_e64 v40, 0, v40, s[2:3]
	v_cndmask_b32_e64 v41, 0, v41, s[2:3]
	v_cndmask_b32_e64 v42, 0, v42, s[2:3]
	v_cndmask_b32_e64 v43, 0, v43, s[2:3]
	v_sub_f32_e32 v20, v20, v36
	v_sub_f32_e32 v21, v21, v37
	v_sub_f32_e32 v22, v22, v38
	v_sub_f32_e32 v23, v23, v39
	v_sub_f32_e32 v24, v24, v40
	v_sub_f32_e32 v25, v25, v41
	v_sub_f32_e32 v26, v26, v42
	v_sub_f32_e32 v27, v27, v43
	v_lshlrev_b32_e32 v28, 16, v152
	v_and_b32_e32 v29, 0xffff0000, v152
	v_lshlrev_b32_e32 v30, 16, v153
	v_and_b32_e32 v31, 0xffff0000, v153
	v_lshlrev_b32_e32 v32, 16, v154
	v_and_b32_e32 v33, 0xffff0000, v154
	v_lshlrev_b32_e32 v34, 16, v155
	v_and_b32_e32 v35, 0xffff0000, v155
	v_add_f32_e32 v20, v20, v28
	v_add_f32_e32 v21, v21, v29
	v_add_f32_e32 v22, v22, v30
	v_add_f32_e32 v23, v23, v31
	v_add_f32_e32 v24, v24, v32
	v_add_f32_e32 v25, v25, v33
	v_add_f32_e32 v26, v26, v34
	v_add_f32_e32 v27, v27, v35
	v_mov_b32_e32 v56, 0x3de38e39
	v_mov_b32_e32 v57, 0x3d800000
	v_cndmask_b32_e64 v56, v56, v57, s[2:3]
	s_nop 0
	v_fma_f32 v44, v56, v20, -v28
	v_fma_f32 v45, v56, v21, -v29
	v_fma_f32 v46, v56, v22, -v30
	v_fma_f32 v47, v56, v23, -v31
	v_fma_f32 v48, v56, v24, -v32
	v_fma_f32 v49, v56, v25, -v33
	v_fma_f32 v50, v56, v26, -v34
	v_fma_f32 v51, v56, v27, -v35
	v_cvt_pk_bf16_f32 v52, v44, v45
	v_cvt_pk_bf16_f32 v53, v46, v47
	v_cvt_pk_bf16_f32 v54, v48, v49
	v_cvt_pk_bf16_f32 v55, v50, v51
	global_store_dwordx4 v[8:9], v[52:55], off
	v_lshl_add_u64 v[8:9], v[8:9], 0, s[6:7]
	s_waitcnt vmcnt(15)
	v_lshlrev_b32_e32 v36, 16, v84
	v_and_b32_e32 v37, 0xffff0000, v84
	v_lshlrev_b32_e32 v38, 16, v85
	v_and_b32_e32 v39, 0xffff0000, v85
	v_lshlrev_b32_e32 v40, 16, v86
	v_and_b32_e32 v41, 0xffff0000, v86
	v_lshlrev_b32_e32 v42, 16, v87
	v_and_b32_e32 v43, 0xffff0000, v87
	v_cndmask_b32_e64 v36, 0, v36, s[2:3]
	v_cndmask_b32_e64 v37, 0, v37, s[2:3]
	v_cndmask_b32_e64 v38, 0, v38, s[2:3]
	v_cndmask_b32_e64 v39, 0, v39, s[2:3]
	v_cndmask_b32_e64 v40, 0, v40, s[2:3]
	v_cndmask_b32_e64 v41, 0, v41, s[2:3]
	v_cndmask_b32_e64 v42, 0, v42, s[2:3]
	v_cndmask_b32_e64 v43, 0, v43, s[2:3]
	v_sub_f32_e32 v20, v20, v36
	v_sub_f32_e32 v21, v21, v37
	v_sub_f32_e32 v22, v22, v38
	v_sub_f32_e32 v23, v23, v39
	v_sub_f32_e32 v24, v24, v40
	v_sub_f32_e32 v25, v25, v41
	v_sub_f32_e32 v26, v26, v42
	v_sub_f32_e32 v27, v27, v43
	v_lshlrev_b32_e32 v28, 16, v156
	v_and_b32_e32 v29, 0xffff0000, v156
	v_lshlrev_b32_e32 v30, 16, v157
	v_and_b32_e32 v31, 0xffff0000, v157
	v_lshlrev_b32_e32 v32, 16, v158
	v_and_b32_e32 v33, 0xffff0000, v158
	v_lshlrev_b32_e32 v34, 16, v159
	v_and_b32_e32 v35, 0xffff0000, v159
	v_add_f32_e32 v20, v20, v28
	v_add_f32_e32 v21, v21, v29
	v_add_f32_e32 v22, v22, v30
	v_add_f32_e32 v23, v23, v31
	v_add_f32_e32 v24, v24, v32
	v_add_f32_e32 v25, v25, v33
	v_add_f32_e32 v26, v26, v34
	v_add_f32_e32 v27, v27, v35
	v_mov_b32_e32 v56, 0x3dcccccd
	v_mov_b32_e32 v57, 0x3d800000
	v_cndmask_b32_e64 v56, v56, v57, s[2:3]
	s_nop 0
	v_fma_f32 v44, v56, v20, -v28
	v_fma_f32 v45, v56, v21, -v29
	v_fma_f32 v46, v56, v22, -v30
	v_fma_f32 v47, v56, v23, -v31
	v_fma_f32 v48, v56, v24, -v32
	v_fma_f32 v49, v56, v25, -v33
	v_fma_f32 v50, v56, v26, -v34
	v_fma_f32 v51, v56, v27, -v35
	v_cvt_pk_bf16_f32 v52, v44, v45
	v_cvt_pk_bf16_f32 v53, v46, v47
	v_cvt_pk_bf16_f32 v54, v48, v49
	v_cvt_pk_bf16_f32 v55, v50, v51
	global_store_dwordx4 v[8:9], v[52:55], off
	v_lshl_add_u64 v[8:9], v[8:9], 0, s[6:7]
	s_waitcnt vmcnt(15)
; __device__ __forceinline__ void phase_pool(const bf16_t* proj, bf16_t* pooled) {
;     ...
;         for (int r = 0; r < 16; ++r) {
;             float f[8]; unpack8(*(const u32x4*)(src + (ptrdiff_t)r * PP), f);
;             const int pos = pos0 + r;
;             if (r >= 1 && pos - w >= 0) { float o[8]; unpack8(*(const u32x4*)(src + (ptrdiff_t)(r - w) * PP), o);
; #pragma unroll
;                 for (int e = 0; e < 8; ++e) sum[e] -= o[e]; }
;             const float rc = 1.0f / (float)(pos + 1 < w ? pos + 1 : w);
;             float out[8];
; #pragma unroll
;             for (int e = 0; e < 8; ++e) { sum[e] += f[e]; out[e] = sum[e] * rc - f[e]; }
;             *(u32x4*)(pooled + (size_t)(r0 + r) * DM + cgi * 8) = pack8(out);
	v_lshlrev_b32_e32 v36, 16, v80
	v_and_b32_e32 v37, 0xffff0000, v80
	v_lshlrev_b32_e32 v38, 16, v81
	v_and_b32_e32 v39, 0xffff0000, v81
	v_lshlrev_b32_e32 v40, 16, v82
	v_and_b32_e32 v41, 0xffff0000, v82
	v_lshlrev_b32_e32 v42, 16, v83
	v_and_b32_e32 v43, 0xffff0000, v83
	v_cndmask_b32_e64 v36, 0, v36, s[2:3]
	v_cndmask_b32_e64 v37, 0, v37, s[2:3]
	v_cndmask_b32_e64 v38, 0, v38, s[2:3]
	v_cndmask_b32_e64 v39, 0, v39, s[2:3]
	v_cndmask_b32_e64 v40, 0, v40, s[2:3]
	v_cndmask_b32_e64 v41, 0, v41, s[2:3]
	v_cndmask_b32_e64 v42, 0, v42, s[2:3]
	v_cndmask_b32_e64 v43, 0, v43, s[2:3]
	v_sub_f32_e32 v20, v20, v36
	v_sub_f32_e32 v21, v21, v37
	v_sub_f32_e32 v22, v22, v38
	v_sub_f32_e32 v23, v23, v39
	v_sub_f32_e32 v24, v24, v40
	v_sub_f32_e32 v25, v25, v41
	v_sub_f32_e32 v26, v26, v42
	v_sub_f32_e32 v27, v27, v43
	v_lshlrev_b32_e32 v28, 16, v160
	v_and_b32_e32 v29, 0xffff0000, v160
	v_lshlrev_b32_e32 v30, 16, v161
	v_and_b32_e32 v31, 0xffff0000, v161
	v_lshlrev_b32_e32 v32, 16, v162
	v_and_b32_e32 v33, 0xffff0000, v162
	v_lshlrev_b32_e32 v34, 16, v163
	v_and_b32_e32 v35, 0xffff0000, v163
	v_add_f32_e32 v20, v20, v28
	v_add_f32_e32 v21, v21, v29
	v_add_f32_e32 v22, v22, v30
	v_add_f32_e32 v23, v23, v31
	v_add_f32_e32 v24, v24, v32
	v_add_f32_e32 v25, v25, v33
	v_add_f32_e32 v26, v26, v34
	v_add_f32_e32 v27, v27, v35
	v_mov_b32_e32 v56, 0x3dba2e8c
	v_mov_b32_e32 v57, 0x3d800000
	v_cndmask_b32_e64 v56, v56, v57, s[2:3]
	s_nop 0
	v_fma_f32 v44, v56, v20, -v28
	v_fma_f32 v45, v56, v21, -v29
	v_fma_f32 v46, v56, v22, -v30
	v_fma_f32 v47, v56, v23, -v31
	v_fma_f32 v48, v56, v24, -v32
	v_fma_f32 v49, v56, v25, -v33
	v_fma_f32 v50, v56, v26, -v34
	v_fma_f32 v51, v56, v27, -v35
	v_cvt_pk_bf16_f32 v52, v44, v45
	v_cvt_pk_bf16_f32 v53, v46, v47
	v_cvt_pk_bf16_f32 v54, v48, v49
	v_cvt_pk_bf16_f32 v55, v50, v51
	global_store_dwordx4 v[8:9], v[52:55], off
	v_lshl_add_u64 v[8:9], v[8:9], 0, s[6:7]
	s_waitcnt vmcnt(15)
	v_lshlrev_b32_e32 v36, 16, v76
	v_and_b32_e32 v37, 0xffff0000, v76
	v_lshlrev_b32_e32 v38, 16, v77
	v_and_b32_e32 v39, 0xffff0000, v77
	v_lshlrev_b32_e32 v40, 16, v78
	v_and_b32_e32 v41, 0xffff0000, v78
	v_lshlrev_b32_e32 v42, 16, v79
	v_and_b32_e32 v43, 0xffff0000, v79
	v_cndmask_b32_e64 v36, 0, v36, s[2:3]
	v_cndmask_b32_e64 v37, 0, v37, s[2:3]
	v_cndmask_b32_e64 v38, 0, v38, s[2:3]
	v_cndmask_b32_e64 v39, 0, v39, s[2:3]
	v_cndmask_b32_e64 v40, 0, v40, s[2:3]
	v_cndmask_b32_e64 v41, 0, v41, s[2:3]
	v_cndmask_b32_e64 v42, 0, v42, s[2:3]
	v_cndmask_b32_e64 v43, 0, v43, s[2:3]
	v_sub_f32_e32 v20, v20, v36
	v_sub_f32_e32 v21, v21, v37
	v_sub_f32_e32 v22, v22, v38
	v_sub_f32_e32 v23, v23, v39
	v_sub_f32_e32 v24, v24, v40
	v_sub_f32_e32 v25, v25, v41
	v_sub_f32_e32 v26, v26, v42
	v_sub_f32_e32 v27, v27, v43
	v_lshlrev_b32_e32 v28, 16, v164
	v_and_b32_e32 v29, 0xffff0000, v164
	v_lshlrev_b32_e32 v30, 16, v165
	v_and_b32_e32 v31, 0xffff0000, v165
	v_lshlrev_b32_e32 v32, 16, v166
	v_and_b32_e32 v33, 0xffff0000, v166
	v_lshlrev_b32_e32 v34, 16, v167
	v_and_b32_e32 v35, 0xffff0000, v167
	v_add_f32_e32 v20, v20, v28
	v_add_f32_e32 v21, v21, v29
	v_add_f32_e32 v22, v22, v30
	v_add_f32_e32 v23, v23, v31
	v_add_f32_e32 v24, v24, v32
	v_add_f32_e32 v25, v25, v33
	v_add_f32_e32 v26, v26, v34
	v_add_f32_e32 v27, v27, v35
	v_mov_b32_e32 v56, 0x3daaaaab
	v_mov_b32_e32 v57, 0x3d800000
	v_cndmask_b32_e64 v56, v56, v57, s[2:3]
	s_nop 0
	v_fma_f32 v44, v56, v20, -v28
	v_fma_f32 v45, v56, v21, -v29
	v_fma_f32 v46, v56, v22, -v30
	v_fma_f32 v47, v56, v23, -v31
	v_fma_f32 v48, v56, v24, -v32
	v_fma_f32 v49, v56, v25, -v33
	v_fma_f32 v50, v56, v26, -v34
	v_fma_f32 v51, v56, v27, -v35
	v_cvt_pk_bf16_f32 v52, v44, v45
	v_cvt_pk_bf16_f32 v53, v46, v47
	v_cvt_pk_bf16_f32 v54, v48, v49
	v_cvt_pk_bf16_f32 v55, v50, v51
	global_store_dwordx4 v[8:9], v[52:55], off
	v_lshl_add_u64 v[8:9], v[8:9], 0, s[6:7]
	s_waitcnt vmcnt(15)
	v_lshlrev_b32_e32 v36, 16, v72
	v_and_b32_e32 v37, 0xffff0000, v72
	v_lshlrev_b32_e32 v38, 16, v73
	v_and_b32_e32 v39, 0xffff0000, v73
	v_lshlrev_b32_e32 v40, 16, v74
	v_and_b32_e32 v41, 0xffff0000, v74
	v_lshlrev_b32_e32 v42, 16, v75
	v_and_b32_e32 v43, 0xffff0000, v75
	v_cndmask_b32_e64 v36, 0, v36, s[2:3]
	v_cndmask_b32_e64 v37, 0, v37, s[2:3]
	v_cndmask_b32_e64 v38, 0, v38, s[2:3]
	v_cndmask_b32_e64 v39, 0, v39, s[2:3]
	v_cndmask_b32_e64 v40, 0, v40, s[2:3]
	v_cndmask_b32_e64 v41, 0, v41, s[2:3]
	v_cndmask_b32_e64 v42, 0, v42, s[2:3]
	v_cndmask_b32_e64 v43, 0, v43, s[2:3]
	v_sub_f32_e32 v20, v20, v36
	v_sub_f32_e32 v21, v21, v37
	v_sub_f32_e32 v22, v22, v38
	v_sub_f32_e32 v23, v23, v39
	v_sub_f32_e32 v24, v24, v40
	v_sub_f32_e32 v25, v25, v41
	v_sub_f32_e32 v26, v26, v42
	v_sub_f32_e32 v27, v27, v43
	v_lshlrev_b32_e32 v28, 16, v168
	v_and_b32_e32 v29, 0xffff0000, v168
	v_lshlrev_b32_e32 v30, 16, v169
	v_and_b32_e32 v31, 0xffff0000, v169
	v_lshlrev_b32_e32 v32, 16, v170
	v_and_b32_e32 v33, 0xffff0000, v170
	v_lshlrev_b32_e32 v34, 16, v171
	v_and_b32_e32 v35, 0xffff0000, v171
	v_add_f32_e32 v20, v20, v28
	v_add_f32_e32 v21, v21, v29
	v_add_f32_e32 v22, v22, v30
	v_add_f32_e32 v23, v23, v31
	v_add_f32_e32 v24, v24, v32
	v_add_f32_e32 v25, v25, v33
	v_add_f32_e32 v26, v26, v34
	v_add_f32_e32 v27, v27, v35
	v_mov_b32_e32 v56, 0x3d9d89d9
	v_mov_b32_e32 v57, 0x3d800000
	v_cndmask_b32_e64 v56, v56, v57, s[2:3]
	s_nop 0
	v_fma_f32 v44, v56, v20, -v28
	v_fma_f32 v45, v56, v21, -v29
	v_fma_f32 v46, v56, v22, -v30
	v_fma_f32 v47, v56, v23, -v31
	v_fma_f32 v48, v56, v24, -v32
	v_fma_f32 v49, v56, v25, -v33
	v_fma_f32 v50, v56, v26, -v34
	v_fma_f32 v51, v56, v27, -v35
	v_cvt_pk_bf16_f32 v52, v44, v45
	v_cvt_pk_bf16_f32 v53, v46, v47
	v_cvt_pk_bf16_f32 v54, v48, v49
	v_cvt_pk_bf16_f32 v55, v50, v51
	global_store_dwordx4 v[8:9], v[52:55], off
	v_lshl_add_u64 v[8:9], v[8:9], 0, s[6:7]
	s_waitcnt vmcnt(15)
; __device__ __forceinline__ void phase_pool(const bf16_t* proj, bf16_t* pooled) {
;     ...
;         for (int r = 0; r < 16; ++r) {
;             float f[8]; unpack8(*(const u32x4*)(src + (ptrdiff_t)r * PP), f);
;             const int pos = pos0 + r;
;             if (r >= 1 && pos - w >= 0) { float o[8]; unpack8(*(const u32x4*)(src + (ptrdiff_t)(r - w) * PP), o);
; #pragma unroll
;                 for (int e = 0; e < 8; ++e) sum[e] -= o[e]; }
;             const float rc = 1.0f / (float)(pos + 1 < w ? pos + 1 : w);
;             float out[8];
; #pragma unroll
;             for (int e = 0; e < 8; ++e) { sum[e] += f[e]; out[e] = sum[e] * rc - f[e]; }
;             *(u32x4*)(pooled + (size_t)(r0 + r) * DM + cgi * 8) = pack8(out);
;         }
	v_lshlrev_b32_e32 v36, 16, v68
	v_and_b32_e32 v37, 0xffff0000, v68
	v_lshlrev_b32_e32 v38, 16, v69
	v_and_b32_e32 v39, 0xffff0000, v69
	v_lshlrev_b32_e32 v40, 16, v70
	v_and_b32_e32 v41, 0xffff0000, v70
	v_lshlrev_b32_e32 v42, 16, v71
	v_and_b32_e32 v43, 0xffff0000, v71
	v_cndmask_b32_e64 v36, 0, v36, s[2:3]
	v_cndmask_b32_e64 v37, 0, v37, s[2:3]
	v_cndmask_b32_e64 v38, 0, v38, s[2:3]
	v_cndmask_b32_e64 v39, 0, v39, s[2:3]
	v_cndmask_b32_e64 v40, 0, v40, s[2:3]
	v_cndmask_b32_e64 v41, 0, v41, s[2:3]
	v_cndmask_b32_e64 v42, 0, v42, s[2:3]
	v_cndmask_b32_e64 v43, 0, v43, s[2:3]
	v_sub_f32_e32 v20, v20, v36
	v_sub_f32_e32 v21, v21, v37
	v_sub_f32_e32 v22, v22, v38
	v_sub_f32_e32 v23, v23, v39
	v_sub_f32_e32 v24, v24, v40
	v_sub_f32_e32 v25, v25, v41
	v_sub_f32_e32 v26, v26, v42
	v_sub_f32_e32 v27, v27, v43
	v_lshlrev_b32_e32 v28, 16, v172
	v_and_b32_e32 v29, 0xffff0000, v172
	v_lshlrev_b32_e32 v30, 16, v173
	v_and_b32_e32 v31, 0xffff0000, v173
	v_lshlrev_b32_e32 v32, 16, v174
	v_and_b32_e32 v33, 0xffff0000, v174
	v_lshlrev_b32_e32 v34, 16, v175
	v_and_b32_e32 v35, 0xffff0000, v175
	v_add_f32_e32 v20, v20, v28
	v_add_f32_e32 v21, v21, v29
	v_add_f32_e32 v22, v22, v30
	v_add_f32_e32 v23, v23, v31
	v_add_f32_e32 v24, v24, v32
	v_add_f32_e32 v25, v25, v33
	v_add_f32_e32 v26, v26, v34
	v_add_f32_e32 v27, v27, v35
	v_mov_b32_e32 v56, 0x3d924925
	v_mov_b32_e32 v57, 0x3d800000
	v_cndmask_b32_e64 v56, v56, v57, s[2:3]
	s_nop 0
	v_fma_f32 v44, v56, v20, -v28
	v_fma_f32 v45, v56, v21, -v29
	v_fma_f32 v46, v56, v22, -v30
	v_fma_f32 v47, v56, v23, -v31
	v_fma_f32 v48, v56, v24, -v32
	v_fma_f32 v49, v56, v25, -v33
	v_fma_f32 v50, v56, v26, -v34
	v_fma_f32 v51, v56, v27, -v35
	v_cvt_pk_bf16_f32 v52, v44, v45
	v_cvt_pk_bf16_f32 v53, v46, v47
	v_cvt_pk_bf16_f32 v54, v48, v49
	v_cvt_pk_bf16_f32 v55, v50, v51
	global_store_dwordx4 v[8:9], v[52:55], off
	v_lshl_add_u64 v[8:9], v[8:9], 0, s[6:7]
	s_waitcnt vmcnt(15)
	v_lshlrev_b32_e32 v36, 16, v64
	v_and_b32_e32 v37, 0xffff0000, v64
	v_lshlrev_b32_e32 v38, 16, v65
	v_and_b32_e32 v39, 0xffff0000, v65
	v_lshlrev_b32_e32 v40, 16, v66
	v_and_b32_e32 v41, 0xffff0000, v66
	v_lshlrev_b32_e32 v42, 16, v67
	v_and_b32_e32 v43, 0xffff0000, v67
	v_cndmask_b32_e64 v36, 0, v36, s[2:3]
	v_cndmask_b32_e64 v37, 0, v37, s[2:3]
	v_cndmask_b32_e64 v38, 0, v38, s[2:3]
	v_cndmask_b32_e64 v39, 0, v39, s[2:3]
	v_cndmask_b32_e64 v40, 0, v40, s[2:3]
	v_cndmask_b32_e64 v41, 0, v41, s[2:3]
	v_cndmask_b32_e64 v42, 0, v42, s[2:3]
	v_cndmask_b32_e64 v43, 0, v43, s[2:3]
	v_sub_f32_e32 v20, v20, v36
	v_sub_f32_e32 v21, v21, v37
	v_sub_f32_e32 v22, v22, v38
	v_sub_f32_e32 v23, v23, v39
	v_sub_f32_e32 v24, v24, v40
	v_sub_f32_e32 v25, v25, v41
	v_sub_f32_e32 v26, v26, v42
	v_sub_f32_e32 v27, v27, v43
	v_lshlrev_b32_e32 v28, 16, v176
	v_and_b32_e32 v29, 0xffff0000, v176
	v_lshlrev_b32_e32 v30, 16, v177
	v_and_b32_e32 v31, 0xffff0000, v177
	v_lshlrev_b32_e32 v32, 16, v178
	v_and_b32_e32 v33, 0xffff0000, v178
	v_lshlrev_b32_e32 v34, 16, v179
	v_and_b32_e32 v35, 0xffff0000, v179
	v_add_f32_e32 v20, v20, v28
	v_add_f32_e32 v21, v21, v29
	v_add_f32_e32 v22, v22, v30
	v_add_f32_e32 v23, v23, v31
	v_add_f32_e32 v24, v24, v32
	v_add_f32_e32 v25, v25, v33
	v_add_f32_e32 v26, v26, v34
	v_add_f32_e32 v27, v27, v35
	v_mov_b32_e32 v56, 0x3d888889
	v_mov_b32_e32 v57, 0x3d800000
	v_cndmask_b32_e64 v56, v56, v57, s[2:3]
	s_nop 0
	v_fma_f32 v44, v56, v20, -v28
	v_fma_f32 v45, v56, v21, -v29
	v_fma_f32 v46, v56, v22, -v30
	v_fma_f32 v47, v56, v23, -v31
	v_fma_f32 v48, v56, v24, -v32
	v_fma_f32 v49, v56, v25, -v33
	v_fma_f32 v50, v56, v26, -v34
	v_fma_f32 v51, v56, v27, -v35
	v_cvt_pk_bf16_f32 v52, v44, v45
	v_cvt_pk_bf16_f32 v53, v46, v47
	v_cvt_pk_bf16_f32 v54, v48, v49
	v_cvt_pk_bf16_f32 v55, v50, v51
	global_store_dwordx4 v[8:9], v[52:55], off
	v_lshl_add_u64 v[8:9], v[8:9], 0, s[6:7]
	s_waitcnt vmcnt(15)
	v_lshlrev_b32_e32 v36, 16, v60
	v_and_b32_e32 v37, 0xffff0000, v60
	v_lshlrev_b32_e32 v38, 16, v61
	v_and_b32_e32 v39, 0xffff0000, v61
	v_lshlrev_b32_e32 v40, 16, v62
	v_and_b32_e32 v41, 0xffff0000, v62
	v_lshlrev_b32_e32 v42, 16, v63
	v_and_b32_e32 v43, 0xffff0000, v63
	v_cndmask_b32_e64 v36, 0, v36, s[2:3]
	v_cndmask_b32_e64 v37, 0, v37, s[2:3]
	v_cndmask_b32_e64 v38, 0, v38, s[2:3]
	v_cndmask_b32_e64 v39, 0, v39, s[2:3]
	v_cndmask_b32_e64 v40, 0, v40, s[2:3]
	v_cndmask_b32_e64 v41, 0, v41, s[2:3]
	v_cndmask_b32_e64 v42, 0, v42, s[2:3]
	v_cndmask_b32_e64 v43, 0, v43, s[2:3]
	v_sub_f32_e32 v20, v20, v36
	v_sub_f32_e32 v21, v21, v37
	v_sub_f32_e32 v22, v22, v38
	v_sub_f32_e32 v23, v23, v39
	v_sub_f32_e32 v24, v24, v40
	v_sub_f32_e32 v25, v25, v41
	v_sub_f32_e32 v26, v26, v42
	v_sub_f32_e32 v27, v27, v43
	v_lshlrev_b32_e32 v28, 16, v180
	v_and_b32_e32 v29, 0xffff0000, v180
	v_lshlrev_b32_e32 v30, 16, v181
	v_and_b32_e32 v31, 0xffff0000, v181
	v_lshlrev_b32_e32 v32, 16, v182
	v_and_b32_e32 v33, 0xffff0000, v182
	v_lshlrev_b32_e32 v34, 16, v183
	v_and_b32_e32 v35, 0xffff0000, v183
	v_add_f32_e32 v20, v20, v28
	v_add_f32_e32 v21, v21, v29
	v_add_f32_e32 v22, v22, v30
	v_add_f32_e32 v23, v23, v31
	v_add_f32_e32 v24, v24, v32
	v_add_f32_e32 v25, v25, v33
	v_add_f32_e32 v26, v26, v34
	v_add_f32_e32 v27, v27, v35
	v_mov_b32_e32 v56, 0x3d800000
	s_nop 0
	v_fma_f32 v44, v56, v20, -v28
	v_fma_f32 v45, v56, v21, -v29
	v_fma_f32 v46, v56, v22, -v30
	v_fma_f32 v47, v56, v23, -v31
	v_fma_f32 v48, v56, v24, -v32
	v_fma_f32 v49, v56, v25, -v33
	v_fma_f32 v50, v56, v26, -v34
	v_fma_f32 v51, v56, v27, -v35
	v_cvt_pk_bf16_f32 v52, v44, v45
	v_cvt_pk_bf16_f32 v53, v46, v47
	v_cvt_pk_bf16_f32 v54, v48, v49
	v_cvt_pk_bf16_f32 v55, v50, v51
	global_store_dwordx4 v[8:9], v[52:55], off
	s_branch .Lmy_pool_next
; __device__ __forceinline__ void phase_pool(const bf16_t* proj, bf16_t* pooled) {
;     ...
;         const int cgi = idx & 127, seg = idx >> 7, r0 = seg * 16, pos0 = r0 & (SEQ - 1), w = 2 << (cgi >> 5);
;         const bf16_t* src = proj + SEC(C_PU) + (size_t)r0 * PP + cgi * 8;
;         float sum[8];
; #pragma unroll
;         for (int e = 0; e < 8; ++e) sum[e] = 0.f;
;         if (pos0 > 0) for (int j = 1; j < w; ++j) { float f[8]; unpack8(*(const u32x4*)(src - (ptrdiff_t)j * PP), f);
; #pragma unroll
;             for (int e = 0; e < 8; ++e) sum[e] += f[e]; }
.Lmy_pool_w8:
	v_lshl_add_u64 v[10:11], v[6:7], 0, s[8:9]
	global_load_dwordx4 v[60:63], v[10:11], off
	v_lshl_add_u64 v[10:11], v[10:11], 0, s[8:9]
	global_load_dwordx4 v[64:67], v[10:11], off
	v_lshl_add_u64 v[10:11], v[10:11], 0, s[8:9]
	global_load_dwordx4 v[68:71], v[10:11], off
	v_lshl_add_u64 v[10:11], v[10:11], 0, s[8:9]
	global_load_dwordx4 v[72:75], v[10:11], off
	v_lshl_add_u64 v[10:11], v[10:11], 0, s[8:9]
	global_load_dwordx4 v[76:79], v[10:11], off
	v_lshl_add_u64 v[10:11], v[10:11], 0, s[8:9]
	global_load_dwordx4 v[80:83], v[10:11], off
	v_lshl_add_u64 v[10:11], v[10:11], 0, s[8:9]
	global_load_dwordx4 v[84:87], v[10:11], off
	v_mov_b32_e32 v10, v6
	v_mov_b32_e32 v11, v7
	global_load_dwordx4 v[120:123], v[10:11], off
	v_lshl_add_u64 v[10:11], v[10:11], 0, s[6:7]
	global_load_dwordx4 v[124:127], v[10:11], off
	v_lshl_add_u64 v[10:11], v[10:11], 0, s[6:7]
	global_load_dwordx4 v[128:131], v[10:11], off
	v_lshl_add_u64 v[10:11], v[10:11], 0, s[6:7]
	global_load_dwordx4 v[132:135], v[10:11], off
	v_lshl_add_u64 v[10:11], v[10:11], 0, s[6:7]
	global_load_dwordx4 v[136:139], v[10:11], off
	v_lshl_add_u64 v[10:11], v[10:11], 0, s[6:7]
	global_load_dwordx4 v[140:143], v[10:11], off
	v_lshl_add_u64 v[10:11], v[10:11], 0, s[6:7]
	global_load_dwordx4 v[144:147], v[10:11], off
	v_lshl_add_u64 v[10:11], v[10:11], 0, s[6:7]
	global_load_dwordx4 v[148:151], v[10:11], off
	v_lshl_add_u64 v[10:11], v[10:11], 0, s[6:7]
	global_load_dwordx4 v[152:155], v[10:11], off
	v_lshl_add_u64 v[10:11], v[10:11], 0, s[6:7]
	global_load_dwordx4 v[156:159], v[10:11], off
	v_lshl_add_u64 v[10:11], v[10:11], 0, s[6:7]
	global_load_dwordx4 v[160:163], v[10:11], off
	v_lshl_add_u64 v[10:11], v[10:11], 0, s[6:7]
	global_load_dwordx4 v[164:167], v[10:11], off
	v_lshl_add_u64 v[10:11], v[10:11], 0, s[6:7]
	global_load_dwordx4 v[168:171], v[10:11], off
	v_lshl_add_u64 v[10:11], v[10:11], 0, s[6:7]
	global_load_dwordx4 v[172:175], v[10:11], off
	v_lshl_add_u64 v[10:11], v[10:11], 0, s[6:7]
	global_load_dwordx4 v[176:179], v[10:11], off
	v_lshl_add_u64 v[10:11], v[10:11], 0, s[6:7]
	global_load_dwordx4 v[180:183], v[10:11], off
	v_mov_b32_e32 v20, 0
	v_mov_b32_e32 v21, 0
	v_mov_b32_e32 v22, 0
	v_mov_b32_e32 v23, 0
	v_mov_b32_e32 v24, 0
	v_mov_b32_e32 v25, 0
	v_mov_b32_e32 v26, 0
	v_mov_b32_e32 v27, 0
	s_waitcnt vmcnt(22)
	v_lshlrev_b32_e32 v28, 16, v60
	v_and_b32_e32 v29, 0xffff0000, v60
	v_lshlrev_b32_e32 v30, 16, v61
	v_and_b32_e32 v31, 0xffff0000, v61
	v_lshlrev_b32_e32 v32, 16, v62
	v_and_b32_e32 v33, 0xffff0000, v62
	v_lshlrev_b32_e32 v34, 16, v63
	v_and_b32_e32 v35, 0xffff0000, v63
	v_cndmask_b32_e64 v28, 0, v28, s[2:3]
	v_cndmask_b32_e64 v29, 0, v29, s[2:3]
	v_cndmask_b32_e64 v30, 0, v30, s[2:3]
	v_cndmask_b32_e64 v31, 0, v31, s[2:3]
	v_cndmask_b32_e64 v32, 0, v32, s[2:3]
	v_cndmask_b32_e64 v33, 0, v33, s[2:3]
	v_cndmask_b32_e64 v34, 0, v34, s[2:3]
	v_cndmask_b32_e64 v35, 0, v35, s[2:3]
	v_add_f32_e32 v20, v20, v28
	v_add_f32_e32 v21, v21, v29
	v_add_f32_e32 v22, v22, v30
	v_add_f32_e32 v23, v23, v31
	v_add_f32_e32 v24, v24, v32
	v_add_f32_e32 v25, v25, v33
	v_add_f32_e32 v26, v26, v34
	v_add_f32_e32 v27, v27, v35
	s_waitcnt vmcnt(21)
	v_lshlrev_b32_e32 v28, 16, v64
	v_and_b32_e32 v29, 0xffff0000, v64
	v_lshlrev_b32_e32 v30, 16, v65
	v_and_b32_e32 v31, 0xffff0000, v65
	v_lshlrev_b32_e32 v32, 16, v66
	v_and_b32_e32 v33, 0xffff0000, v66
	v_lshlrev_b32_e32 v34, 16, v67
	v_and_b32_e32 v35, 0xffff0000, v67
	v_cndmask_b32_e64 v28, 0, v28, s[2:3]
	v_cndmask_b32_e64 v29, 0, v29, s[2:3]
	v_cndmask_b32_e64 v30, 0, v30, s[2:3]
	v_cndmask_b32_e64 v31, 0, v31, s[2:3]
	v_cndmask_b32_e64 v32, 0, v32, s[2:3]
	v_cndmask_b32_e64 v33, 0, v33, s[2:3]
	v_cndmask_b32_e64 v34, 0, v34, s[2:3]
	v_cndmask_b32_e64 v35, 0, v35, s[2:3]
	v_add_f32_e32 v20, v20, v28
	v_add_f32_e32 v21, v21, v29
	v_add_f32_e32 v22, v22, v30
	v_add_f32_e32 v23, v23, v31
	v_add_f32_e32 v24, v24, v32
	v_add_f32_e32 v25, v25, v33
	v_add_f32_e32 v26, v26, v34
	v_add_f32_e32 v27, v27, v35
	s_waitcnt vmcnt(20)
	v_lshlrev_b32_e32 v28, 16, v68
	v_and_b32_e32 v29, 0xffff0000, v68
	v_lshlrev_b32_e32 v30, 16, v69
	v_and_b32_e32 v31, 0xffff0000, v69
	v_lshlrev_b32_e32 v32, 16, v70
	v_and_b32_e32 v33, 0xffff0000, v70
	v_lshlrev_b32_e32 v34, 16, v71
	v_and_b32_e32 v35, 0xffff0000, v71
	v_cndmask_b32_e64 v28, 0, v28, s[2:3]
	v_cndmask_b32_e64 v29, 0, v29, s[2:3]
	v_cndmask_b32_e64 v30, 0, v30, s[2:3]
	v_cndmask_b32_e64 v31, 0, v31, s[2:3]
	v_cndmask_b32_e64 v32, 0, v32, s[2:3]
	v_cndmask_b32_e64 v33, 0, v33, s[2:3]
	v_cndmask_b32_e64 v34, 0, v34, s[2:3]
	v_cndmask_b32_e64 v35, 0, v35, s[2:3]
	v_add_f32_e32 v20, v20, v28
	v_add_f32_e32 v21, v21, v29
	v_add_f32_e32 v22, v22, v30
	v_add_f32_e32 v23, v23, v31
	v_add_f32_e32 v24, v24, v32
	v_add_f32_e32 v25, v25, v33
	v_add_f32_e32 v26, v26, v34
	v_add_f32_e32 v27, v27, v35
	s_waitcnt vmcnt(19)
	v_lshlrev_b32_e32 v28, 16, v72
	v_and_b32_e32 v29, 0xffff0000, v72
	v_lshlrev_b32_e32 v30, 16, v73
	v_and_b32_e32 v31, 0xffff0000, v73
	v_lshlrev_b32_e32 v32, 16, v74
	v_and_b32_e32 v33, 0xffff0000, v74
	v_lshlrev_b32_e32 v34, 16, v75
	v_and_b32_e32 v35, 0xffff0000, v75
	v_cndmask_b32_e64 v28, 0, v28, s[2:3]
	v_cndmask_b32_e64 v29, 0, v29, s[2:3]
	v_cndmask_b32_e64 v30, 0, v30, s[2:3]
	v_cndmask_b32_e64 v31, 0, v31, s[2:3]
	v_cndmask_b32_e64 v32, 0, v32, s[2:3]
	v_cndmask_b32_e64 v33, 0, v33, s[2:3]
	v_cndmask_b32_e64 v34, 0, v34, s[2:3]
	v_cndmask_b32_e64 v35, 0, v35, s[2:3]
	v_add_f32_e32 v20, v20, v28
	v_add_f32_e32 v21, v21, v29
	v_add_f32_e32 v22, v22, v30
	v_add_f32_e32 v23, v23, v31
	v_add_f32_e32 v24, v24, v32
	v_add_f32_e32 v25, v25, v33
	v_add_f32_e32 v26, v26, v34
	v_add_f32_e32 v27, v27, v35
	s_waitcnt vmcnt(18)
; __device__ __forceinline__ void phase_pool(const bf16_t* proj, bf16_t* pooled) {
;     ...
;         if (pos0 > 0) for (int j = 1; j < w; ++j) { float f[8]; unpack8(*(const u32x4*)(src - (ptrdiff_t)j * PP), f);
; #pragma unroll
;             for (int e = 0; e < 8; ++e) sum[e] += f[e]; }
;         for (int r = 0; r < 16; ++r) {
;             float f[8]; unpack8(*(const u32x4*)(src + (ptrdiff_t)r * PP), f);
;             const int pos = pos0 + r;
;             if (r >= 1 && pos - w >= 0) { float o[8]; unpack8(*(const u32x4*)(src + (ptrdiff_t)(r - w) * PP), o);
; #pragma unroll
;                 for (int e = 0; e < 8; ++e) sum[e] -= o[e]; }
;             const float rc = 1.0f / (float)(pos + 1 < w ? pos + 1 : w);
;             float out[8];
; #pragma unroll
;             for (int e = 0; e < 8; ++e) { sum[e] += f[e]; out[e] = sum[e] * rc - f[e]; }
;             *(u32x4*)(pooled + (size_t)(r0 + r) * DM + cgi * 8) = pack8(out);
	v_lshlrev_b32_e32 v28, 16, v76
	v_and_b32_e32 v29, 0xffff0000, v76
	v_lshlrev_b32_e32 v30, 16, v77
	v_and_b32_e32 v31, 0xffff0000, v77
	v_lshlrev_b32_e32 v32, 16, v78
	v_and_b32_e32 v33, 0xffff0000, v78
	v_lshlrev_b32_e32 v34, 16, v79
	v_and_b32_e32 v35, 0xffff0000, v79
	v_cndmask_b32_e64 v28, 0, v28, s[2:3]
	v_cndmask_b32_e64 v29, 0, v29, s[2:3]
	v_cndmask_b32_e64 v30, 0, v30, s[2:3]
	v_cndmask_b32_e64 v31, 0, v31, s[2:3]
	v_cndmask_b32_e64 v32, 0, v32, s[2:3]
	v_cndmask_b32_e64 v33, 0, v33, s[2:3]
	v_cndmask_b32_e64 v34, 0, v34, s[2:3]
	v_cndmask_b32_e64 v35, 0, v35, s[2:3]
	v_add_f32_e32 v20, v20, v28
	v_add_f32_e32 v21, v21, v29
	v_add_f32_e32 v22, v22, v30
	v_add_f32_e32 v23, v23, v31
	v_add_f32_e32 v24, v24, v32
	v_add_f32_e32 v25, v25, v33
	v_add_f32_e32 v26, v26, v34
	v_add_f32_e32 v27, v27, v35
	s_waitcnt vmcnt(17)
	v_lshlrev_b32_e32 v28, 16, v80
	v_and_b32_e32 v29, 0xffff0000, v80
	v_lshlrev_b32_e32 v30, 16, v81
	v_and_b32_e32 v31, 0xffff0000, v81
	v_lshlrev_b32_e32 v32, 16, v82
	v_and_b32_e32 v33, 0xffff0000, v82
	v_lshlrev_b32_e32 v34, 16, v83
	v_and_b32_e32 v35, 0xffff0000, v83
	v_cndmask_b32_e64 v28, 0, v28, s[2:3]
	v_cndmask_b32_e64 v29, 0, v29, s[2:3]
	v_cndmask_b32_e64 v30, 0, v30, s[2:3]
	v_cndmask_b32_e64 v31, 0, v31, s[2:3]
	v_cndmask_b32_e64 v32, 0, v32, s[2:3]
	v_cndmask_b32_e64 v33, 0, v33, s[2:3]
	v_cndmask_b32_e64 v34, 0, v34, s[2:3]
	v_cndmask_b32_e64 v35, 0, v35, s[2:3]
	v_add_f32_e32 v20, v20, v28
	v_add_f32_e32 v21, v21, v29
	v_add_f32_e32 v22, v22, v30
	v_add_f32_e32 v23, v23, v31
	v_add_f32_e32 v24, v24, v32
	v_add_f32_e32 v25, v25, v33
	v_add_f32_e32 v26, v26, v34
	v_add_f32_e32 v27, v27, v35
	s_waitcnt vmcnt(16)
	v_lshlrev_b32_e32 v28, 16, v84
	v_and_b32_e32 v29, 0xffff0000, v84
	v_lshlrev_b32_e32 v30, 16, v85
	v_and_b32_e32 v31, 0xffff0000, v85
	v_lshlrev_b32_e32 v32, 16, v86
	v_and_b32_e32 v33, 0xffff0000, v86
	v_lshlrev_b32_e32 v34, 16, v87
	v_and_b32_e32 v35, 0xffff0000, v87
	v_cndmask_b32_e64 v28, 0, v28, s[2:3]
	v_cndmask_b32_e64 v29, 0, v29, s[2:3]
	v_cndmask_b32_e64 v30, 0, v30, s[2:3]
	v_cndmask_b32_e64 v31, 0, v31, s[2:3]
	v_cndmask_b32_e64 v32, 0, v32, s[2:3]
	v_cndmask_b32_e64 v33, 0, v33, s[2:3]
	v_cndmask_b32_e64 v34, 0, v34, s[2:3]
	v_cndmask_b32_e64 v35, 0, v35, s[2:3]
	v_add_f32_e32 v20, v20, v28
	v_add_f32_e32 v21, v21, v29
	v_add_f32_e32 v22, v22, v30
	v_add_f32_e32 v23, v23, v31
	v_add_f32_e32 v24, v24, v32
	v_add_f32_e32 v25, v25, v33
	v_add_f32_e32 v26, v26, v34
	v_add_f32_e32 v27, v27, v35
	s_waitcnt vmcnt(15)
	v_lshlrev_b32_e32 v28, 16, v120
	v_and_b32_e32 v29, 0xffff0000, v120
	v_lshlrev_b32_e32 v30, 16, v121
	v_and_b32_e32 v31, 0xffff0000, v121
	v_lshlrev_b32_e32 v32, 16, v122
	v_and_b32_e32 v33, 0xffff0000, v122
	v_lshlrev_b32_e32 v34, 16, v123
	v_and_b32_e32 v35, 0xffff0000, v123
	v_add_f32_e32 v20, v20, v28
	v_add_f32_e32 v21, v21, v29
	v_add_f32_e32 v22, v22, v30
	v_add_f32_e32 v23, v23, v31
	v_add_f32_e32 v24, v24, v32
	v_add_f32_e32 v25, v25, v33
	v_add_f32_e32 v26, v26, v34
	v_add_f32_e32 v27, v27, v35
	v_mov_b32_e32 v56, 0x3f800000
	v_mov_b32_e32 v57, 0x3e000000
	v_cndmask_b32_e64 v56, v56, v57, s[2:3]
	s_nop 0
	v_fma_f32 v44, v56, v20, -v28
	v_fma_f32 v45, v56, v21, -v29
	v_fma_f32 v46, v56, v22, -v30
	v_fma_f32 v47, v56, v23, -v31
	v_fma_f32 v48, v56, v24, -v32
	v_fma_f32 v49, v56, v25, -v33
	v_fma_f32 v50, v56, v26, -v34
	v_fma_f32 v51, v56, v27, -v35
	v_cvt_pk_bf16_f32 v52, v44, v45
	v_cvt_pk_bf16_f32 v53, v46, v47
	v_cvt_pk_bf16_f32 v54, v48, v49
	v_cvt_pk_bf16_f32 v55, v50, v51
	global_store_dwordx4 v[8:9], v[52:55], off
	v_lshl_add_u64 v[8:9], v[8:9], 0, s[6:7]
	s_waitcnt vmcnt(15)
	v_lshlrev_b32_e32 v36, 16, v84
	v_and_b32_e32 v37, 0xffff0000, v84
	v_lshlrev_b32_e32 v38, 16, v85
	v_and_b32_e32 v39, 0xffff0000, v85
	v_lshlrev_b32_e32 v40, 16, v86
	v_and_b32_e32 v41, 0xffff0000, v86
	v_lshlrev_b32_e32 v42, 16, v87
	v_and_b32_e32 v43, 0xffff0000, v87
	v_cndmask_b32_e64 v36, 0, v36, s[2:3]
	v_cndmask_b32_e64 v37, 0, v37, s[2:3]
	v_cndmask_b32_e64 v38, 0, v38, s[2:3]
	v_cndmask_b32_e64 v39, 0, v39, s[2:3]
	v_cndmask_b32_e64 v40, 0, v40, s[2:3]
	v_cndmask_b32_e64 v41, 0, v41, s[2:3]
	v_cndmask_b32_e64 v42, 0, v42, s[2:3]
	v_cndmask_b32_e64 v43, 0, v43, s[2:3]
	v_sub_f32_e32 v20, v20, v36
	v_sub_f32_e32 v21, v21, v37
	v_sub_f32_e32 v22, v22, v38
	v_sub_f32_e32 v23, v23, v39
	v_sub_f32_e32 v24, v24, v40
	v_sub_f32_e32 v25, v25, v41
	v_sub_f32_e32 v26, v26, v42
	v_sub_f32_e32 v27, v27, v43
	v_lshlrev_b32_e32 v28, 16, v124
	v_and_b32_e32 v29, 0xffff0000, v124
	v_lshlrev_b32_e32 v30, 16, v125
	v_and_b32_e32 v31, 0xffff0000, v125
	v_lshlrev_b32_e32 v32, 16, v126
	v_and_b32_e32 v33, 0xffff0000, v126
	v_lshlrev_b32_e32 v34, 16, v127
	v_and_b32_e32 v35, 0xffff0000, v127
	v_add_f32_e32 v20, v20, v28
	v_add_f32_e32 v21, v21, v29
	v_add_f32_e32 v22, v22, v30
	v_add_f32_e32 v23, v23, v31
	v_add_f32_e32 v24, v24, v32
	v_add_f32_e32 v25, v25, v33
	v_add_f32_e32 v26, v26, v34
	v_add_f32_e32 v27, v27, v35
	v_mov_b32_e32 v56, 0x3f000000
	v_mov_b32_e32 v57, 0x3e000000
	v_cndmask_b32_e64 v56, v56, v57, s[2:3]
	s_nop 0
	v_fma_f32 v44, v56, v20, -v28
	v_fma_f32 v45, v56, v21, -v29
	v_fma_f32 v46, v56, v22, -v30
	v_fma_f32 v47, v56, v23, -v31
	v_fma_f32 v48, v56, v24, -v32
	v_fma_f32 v49, v56, v25, -v33
	v_fma_f32 v50, v56, v26, -v34
	v_fma_f32 v51, v56, v27, -v35
	v_cvt_pk_bf16_f32 v52, v44, v45
	v_cvt_pk_bf16_f32 v53, v46, v47
	v_cvt_pk_bf16_f32 v54, v48, v49
	v_cvt_pk_bf16_f32 v55, v50, v51
	global_store_dwordx4 v[8:9], v[52:55], off
	v_lshl_add_u64 v[8:9], v[8:9], 0, s[6:7]
	s_waitcnt vmcnt(15)
; __device__ __forceinline__ void phase_pool(const bf16_t* proj, bf16_t* pooled) {
;     ...
;         for (int r = 0; r < 16; ++r) {
;             float f[8]; unpack8(*(const u32x4*)(src + (ptrdiff_t)r * PP), f);
;             const int pos = pos0 + r;
;             if (r >= 1 && pos - w >= 0) { float o[8]; unpack8(*(const u32x4*)(src + (ptrdiff_t)(r - w) * PP), o);
; #pragma unroll
;                 for (int e = 0; e < 8; ++e) sum[e] -= o[e]; }
;             const float rc = 1.0f / (float)(pos + 1 < w ? pos + 1 : w);
;             float out[8];
; #pragma unroll
;             for (int e = 0; e < 8; ++e) { sum[e] += f[e]; out[e] = sum[e] * rc - f[e]; }
;             *(u32x4*)(pooled + (size_t)(r0 + r) * DM + cgi * 8) = pack8(out);
	v_lshlrev_b32_e32 v36, 16, v80
	v_and_b32_e32 v37, 0xffff0000, v80
	v_lshlrev_b32_e32 v38, 16, v81
	v_and_b32_e32 v39, 0xffff0000, v81
	v_lshlrev_b32_e32 v40, 16, v82
	v_and_b32_e32 v41, 0xffff0000, v82
	v_lshlrev_b32_e32 v42, 16, v83
	v_and_b32_e32 v43, 0xffff0000, v83
	v_cndmask_b32_e64 v36, 0, v36, s[2:3]
	v_cndmask_b32_e64 v37, 0, v37, s[2:3]
	v_cndmask_b32_e64 v38, 0, v38, s[2:3]
	v_cndmask_b32_e64 v39, 0, v39, s[2:3]
	v_cndmask_b32_e64 v40, 0, v40, s[2:3]
	v_cndmask_b32_e64 v41, 0, v41, s[2:3]
	v_cndmask_b32_e64 v42, 0, v42, s[2:3]
	v_cndmask_b32_e64 v43, 0, v43, s[2:3]
	v_sub_f32_e32 v20, v20, v36
	v_sub_f32_e32 v21, v21, v37
	v_sub_f32_e32 v22, v22, v38
	v_sub_f32_e32 v23, v23, v39
	v_sub_f32_e32 v24, v24, v40
	v_sub_f32_e32 v25, v25, v41
	v_sub_f32_e32 v26, v26, v42
	v_sub_f32_e32 v27, v27, v43
	v_lshlrev_b32_e32 v28, 16, v128
	v_and_b32_e32 v29, 0xffff0000, v128
	v_lshlrev_b32_e32 v30, 16, v129
	v_and_b32_e32 v31, 0xffff0000, v129
	v_lshlrev_b32_e32 v32, 16, v130
	v_and_b32_e32 v33, 0xffff0000, v130
	v_lshlrev_b32_e32 v34, 16, v131
	v_and_b32_e32 v35, 0xffff0000, v131
	v_add_f32_e32 v20, v20, v28
	v_add_f32_e32 v21, v21, v29
	v_add_f32_e32 v22, v22, v30
	v_add_f32_e32 v23, v23, v31
	v_add_f32_e32 v24, v24, v32
	v_add_f32_e32 v25, v25, v33
	v_add_f32_e32 v26, v26, v34
	v_add_f32_e32 v27, v27, v35
	v_mov_b32_e32 v56, 0x3eaaaaab
	v_mov_b32_e32 v57, 0x3e000000
	v_cndmask_b32_e64 v56, v56, v57, s[2:3]
	s_nop 0
	v_fma_f32 v44, v56, v20, -v28
	v_fma_f32 v45, v56, v21, -v29
	v_fma_f32 v46, v56, v22, -v30
	v_fma_f32 v47, v56, v23, -v31
	v_fma_f32 v48, v56, v24, -v32
	v_fma_f32 v49, v56, v25, -v33
	v_fma_f32 v50, v56, v26, -v34
	v_fma_f32 v51, v56, v27, -v35
	v_cvt_pk_bf16_f32 v52, v44, v45
	v_cvt_pk_bf16_f32 v53, v46, v47
	v_cvt_pk_bf16_f32 v54, v48, v49
	v_cvt_pk_bf16_f32 v55, v50, v51
	global_store_dwordx4 v[8:9], v[52:55], off
	v_lshl_add_u64 v[8:9], v[8:9], 0, s[6:7]
	s_waitcnt vmcnt(15)
	v_lshlrev_b32_e32 v36, 16, v76
	v_and_b32_e32 v37, 0xffff0000, v76
	v_lshlrev_b32_e32 v38, 16, v77
	v_and_b32_e32 v39, 0xffff0000, v77
	v_lshlrev_b32_e32 v40, 16, v78
	v_and_b32_e32 v41, 0xffff0000, v78
	v_lshlrev_b32_e32 v42, 16, v79
	v_and_b32_e32 v43, 0xffff0000, v79
	v_cndmask_b32_e64 v36, 0, v36, s[2:3]
	v_cndmask_b32_e64 v37, 0, v37, s[2:3]
	v_cndmask_b32_e64 v38, 0, v38, s[2:3]
	v_cndmask_b32_e64 v39, 0, v39, s[2:3]
	v_cndmask_b32_e64 v40, 0, v40, s[2:3]
	v_cndmask_b32_e64 v41, 0, v41, s[2:3]
	v_cndmask_b32_e64 v42, 0, v42, s[2:3]
	v_cndmask_b32_e64 v43, 0, v43, s[2:3]
	v_sub_f32_e32 v20, v20, v36
	v_sub_f32_e32 v21, v21, v37
	v_sub_f32_e32 v22, v22, v38
	v_sub_f32_e32 v23, v23, v39
	v_sub_f32_e32 v24, v24, v40
	v_sub_f32_e32 v25, v25, v41
	v_sub_f32_e32 v26, v26, v42
	v_sub_f32_e32 v27, v27, v43
	v_lshlrev_b32_e32 v28, 16, v132
	v_and_b32_e32 v29, 0xffff0000, v132
	v_lshlrev_b32_e32 v30, 16, v133
	v_and_b32_e32 v31, 0xffff0000, v133
	v_lshlrev_b32_e32 v32, 16, v134
	v_and_b32_e32 v33, 0xffff0000, v134
	v_lshlrev_b32_e32 v34, 16, v135
	v_and_b32_e32 v35, 0xffff0000, v135
	v_add_f32_e32 v20, v20, v28
	v_add_f32_e32 v21, v21, v29
	v_add_f32_e32 v22, v22, v30
	v_add_f32_e32 v23, v23, v31
	v_add_f32_e32 v24, v24, v32
	v_add_f32_e32 v25, v25, v33
	v_add_f32_e32 v26, v26, v34
	v_add_f32_e32 v27, v27, v35
	v_mov_b32_e32 v56, 0x3e800000
	v_mov_b32_e32 v57, 0x3e000000
	v_cndmask_b32_e64 v56, v56, v57, s[2:3]
	s_nop 0
	v_fma_f32 v44, v56, v20, -v28
	v_fma_f32 v45, v56, v21, -v29
	v_fma_f32 v46, v56, v22, -v30
	v_fma_f32 v47, v56, v23, -v31
	v_fma_f32 v48, v56, v24, -v32
	v_fma_f32 v49, v56, v25, -v33
	v_fma_f32 v50, v56, v26, -v34
	v_fma_f32 v51, v56, v27, -v35
	v_cvt_pk_bf16_f32 v52, v44, v45
	v_cvt_pk_bf16_f32 v53, v46, v47
	v_cvt_pk_bf16_f32 v54, v48, v49
	v_cvt_pk_bf16_f32 v55, v50, v51
	global_store_dwordx4 v[8:9], v[52:55], off
	v_lshl_add_u64 v[8:9], v[8:9], 0, s[6:7]
	s_waitcnt vmcnt(15)
	v_lshlrev_b32_e32 v36, 16, v72
	v_and_b32_e32 v37, 0xffff0000, v72
	v_lshlrev_b32_e32 v38, 16, v73
	v_and_b32_e32 v39, 0xffff0000, v73
	v_lshlrev_b32_e32 v40, 16, v74
	v_and_b32_e32 v41, 0xffff0000, v74
	v_lshlrev_b32_e32 v42, 16, v75
	v_and_b32_e32 v43, 0xffff0000, v75
	v_cndmask_b32_e64 v36, 0, v36, s[2:3]
	v_cndmask_b32_e64 v37, 0, v37, s[2:3]
	v_cndmask_b32_e64 v38, 0, v38, s[2:3]
	v_cndmask_b32_e64 v39, 0, v39, s[2:3]
	v_cndmask_b32_e64 v40, 0, v40, s[2:3]
	v_cndmask_b32_e64 v41, 0, v41, s[2:3]
	v_cndmask_b32_e64 v42, 0, v42, s[2:3]
	v_cndmask_b32_e64 v43, 0, v43, s[2:3]
	v_sub_f32_e32 v20, v20, v36
	v_sub_f32_e32 v21, v21, v37
	v_sub_f32_e32 v22, v22, v38
	v_sub_f32_e32 v23, v23, v39
	v_sub_f32_e32 v24, v24, v40
	v_sub_f32_e32 v25, v25, v41
	v_sub_f32_e32 v26, v26, v42
	v_sub_f32_e32 v27, v27, v43
	v_lshlrev_b32_e32 v28, 16, v136
	v_and_b32_e32 v29, 0xffff0000, v136
	v_lshlrev_b32_e32 v30, 16, v137
	v_and_b32_e32 v31, 0xffff0000, v137
	v_lshlrev_b32_e32 v32, 16, v138
	v_and_b32_e32 v33, 0xffff0000, v138
	v_lshlrev_b32_e32 v34, 16, v139
	v_and_b32_e32 v35, 0xffff0000, v139
	v_add_f32_e32 v20, v20, v28
	v_add_f32_e32 v21, v21, v29
	v_add_f32_e32 v22, v22, v30
	v_add_f32_e32 v23, v23, v31
	v_add_f32_e32 v24, v24, v32
	v_add_f32_e32 v25, v25, v33
	v_add_f32_e32 v26, v26, v34
	v_add_f32_e32 v27, v27, v35
	v_mov_b32_e32 v56, 0x3e4ccccd
	v_mov_b32_e32 v57, 0x3e000000
	v_cndmask_b32_e64 v56, v56, v57, s[2:3]
	s_nop 0
	v_fma_f32 v44, v56, v20, -v28
	v_fma_f32 v45, v56, v21, -v29
	v_fma_f32 v46, v56, v22, -v30
	v_fma_f32 v47, v56, v23, -v31
	v_fma_f32 v48, v56, v24, -v32
	v_fma_f32 v49, v56, v25, -v33
	v_fma_f32 v50, v56, v26, -v34
	v_fma_f32 v51, v56, v27, -v35
	v_cvt_pk_bf16_f32 v52, v44, v45
	v_cvt_pk_bf16_f32 v53, v46, v47
	v_cvt_pk_bf16_f32 v54, v48, v49
	v_cvt_pk_bf16_f32 v55, v50, v51
	global_store_dwordx4 v[8:9], v[52:55], off
	v_lshl_add_u64 v[8:9], v[8:9], 0, s[6:7]
	s_waitcnt vmcnt(15)
; __device__ __forceinline__ void phase_pool(const bf16_t* proj, bf16_t* pooled) {
;     ...
;         for (int r = 0; r < 16; ++r) {
;             float f[8]; unpack8(*(const u32x4*)(src + (ptrdiff_t)r * PP), f);
;             const int pos = pos0 + r;
;             if (r >= 1 && pos - w >= 0) { float o[8]; unpack8(*(const u32x4*)(src + (ptrdiff_t)(r - w) * PP), o);
; #pragma unroll
;                 for (int e = 0; e < 8; ++e) sum[e] -= o[e]; }
;             const float rc = 1.0f / (float)(pos + 1 < w ? pos + 1 : w);
;             float out[8];
; #pragma unroll
;             for (int e = 0; e < 8; ++e) { sum[e] += f[e]; out[e] = sum[e] * rc - f[e]; }
;             *(u32x4*)(pooled + (size_t)(r0 + r) * DM + cgi * 8) = pack8(out);
	v_lshlrev_b32_e32 v36, 16, v68
	v_and_b32_e32 v37, 0xffff0000, v68
	v_lshlrev_b32_e32 v38, 16, v69
	v_and_b32_e32 v39, 0xffff0000, v69
	v_lshlrev_b32_e32 v40, 16, v70
	v_and_b32_e32 v41, 0xffff0000, v70
	v_lshlrev_b32_e32 v42, 16, v71
	v_and_b32_e32 v43, 0xffff0000, v71
	v_cndmask_b32_e64 v36, 0, v36, s[2:3]
	v_cndmask_b32_e64 v37, 0, v37, s[2:3]
	v_cndmask_b32_e64 v38, 0, v38, s[2:3]
	v_cndmask_b32_e64 v39, 0, v39, s[2:3]
	v_cndmask_b32_e64 v40, 0, v40, s[2:3]
	v_cndmask_b32_e64 v41, 0, v41, s[2:3]
	v_cndmask_b32_e64 v42, 0, v42, s[2:3]
	v_cndmask_b32_e64 v43, 0, v43, s[2:3]
	v_sub_f32_e32 v20, v20, v36
	v_sub_f32_e32 v21, v21, v37
	v_sub_f32_e32 v22, v22, v38
	v_sub_f32_e32 v23, v23, v39
	v_sub_f32_e32 v24, v24, v40
	v_sub_f32_e32 v25, v25, v41
	v_sub_f32_e32 v26, v26, v42
	v_sub_f32_e32 v27, v27, v43
	v_lshlrev_b32_e32 v28, 16, v140
	v_and_b32_e32 v29, 0xffff0000, v140
	v_lshlrev_b32_e32 v30, 16, v141
	v_and_b32_e32 v31, 0xffff0000, v141
	v_lshlrev_b32_e32 v32, 16, v142
	v_and_b32_e32 v33, 0xffff0000, v142
	v_lshlrev_b32_e32 v34, 16, v143
	v_and_b32_e32 v35, 0xffff0000, v143
	v_add_f32_e32 v20, v20, v28
	v_add_f32_e32 v21, v21, v29
	v_add_f32_e32 v22, v22, v30
	v_add_f32_e32 v23, v23, v31
	v_add_f32_e32 v24, v24, v32
	v_add_f32_e32 v25, v25, v33
	v_add_f32_e32 v26, v26, v34
	v_add_f32_e32 v27, v27, v35
	v_mov_b32_e32 v56, 0x3e2aaaab
	v_mov_b32_e32 v57, 0x3e000000
	v_cndmask_b32_e64 v56, v56, v57, s[2:3]
	s_nop 0
	v_fma_f32 v44, v56, v20, -v28
	v_fma_f32 v45, v56, v21, -v29
	v_fma_f32 v46, v56, v22, -v30
	v_fma_f32 v47, v56, v23, -v31
	v_fma_f32 v48, v56, v24, -v32
	v_fma_f32 v49, v56, v25, -v33
	v_fma_f32 v50, v56, v26, -v34
	v_fma_f32 v51, v56, v27, -v35
	v_cvt_pk_bf16_f32 v52, v44, v45
	v_cvt_pk_bf16_f32 v53, v46, v47
	v_cvt_pk_bf16_f32 v54, v48, v49
	v_cvt_pk_bf16_f32 v55, v50, v51
	global_store_dwordx4 v[8:9], v[52:55], off
	v_lshl_add_u64 v[8:9], v[8:9], 0, s[6:7]
	s_waitcnt vmcnt(15)
	v_lshlrev_b32_e32 v36, 16, v64
	v_and_b32_e32 v37, 0xffff0000, v64
	v_lshlrev_b32_e32 v38, 16, v65
	v_and_b32_e32 v39, 0xffff0000, v65
	v_lshlrev_b32_e32 v40, 16, v66
	v_and_b32_e32 v41, 0xffff0000, v66
	v_lshlrev_b32_e32 v42, 16, v67
	v_and_b32_e32 v43, 0xffff0000, v67
	v_cndmask_b32_e64 v36, 0, v36, s[2:3]
	v_cndmask_b32_e64 v37, 0, v37, s[2:3]
	v_cndmask_b32_e64 v38, 0, v38, s[2:3]
	v_cndmask_b32_e64 v39, 0, v39, s[2:3]
	v_cndmask_b32_e64 v40, 0, v40, s[2:3]
	v_cndmask_b32_e64 v41, 0, v41, s[2:3]
	v_cndmask_b32_e64 v42, 0, v42, s[2:3]
	v_cndmask_b32_e64 v43, 0, v43, s[2:3]
	v_sub_f32_e32 v20, v20, v36
	v_sub_f32_e32 v21, v21, v37
	v_sub_f32_e32 v22, v22, v38
	v_sub_f32_e32 v23, v23, v39
	v_sub_f32_e32 v24, v24, v40
	v_sub_f32_e32 v25, v25, v41
	v_sub_f32_e32 v26, v26, v42
	v_sub_f32_e32 v27, v27, v43
	v_lshlrev_b32_e32 v28, 16, v144
	v_and_b32_e32 v29, 0xffff0000, v144
	v_lshlrev_b32_e32 v30, 16, v145
	v_and_b32_e32 v31, 0xffff0000, v145
	v_lshlrev_b32_e32 v32, 16, v146
	v_and_b32_e32 v33, 0xffff0000, v146
	v_lshlrev_b32_e32 v34, 16, v147
	v_and_b32_e32 v35, 0xffff0000, v147
	v_add_f32_e32 v20, v20, v28
	v_add_f32_e32 v21, v21, v29
	v_add_f32_e32 v22, v22, v30
	v_add_f32_e32 v23, v23, v31
	v_add_f32_e32 v24, v24, v32
	v_add_f32_e32 v25, v25, v33
	v_add_f32_e32 v26, v26, v34
	v_add_f32_e32 v27, v27, v35
	v_mov_b32_e32 v56, 0x3e124925
	v_mov_b32_e32 v57, 0x3e000000
	v_cndmask_b32_e64 v56, v56, v57, s[2:3]
	s_nop 0
	v_fma_f32 v44, v56, v20, -v28
	v_fma_f32 v45, v56, v21, -v29
	v_fma_f32 v46, v56, v22, -v30
	v_fma_f32 v47, v56, v23, -v31
	v_fma_f32 v48, v56, v24, -v32
	v_fma_f32 v49, v56, v25, -v33
	v_fma_f32 v50, v56, v26, -v34
	v_fma_f32 v51, v56, v27, -v35
	v_cvt_pk_bf16_f32 v52, v44, v45
	v_cvt_pk_bf16_f32 v53, v46, v47
	v_cvt_pk_bf16_f32 v54, v48, v49
	v_cvt_pk_bf16_f32 v55, v50, v51
	global_store_dwordx4 v[8:9], v[52:55], off
	v_lshl_add_u64 v[8:9], v[8:9], 0, s[6:7]
	s_waitcnt vmcnt(15)
	v_lshlrev_b32_e32 v36, 16, v60
	v_and_b32_e32 v37, 0xffff0000, v60
	v_lshlrev_b32_e32 v38, 16, v61
	v_and_b32_e32 v39, 0xffff0000, v61
	v_lshlrev_b32_e32 v40, 16, v62
	v_and_b32_e32 v41, 0xffff0000, v62
	v_lshlrev_b32_e32 v42, 16, v63
	v_and_b32_e32 v43, 0xffff0000, v63
	v_cndmask_b32_e64 v36, 0, v36, s[2:3]
	v_cndmask_b32_e64 v37, 0, v37, s[2:3]
	v_cndmask_b32_e64 v38, 0, v38, s[2:3]
	v_cndmask_b32_e64 v39, 0, v39, s[2:3]
	v_cndmask_b32_e64 v40, 0, v40, s[2:3]
	v_cndmask_b32_e64 v41, 0, v41, s[2:3]
	v_cndmask_b32_e64 v42, 0, v42, s[2:3]
	v_cndmask_b32_e64 v43, 0, v43, s[2:3]
	v_sub_f32_e32 v20, v20, v36
	v_sub_f32_e32 v21, v21, v37
	v_sub_f32_e32 v22, v22, v38
	v_sub_f32_e32 v23, v23, v39
	v_sub_f32_e32 v24, v24, v40
	v_sub_f32_e32 v25, v25, v41
	v_sub_f32_e32 v26, v26, v42
	v_sub_f32_e32 v27, v27, v43
	v_lshlrev_b32_e32 v28, 16, v148
	v_and_b32_e32 v29, 0xffff0000, v148
	v_lshlrev_b32_e32 v30, 16, v149
	v_and_b32_e32 v31, 0xffff0000, v149
	v_lshlrev_b32_e32 v32, 16, v150
	v_and_b32_e32 v33, 0xffff0000, v150
	v_lshlrev_b32_e32 v34, 16, v151
	v_and_b32_e32 v35, 0xffff0000, v151
	v_add_f32_e32 v20, v20, v28
	v_add_f32_e32 v21, v21, v29
	v_add_f32_e32 v22, v22, v30
	v_add_f32_e32 v23, v23, v31
	v_add_f32_e32 v24, v24, v32
	v_add_f32_e32 v25, v25, v33
	v_add_f32_e32 v26, v26, v34
	v_add_f32_e32 v27, v27, v35
	v_mov_b32_e32 v56, 0x3e000000
	s_nop 0
	v_fma_f32 v44, v56, v20, -v28
	v_fma_f32 v45, v56, v21, -v29
	v_fma_f32 v46, v56, v22, -v30
	v_fma_f32 v47, v56, v23, -v31
	v_fma_f32 v48, v56, v24, -v32
	v_fma_f32 v49, v56, v25, -v33
	v_fma_f32 v50, v56, v26, -v34
	v_fma_f32 v51, v56, v27, -v35
	v_cvt_pk_bf16_f32 v52, v44, v45
	v_cvt_pk_bf16_f32 v53, v46, v47
	v_cvt_pk_bf16_f32 v54, v48, v49
	v_cvt_pk_bf16_f32 v55, v50, v51
	global_store_dwordx4 v[8:9], v[52:55], off
	v_lshl_add_u64 v[8:9], v[8:9], 0, s[6:7]
	s_waitcnt vmcnt(15)
; __device__ __forceinline__ void phase_pool(const bf16_t* proj, bf16_t* pooled) {
;     ...
;         for (int r = 0; r < 16; ++r) {
;             float f[8]; unpack8(*(const u32x4*)(src + (ptrdiff_t)r * PP), f);
;             const int pos = pos0 + r;
;             if (r >= 1 && pos - w >= 0) { float o[8]; unpack8(*(const u32x4*)(src + (ptrdiff_t)(r - w) * PP), o);
; #pragma unroll
;                 for (int e = 0; e < 8; ++e) sum[e] -= o[e]; }
;             const float rc = 1.0f / (float)(pos + 1 < w ? pos + 1 : w);
;             float out[8];
; #pragma unroll
;             for (int e = 0; e < 8; ++e) { sum[e] += f[e]; out[e] = sum[e] * rc - f[e]; }
;             *(u32x4*)(pooled + (size_t)(r0 + r) * DM + cgi * 8) = pack8(out);
	v_lshlrev_b32_e32 v36, 16, v120
	v_and_b32_e32 v37, 0xffff0000, v120
	v_lshlrev_b32_e32 v38, 16, v121
	v_and_b32_e32 v39, 0xffff0000, v121
	v_lshlrev_b32_e32 v40, 16, v122
	v_and_b32_e32 v41, 0xffff0000, v122
	v_lshlrev_b32_e32 v42, 16, v123
	v_and_b32_e32 v43, 0xffff0000, v123
	v_sub_f32_e32 v20, v20, v36
	v_sub_f32_e32 v21, v21, v37
	v_sub_f32_e32 v22, v22, v38
	v_sub_f32_e32 v23, v23, v39
	v_sub_f32_e32 v24, v24, v40
	v_sub_f32_e32 v25, v25, v41
	v_sub_f32_e32 v26, v26, v42
	v_sub_f32_e32 v27, v27, v43
	v_lshlrev_b32_e32 v28, 16, v152
	v_and_b32_e32 v29, 0xffff0000, v152
	v_lshlrev_b32_e32 v30, 16, v153
	v_and_b32_e32 v31, 0xffff0000, v153
	v_lshlrev_b32_e32 v32, 16, v154
	v_and_b32_e32 v33, 0xffff0000, v154
	v_lshlrev_b32_e32 v34, 16, v155
	v_and_b32_e32 v35, 0xffff0000, v155
	v_add_f32_e32 v20, v20, v28
	v_add_f32_e32 v21, v21, v29
	v_add_f32_e32 v22, v22, v30
	v_add_f32_e32 v23, v23, v31
	v_add_f32_e32 v24, v24, v32
	v_add_f32_e32 v25, v25, v33
	v_add_f32_e32 v26, v26, v34
	v_add_f32_e32 v27, v27, v35
	v_mov_b32_e32 v56, 0x3e000000
	s_nop 0
	v_fma_f32 v44, v56, v20, -v28
	v_fma_f32 v45, v56, v21, -v29
	v_fma_f32 v46, v56, v22, -v30
	v_fma_f32 v47, v56, v23, -v31
	v_fma_f32 v48, v56, v24, -v32
	v_fma_f32 v49, v56, v25, -v33
	v_fma_f32 v50, v56, v26, -v34
	v_fma_f32 v51, v56, v27, -v35
	v_cvt_pk_bf16_f32 v52, v44, v45
	v_cvt_pk_bf16_f32 v53, v46, v47
	v_cvt_pk_bf16_f32 v54, v48, v49
	v_cvt_pk_bf16_f32 v55, v50, v51
	global_store_dwordx4 v[8:9], v[52:55], off
	v_lshl_add_u64 v[8:9], v[8:9], 0, s[6:7]
	s_waitcnt vmcnt(15)
	v_lshlrev_b32_e32 v36, 16, v124
	v_and_b32_e32 v37, 0xffff0000, v124
	v_lshlrev_b32_e32 v38, 16, v125
	v_and_b32_e32 v39, 0xffff0000, v125
	v_lshlrev_b32_e32 v40, 16, v126
	v_and_b32_e32 v41, 0xffff0000, v126
	v_lshlrev_b32_e32 v42, 16, v127
	v_and_b32_e32 v43, 0xffff0000, v127
	v_sub_f32_e32 v20, v20, v36
	v_sub_f32_e32 v21, v21, v37
	v_sub_f32_e32 v22, v22, v38
	v_sub_f32_e32 v23, v23, v39
	v_sub_f32_e32 v24, v24, v40
	v_sub_f32_e32 v25, v25, v41
	v_sub_f32_e32 v26, v26, v42
	v_sub_f32_e32 v27, v27, v43
	v_lshlrev_b32_e32 v28, 16, v156
	v_and_b32_e32 v29, 0xffff0000, v156
	v_lshlrev_b32_e32 v30, 16, v157
	v_and_b32_e32 v31, 0xffff0000, v157
	v_lshlrev_b32_e32 v32, 16, v158
	v_and_b32_e32 v33, 0xffff0000, v158
	v_lshlrev_b32_e32 v34, 16, v159
	v_and_b32_e32 v35, 0xffff0000, v159
	v_add_f32_e32 v20, v20, v28
	v_add_f32_e32 v21, v21, v29
	v_add_f32_e32 v22, v22, v30
	v_add_f32_e32 v23, v23, v31
	v_add_f32_e32 v24, v24, v32
	v_add_f32_e32 v25, v25, v33
	v_add_f32_e32 v26, v26, v34
	v_add_f32_e32 v27, v27, v35
	v_mov_b32_e32 v56, 0x3e000000
	s_nop 0
	v_fma_f32 v44, v56, v20, -v28
	v_fma_f32 v45, v56, v21, -v29
	v_fma_f32 v46, v56, v22, -v30
	v_fma_f32 v47, v56, v23, -v31
	v_fma_f32 v48, v56, v24, -v32
	v_fma_f32 v49, v56, v25, -v33
	v_fma_f32 v50, v56, v26, -v34
	v_fma_f32 v51, v56, v27, -v35
	v_cvt_pk_bf16_f32 v52, v44, v45
	v_cvt_pk_bf16_f32 v53, v46, v47
	v_cvt_pk_bf16_f32 v54, v48, v49
	v_cvt_pk_bf16_f32 v55, v50, v51
	global_store_dwordx4 v[8:9], v[52:55], off
	v_lshl_add_u64 v[8:9], v[8:9], 0, s[6:7]
	s_waitcnt vmcnt(15)
	v_lshlrev_b32_e32 v36, 16, v128
	v_and_b32_e32 v37, 0xffff0000, v128
	v_lshlrev_b32_e32 v38, 16, v129
	v_and_b32_e32 v39, 0xffff0000, v129
	v_lshlrev_b32_e32 v40, 16, v130
	v_and_b32_e32 v41, 0xffff0000, v130
	v_lshlrev_b32_e32 v42, 16, v131
	v_and_b32_e32 v43, 0xffff0000, v131
	v_sub_f32_e32 v20, v20, v36
	v_sub_f32_e32 v21, v21, v37
	v_sub_f32_e32 v22, v22, v38
	v_sub_f32_e32 v23, v23, v39
	v_sub_f32_e32 v24, v24, v40
	v_sub_f32_e32 v25, v25, v41
	v_sub_f32_e32 v26, v26, v42
	v_sub_f32_e32 v27, v27, v43
	v_lshlrev_b32_e32 v28, 16, v160
	v_and_b32_e32 v29, 0xffff0000, v160
	v_lshlrev_b32_e32 v30, 16, v161
	v_and_b32_e32 v31, 0xffff0000, v161
	v_lshlrev_b32_e32 v32, 16, v162
	v_and_b32_e32 v33, 0xffff0000, v162
	v_lshlrev_b32_e32 v34, 16, v163
	v_and_b32_e32 v35, 0xffff0000, v163
	v_add_f32_e32 v20, v20, v28
	v_add_f32_e32 v21, v21, v29
	v_add_f32_e32 v22, v22, v30
	v_add_f32_e32 v23, v23, v31
	v_add_f32_e32 v24, v24, v32
	v_add_f32_e32 v25, v25, v33
	v_add_f32_e32 v26, v26, v34
	v_add_f32_e32 v27, v27, v35
	v_mov_b32_e32 v56, 0x3e000000
	s_nop 0
	v_fma_f32 v44, v56, v20, -v28
	v_fma_f32 v45, v56, v21, -v29
	v_fma_f32 v46, v56, v22, -v30
	v_fma_f32 v47, v56, v23, -v31
	v_fma_f32 v48, v56, v24, -v32
	v_fma_f32 v49, v56, v25, -v33
	v_fma_f32 v50, v56, v26, -v34
	v_fma_f32 v51, v56, v27, -v35
	v_cvt_pk_bf16_f32 v52, v44, v45
	v_cvt_pk_bf16_f32 v53, v46, v47
	v_cvt_pk_bf16_f32 v54, v48, v49
	v_cvt_pk_bf16_f32 v55, v50, v51
	global_store_dwordx4 v[8:9], v[52:55], off
	v_lshl_add_u64 v[8:9], v[8:9], 0, s[6:7]
	s_waitcnt vmcnt(15)
	v_lshlrev_b32_e32 v36, 16, v132
	v_and_b32_e32 v37, 0xffff0000, v132
	v_lshlrev_b32_e32 v38, 16, v133
	v_and_b32_e32 v39, 0xffff0000, v133
	v_lshlrev_b32_e32 v40, 16, v134
	v_and_b32_e32 v41, 0xffff0000, v134
	v_lshlrev_b32_e32 v42, 16, v135
	v_and_b32_e32 v43, 0xffff0000, v135
	v_sub_f32_e32 v20, v20, v36
	v_sub_f32_e32 v21, v21, v37
	v_sub_f32_e32 v22, v22, v38
	v_sub_f32_e32 v23, v23, v39
	v_sub_f32_e32 v24, v24, v40
	v_sub_f32_e32 v25, v25, v41
	v_sub_f32_e32 v26, v26, v42
	v_sub_f32_e32 v27, v27, v43
	v_lshlrev_b32_e32 v28, 16, v164
	v_and_b32_e32 v29, 0xffff0000, v164
	v_lshlrev_b32_e32 v30, 16, v165
	v_and_b32_e32 v31, 0xffff0000, v165
	v_lshlrev_b32_e32 v32, 16, v166
	v_and_b32_e32 v33, 0xffff0000, v166
	v_lshlrev_b32_e32 v34, 16, v167
	v_and_b32_e32 v35, 0xffff0000, v167
	v_add_f32_e32 v20, v20, v28
	v_add_f32_e32 v21, v21, v29
	v_add_f32_e32 v22, v22, v30
	v_add_f32_e32 v23, v23, v31
	v_add_f32_e32 v24, v24, v32
	v_add_f32_e32 v25, v25, v33
	v_add_f32_e32 v26, v26, v34
	v_add_f32_e32 v27, v27, v35
	v_mov_b32_e32 v56, 0x3e000000
	s_nop 0
	v_fma_f32 v44, v56, v20, -v28
	v_fma_f32 v45, v56, v21, -v29
	v_fma_f32 v46, v56, v22, -v30
	v_fma_f32 v47, v56, v23, -v31
	v_fma_f32 v48, v56, v24, -v32
	v_fma_f32 v49, v56, v25, -v33
	v_fma_f32 v50, v56, v26, -v34
	v_fma_f32 v51, v56, v27, -v35
	v_cvt_pk_bf16_f32 v52, v44, v45
	v_cvt_pk_bf16_f32 v53, v46, v47
	v_cvt_pk_bf16_f32 v54, v48, v49
	v_cvt_pk_bf16_f32 v55, v50, v51
	global_store_dwordx4 v[8:9], v[52:55], off
	v_lshl_add_u64 v[8:9], v[8:9], 0, s[6:7]
	s_waitcnt vmcnt(15)
; __device__ __forceinline__ void phase_pool(const bf16_t* proj, bf16_t* pooled) {
;     ...
;         for (int r = 0; r < 16; ++r) {
;             float f[8]; unpack8(*(const u32x4*)(src + (ptrdiff_t)r * PP), f);
;             const int pos = pos0 + r;
;             if (r >= 1 && pos - w >= 0) { float o[8]; unpack8(*(const u32x4*)(src + (ptrdiff_t)(r - w) * PP), o);
; #pragma unroll
;                 for (int e = 0; e < 8; ++e) sum[e] -= o[e]; }
;             const float rc = 1.0f / (float)(pos + 1 < w ? pos + 1 : w);
;             float out[8];
; #pragma unroll
;             for (int e = 0; e < 8; ++e) { sum[e] += f[e]; out[e] = sum[e] * rc - f[e]; }
;             *(u32x4*)(pooled + (size_t)(r0 + r) * DM + cgi * 8) = pack8(out);
;         }
	v_lshlrev_b32_e32 v36, 16, v136
	v_and_b32_e32 v37, 0xffff0000, v136
	v_lshlrev_b32_e32 v38, 16, v137
	v_and_b32_e32 v39, 0xffff0000, v137
	v_lshlrev_b32_e32 v40, 16, v138
	v_and_b32_e32 v41, 0xffff0000, v138
	v_lshlrev_b32_e32 v42, 16, v139
	v_and_b32_e32 v43, 0xffff0000, v139
	v_sub_f32_e32 v20, v20, v36
	v_sub_f32_e32 v21, v21, v37
	v_sub_f32_e32 v22, v22, v38
	v_sub_f32_e32 v23, v23, v39
	v_sub_f32_e32 v24, v24, v40
	v_sub_f32_e32 v25, v25, v41
	v_sub_f32_e32 v26, v26, v42
	v_sub_f32_e32 v27, v27, v43
	v_lshlrev_b32_e32 v28, 16, v168
	v_and_b32_e32 v29, 0xffff0000, v168
	v_lshlrev_b32_e32 v30, 16, v169
	v_and_b32_e32 v31, 0xffff0000, v169
	v_lshlrev_b32_e32 v32, 16, v170
	v_and_b32_e32 v33, 0xffff0000, v170
	v_lshlrev_b32_e32 v34, 16, v171
	v_and_b32_e32 v35, 0xffff0000, v171
	v_add_f32_e32 v20, v20, v28
	v_add_f32_e32 v21, v21, v29
	v_add_f32_e32 v22, v22, v30
	v_add_f32_e32 v23, v23, v31
	v_add_f32_e32 v24, v24, v32
	v_add_f32_e32 v25, v25, v33
	v_add_f32_e32 v26, v26, v34
	v_add_f32_e32 v27, v27, v35
	v_mov_b32_e32 v56, 0x3e000000
	s_nop 0
	v_fma_f32 v44, v56, v20, -v28
	v_fma_f32 v45, v56, v21, -v29
	v_fma_f32 v46, v56, v22, -v30
	v_fma_f32 v47, v56, v23, -v31
	v_fma_f32 v48, v56, v24, -v32
	v_fma_f32 v49, v56, v25, -v33
	v_fma_f32 v50, v56, v26, -v34
	v_fma_f32 v51, v56, v27, -v35
	v_cvt_pk_bf16_f32 v52, v44, v45
	v_cvt_pk_bf16_f32 v53, v46, v47
	v_cvt_pk_bf16_f32 v54, v48, v49
	v_cvt_pk_bf16_f32 v55, v50, v51
	global_store_dwordx4 v[8:9], v[52:55], off
	v_lshl_add_u64 v[8:9], v[8:9], 0, s[6:7]
	s_waitcnt vmcnt(15)
	v_lshlrev_b32_e32 v36, 16, v140
	v_and_b32_e32 v37, 0xffff0000, v140
	v_lshlrev_b32_e32 v38, 16, v141
	v_and_b32_e32 v39, 0xffff0000, v141
	v_lshlrev_b32_e32 v40, 16, v142
	v_and_b32_e32 v41, 0xffff0000, v142
	v_lshlrev_b32_e32 v42, 16, v143
	v_and_b32_e32 v43, 0xffff0000, v143
	v_sub_f32_e32 v20, v20, v36
	v_sub_f32_e32 v21, v21, v37
	v_sub_f32_e32 v22, v22, v38
	v_sub_f32_e32 v23, v23, v39
	v_sub_f32_e32 v24, v24, v40
	v_sub_f32_e32 v25, v25, v41
	v_sub_f32_e32 v26, v26, v42
	v_sub_f32_e32 v27, v27, v43
	v_lshlrev_b32_e32 v28, 16, v172
	v_and_b32_e32 v29, 0xffff0000, v172
	v_lshlrev_b32_e32 v30, 16, v173
	v_and_b32_e32 v31, 0xffff0000, v173
	v_lshlrev_b32_e32 v32, 16, v174
	v_and_b32_e32 v33, 0xffff0000, v174
	v_lshlrev_b32_e32 v34, 16, v175
	v_and_b32_e32 v35, 0xffff0000, v175
	v_add_f32_e32 v20, v20, v28
	v_add_f32_e32 v21, v21, v29
	v_add_f32_e32 v22, v22, v30
	v_add_f32_e32 v23, v23, v31
	v_add_f32_e32 v24, v24, v32
	v_add_f32_e32 v25, v25, v33
	v_add_f32_e32 v26, v26, v34
	v_add_f32_e32 v27, v27, v35
	v_mov_b32_e32 v56, 0x3e000000
	s_nop 0
	v_fma_f32 v44, v56, v20, -v28
	v_fma_f32 v45, v56, v21, -v29
	v_fma_f32 v46, v56, v22, -v30
	v_fma_f32 v47, v56, v23, -v31
	v_fma_f32 v48, v56, v24, -v32
	v_fma_f32 v49, v56, v25, -v33
	v_fma_f32 v50, v56, v26, -v34
	v_fma_f32 v51, v56, v27, -v35
	v_cvt_pk_bf16_f32 v52, v44, v45
	v_cvt_pk_bf16_f32 v53, v46, v47
	v_cvt_pk_bf16_f32 v54, v48, v49
	v_cvt_pk_bf16_f32 v55, v50, v51
	global_store_dwordx4 v[8:9], v[52:55], off
	v_lshl_add_u64 v[8:9], v[8:9], 0, s[6:7]
	s_waitcnt vmcnt(15)
	v_lshlrev_b32_e32 v36, 16, v144
	v_and_b32_e32 v37, 0xffff0000, v144
	v_lshlrev_b32_e32 v38, 16, v145
	v_and_b32_e32 v39, 0xffff0000, v145
	v_lshlrev_b32_e32 v40, 16, v146
	v_and_b32_e32 v41, 0xffff0000, v146
	v_lshlrev_b32_e32 v42, 16, v147
	v_and_b32_e32 v43, 0xffff0000, v147
	v_sub_f32_e32 v20, v20, v36
	v_sub_f32_e32 v21, v21, v37
	v_sub_f32_e32 v22, v22, v38
	v_sub_f32_e32 v23, v23, v39
	v_sub_f32_e32 v24, v24, v40
	v_sub_f32_e32 v25, v25, v41
	v_sub_f32_e32 v26, v26, v42
	v_sub_f32_e32 v27, v27, v43
	v_lshlrev_b32_e32 v28, 16, v176
	v_and_b32_e32 v29, 0xffff0000, v176
	v_lshlrev_b32_e32 v30, 16, v177
	v_and_b32_e32 v31, 0xffff0000, v177
	v_lshlrev_b32_e32 v32, 16, v178
	v_and_b32_e32 v33, 0xffff0000, v178
	v_lshlrev_b32_e32 v34, 16, v179
	v_and_b32_e32 v35, 0xffff0000, v179
	v_add_f32_e32 v20, v20, v28
	v_add_f32_e32 v21, v21, v29
	v_add_f32_e32 v22, v22, v30
	v_add_f32_e32 v23, v23, v31
	v_add_f32_e32 v24, v24, v32
	v_add_f32_e32 v25, v25, v33
	v_add_f32_e32 v26, v26, v34
	v_add_f32_e32 v27, v27, v35
	v_mov_b32_e32 v56, 0x3e000000
	s_nop 0
	v_fma_f32 v44, v56, v20, -v28
	v_fma_f32 v45, v56, v21, -v29
	v_fma_f32 v46, v56, v22, -v30
	v_fma_f32 v47, v56, v23, -v31
	v_fma_f32 v48, v56, v24, -v32
	v_fma_f32 v49, v56, v25, -v33
	v_fma_f32 v50, v56, v26, -v34
	v_fma_f32 v51, v56, v27, -v35
	v_cvt_pk_bf16_f32 v52, v44, v45
	v_cvt_pk_bf16_f32 v53, v46, v47
	v_cvt_pk_bf16_f32 v54, v48, v49
	v_cvt_pk_bf16_f32 v55, v50, v51
	global_store_dwordx4 v[8:9], v[52:55], off
	v_lshl_add_u64 v[8:9], v[8:9], 0, s[6:7]
	s_waitcnt vmcnt(15)
	v_lshlrev_b32_e32 v36, 16, v148
	v_and_b32_e32 v37, 0xffff0000, v148
	v_lshlrev_b32_e32 v38, 16, v149
	v_and_b32_e32 v39, 0xffff0000, v149
	v_lshlrev_b32_e32 v40, 16, v150
	v_and_b32_e32 v41, 0xffff0000, v150
	v_lshlrev_b32_e32 v42, 16, v151
	v_and_b32_e32 v43, 0xffff0000, v151
	v_sub_f32_e32 v20, v20, v36
	v_sub_f32_e32 v21, v21, v37
	v_sub_f32_e32 v22, v22, v38
	v_sub_f32_e32 v23, v23, v39
	v_sub_f32_e32 v24, v24, v40
	v_sub_f32_e32 v25, v25, v41
	v_sub_f32_e32 v26, v26, v42
	v_sub_f32_e32 v27, v27, v43
	v_lshlrev_b32_e32 v28, 16, v180
	v_and_b32_e32 v29, 0xffff0000, v180
	v_lshlrev_b32_e32 v30, 16, v181
	v_and_b32_e32 v31, 0xffff0000, v181
	v_lshlrev_b32_e32 v32, 16, v182
	v_and_b32_e32 v33, 0xffff0000, v182
	v_lshlrev_b32_e32 v34, 16, v183
	v_and_b32_e32 v35, 0xffff0000, v183
	v_add_f32_e32 v20, v20, v28
	v_add_f32_e32 v21, v21, v29
	v_add_f32_e32 v22, v22, v30
	v_add_f32_e32 v23, v23, v31
	v_add_f32_e32 v24, v24, v32
	v_add_f32_e32 v25, v25, v33
	v_add_f32_e32 v26, v26, v34
	v_add_f32_e32 v27, v27, v35
	v_mov_b32_e32 v56, 0x3e000000
	s_nop 0
	v_fma_f32 v44, v56, v20, -v28
	v_fma_f32 v45, v56, v21, -v29
	v_fma_f32 v46, v56, v22, -v30
	v_fma_f32 v47, v56, v23, -v31
	v_fma_f32 v48, v56, v24, -v32
	v_fma_f32 v49, v56, v25, -v33
	v_fma_f32 v50, v56, v26, -v34
	v_fma_f32 v51, v56, v27, -v35
	v_cvt_pk_bf16_f32 v52, v44, v45
	v_cvt_pk_bf16_f32 v53, v46, v47
	v_cvt_pk_bf16_f32 v54, v48, v49
	v_cvt_pk_bf16_f32 v55, v50, v51
	global_store_dwordx4 v[8:9], v[52:55], off
	s_branch .Lmy_pool_next
; __device__ __forceinline__ void phase_pool(const bf16_t* proj, bf16_t* pooled) {
;     ...
;         const int cgi = idx & 127, seg = idx >> 7, r0 = seg * 16, pos0 = r0 & (SEQ - 1), w = 2 << (cgi >> 5);
;         const bf16_t* src = proj + SEC(C_PU) + (size_t)r0 * PP + cgi * 8;
;         float sum[8];
; #pragma unroll
;         for (int e = 0; e < 8; ++e) sum[e] = 0.f;
;         if (pos0 > 0) for (int j = 1; j < w; ++j) { float f[8]; unpack8(*(const u32x4*)(src - (ptrdiff_t)j * PP), f);
; #pragma unroll
;             for (int e = 0; e < 8; ++e) sum[e] += f[e]; }
;         for (int r = 0; r < 16; ++r) {
;             float f[8]; unpack8(*(const u32x4*)(src + (ptrdiff_t)r * PP), f);
;             const int pos = pos0 + r;
;             if (r >= 1 && pos - w >= 0) { float o[8]; unpack8(*(const u32x4*)(src + (ptrdiff_t)(r - w) * PP), o);
; #pragma unroll
;                 for (int e = 0; e < 8; ++e) sum[e] -= o[e]; }
;             const float rc = 1.0f / (float)(pos + 1 < w ? pos + 1 : w);
;             float out[8];
; #pragma unroll
;             for (int e = 0; e < 8; ++e) { sum[e] += f[e]; out[e] = sum[e] * rc - f[e]; }
;             *(u32x4*)(pooled + (size_t)(r0 + r) * DM + cgi * 8) = pack8(out);
.Lmy_pool_w4:
	v_lshl_add_u64 v[10:11], v[6:7], 0, s[8:9]
	global_load_dwordx4 v[60:63], v[10:11], off
	v_lshl_add_u64 v[10:11], v[10:11], 0, s[8:9]
	global_load_dwordx4 v[64:67], v[10:11], off
	v_lshl_add_u64 v[10:11], v[10:11], 0, s[8:9]
	global_load_dwordx4 v[68:71], v[10:11], off
	v_mov_b32_e32 v10, v6
	v_mov_b32_e32 v11, v7
	global_load_dwordx4 v[120:123], v[10:11], off
	v_lshl_add_u64 v[10:11], v[10:11], 0, s[6:7]
	global_load_dwordx4 v[124:127], v[10:11], off
	v_lshl_add_u64 v[10:11], v[10:11], 0, s[6:7]
	global_load_dwordx4 v[128:131], v[10:11], off
	v_lshl_add_u64 v[10:11], v[10:11], 0, s[6:7]
	global_load_dwordx4 v[132:135], v[10:11], off
	v_lshl_add_u64 v[10:11], v[10:11], 0, s[6:7]
	global_load_dwordx4 v[136:139], v[10:11], off
	v_lshl_add_u64 v[10:11], v[10:11], 0, s[6:7]
	global_load_dwordx4 v[140:143], v[10:11], off
	v_lshl_add_u64 v[10:11], v[10:11], 0, s[6:7]
	global_load_dwordx4 v[144:147], v[10:11], off
	v_lshl_add_u64 v[10:11], v[10:11], 0, s[6:7]
	global_load_dwordx4 v[148:151], v[10:11], off
	v_lshl_add_u64 v[10:11], v[10:11], 0, s[6:7]
	global_load_dwordx4 v[152:155], v[10:11], off
	v_lshl_add_u64 v[10:11], v[10:11], 0, s[6:7]
	global_load_dwordx4 v[156:159], v[10:11], off
	v_lshl_add_u64 v[10:11], v[10:11], 0, s[6:7]
	global_load_dwordx4 v[160:163], v[10:11], off
	v_lshl_add_u64 v[10:11], v[10:11], 0, s[6:7]
	global_load_dwordx4 v[164:167], v[10:11], off
	v_lshl_add_u64 v[10:11], v[10:11], 0, s[6:7]
	global_load_dwordx4 v[168:171], v[10:11], off
	v_lshl_add_u64 v[10:11], v[10:11], 0, s[6:7]
	global_load_dwordx4 v[172:175], v[10:11], off
	v_lshl_add_u64 v[10:11], v[10:11], 0, s[6:7]
	global_load_dwordx4 v[176:179], v[10:11], off
	v_lshl_add_u64 v[10:11], v[10:11], 0, s[6:7]
	global_load_dwordx4 v[180:183], v[10:11], off
	v_mov_b32_e32 v20, 0
	v_mov_b32_e32 v21, 0
	v_mov_b32_e32 v22, 0
	v_mov_b32_e32 v23, 0
	v_mov_b32_e32 v24, 0
	v_mov_b32_e32 v25, 0
	v_mov_b32_e32 v26, 0
	v_mov_b32_e32 v27, 0
	s_waitcnt vmcnt(18)
	v_lshlrev_b32_e32 v28, 16, v60
	v_and_b32_e32 v29, 0xffff0000, v60
	v_lshlrev_b32_e32 v30, 16, v61
	v_and_b32_e32 v31, 0xffff0000, v61
	v_lshlrev_b32_e32 v32, 16, v62
	v_and_b32_e32 v33, 0xffff0000, v62
	v_lshlrev_b32_e32 v34, 16, v63
	v_and_b32_e32 v35, 0xffff0000, v63
	v_cndmask_b32_e64 v28, 0, v28, s[2:3]
	v_cndmask_b32_e64 v29, 0, v29, s[2:3]
	v_cndmask_b32_e64 v30, 0, v30, s[2:3]
	v_cndmask_b32_e64 v31, 0, v31, s[2:3]
	v_cndmask_b32_e64 v32, 0, v32, s[2:3]
	v_cndmask_b32_e64 v33, 0, v33, s[2:3]
	v_cndmask_b32_e64 v34, 0, v34, s[2:3]
	v_cndmask_b32_e64 v35, 0, v35, s[2:3]
	v_add_f32_e32 v20, v20, v28
	v_add_f32_e32 v21, v21, v29
	v_add_f32_e32 v22, v22, v30
	v_add_f32_e32 v23, v23, v31
	v_add_f32_e32 v24, v24, v32
	v_add_f32_e32 v25, v25, v33
	v_add_f32_e32 v26, v26, v34
	v_add_f32_e32 v27, v27, v35
	s_waitcnt vmcnt(17)
	v_lshlrev_b32_e32 v28, 16, v64
	v_and_b32_e32 v29, 0xffff0000, v64
	v_lshlrev_b32_e32 v30, 16, v65
	v_and_b32_e32 v31, 0xffff0000, v65
	v_lshlrev_b32_e32 v32, 16, v66
	v_and_b32_e32 v33, 0xffff0000, v66
	v_lshlrev_b32_e32 v34, 16, v67
	v_and_b32_e32 v35, 0xffff0000, v67
	v_cndmask_b32_e64 v28, 0, v28, s[2:3]
	v_cndmask_b32_e64 v29, 0, v29, s[2:3]
	v_cndmask_b32_e64 v30, 0, v30, s[2:3]
	v_cndmask_b32_e64 v31, 0, v31, s[2:3]
	v_cndmask_b32_e64 v32, 0, v32, s[2:3]
	v_cndmask_b32_e64 v33, 0, v33, s[2:3]
	v_cndmask_b32_e64 v34, 0, v34, s[2:3]
	v_cndmask_b32_e64 v35, 0, v35, s[2:3]
	v_add_f32_e32 v20, v20, v28
	v_add_f32_e32 v21, v21, v29
	v_add_f32_e32 v22, v22, v30
	v_add_f32_e32 v23, v23, v31
	v_add_f32_e32 v24, v24, v32
	v_add_f32_e32 v25, v25, v33
	v_add_f32_e32 v26, v26, v34
	v_add_f32_e32 v27, v27, v35
	s_waitcnt vmcnt(16)
	v_lshlrev_b32_e32 v28, 16, v68
	v_and_b32_e32 v29, 0xffff0000, v68
	v_lshlrev_b32_e32 v30, 16, v69
	v_and_b32_e32 v31, 0xffff0000, v69
	v_lshlrev_b32_e32 v32, 16, v70
	v_and_b32_e32 v33, 0xffff0000, v70
	v_lshlrev_b32_e32 v34, 16, v71
	v_and_b32_e32 v35, 0xffff0000, v71
	v_cndmask_b32_e64 v28, 0, v28, s[2:3]
	v_cndmask_b32_e64 v29, 0, v29, s[2:3]
	v_cndmask_b32_e64 v30, 0, v30, s[2:3]
	v_cndmask_b32_e64 v31, 0, v31, s[2:3]
	v_cndmask_b32_e64 v32, 0, v32, s[2:3]
	v_cndmask_b32_e64 v33, 0, v33, s[2:3]
	v_cndmask_b32_e64 v34, 0, v34, s[2:3]
	v_cndmask_b32_e64 v35, 0, v35, s[2:3]
	v_add_f32_e32 v20, v20, v28
	v_add_f32_e32 v21, v21, v29
	v_add_f32_e32 v22, v22, v30
	v_add_f32_e32 v23, v23, v31
	v_add_f32_e32 v24, v24, v32
	v_add_f32_e32 v25, v25, v33
	v_add_f32_e32 v26, v26, v34
	v_add_f32_e32 v27, v27, v35
	s_waitcnt vmcnt(15)
	v_lshlrev_b32_e32 v28, 16, v120
	v_and_b32_e32 v29, 0xffff0000, v120
	v_lshlrev_b32_e32 v30, 16, v121
	v_and_b32_e32 v31, 0xffff0000, v121
	v_lshlrev_b32_e32 v32, 16, v122
	v_and_b32_e32 v33, 0xffff0000, v122
	v_lshlrev_b32_e32 v34, 16, v123
	v_and_b32_e32 v35, 0xffff0000, v123
	v_add_f32_e32 v20, v20, v28
	v_add_f32_e32 v21, v21, v29
	v_add_f32_e32 v22, v22, v30
	v_add_f32_e32 v23, v23, v31
	v_add_f32_e32 v24, v24, v32
	v_add_f32_e32 v25, v25, v33
	v_add_f32_e32 v26, v26, v34
	v_add_f32_e32 v27, v27, v35
	v_mov_b32_e32 v56, 0x3f800000
	v_mov_b32_e32 v57, 0x3e800000
	v_cndmask_b32_e64 v56, v56, v57, s[2:3]
	s_nop 0
	v_fma_f32 v44, v56, v20, -v28
	v_fma_f32 v45, v56, v21, -v29
	v_fma_f32 v46, v56, v22, -v30
	v_fma_f32 v47, v56, v23, -v31
	v_fma_f32 v48, v56, v24, -v32
	v_fma_f32 v49, v56, v25, -v33
	v_fma_f32 v50, v56, v26, -v34
	v_fma_f32 v51, v56, v27, -v35
	v_cvt_pk_bf16_f32 v52, v44, v45
	v_cvt_pk_bf16_f32 v53, v46, v47
	v_cvt_pk_bf16_f32 v54, v48, v49
	v_cvt_pk_bf16_f32 v55, v50, v51
	global_store_dwordx4 v[8:9], v[52:55], off
	v_lshl_add_u64 v[8:9], v[8:9], 0, s[6:7]
	s_waitcnt vmcnt(15)
; __device__ __forceinline__ void phase_pool(const bf16_t* proj, bf16_t* pooled) {
;     ...
;         for (int r = 0; r < 16; ++r) {
;             float f[8]; unpack8(*(const u32x4*)(src + (ptrdiff_t)r * PP), f);
;             const int pos = pos0 + r;
;             if (r >= 1 && pos - w >= 0) { float o[8]; unpack8(*(const u32x4*)(src + (ptrdiff_t)(r - w) * PP), o);
; #pragma unroll
;                 for (int e = 0; e < 8; ++e) sum[e] -= o[e]; }
;             const float rc = 1.0f / (float)(pos + 1 < w ? pos + 1 : w);
;             float out[8];
; #pragma unroll
;             for (int e = 0; e < 8; ++e) { sum[e] += f[e]; out[e] = sum[e] * rc - f[e]; }
;             *(u32x4*)(pooled + (size_t)(r0 + r) * DM + cgi * 8) = pack8(out);
	v_lshlrev_b32_e32 v36, 16, v68
	v_and_b32_e32 v37, 0xffff0000, v68
	v_lshlrev_b32_e32 v38, 16, v69
	v_and_b32_e32 v39, 0xffff0000, v69
	v_lshlrev_b32_e32 v40, 16, v70
	v_and_b32_e32 v41, 0xffff0000, v70
	v_lshlrev_b32_e32 v42, 16, v71
	v_and_b32_e32 v43, 0xffff0000, v71
	v_cndmask_b32_e64 v36, 0, v36, s[2:3]
	v_cndmask_b32_e64 v37, 0, v37, s[2:3]
	v_cndmask_b32_e64 v38, 0, v38, s[2:3]
	v_cndmask_b32_e64 v39, 0, v39, s[2:3]
	v_cndmask_b32_e64 v40, 0, v40, s[2:3]
	v_cndmask_b32_e64 v41, 0, v41, s[2:3]
	v_cndmask_b32_e64 v42, 0, v42, s[2:3]
	v_cndmask_b32_e64 v43, 0, v43, s[2:3]
	v_sub_f32_e32 v20, v20, v36
	v_sub_f32_e32 v21, v21, v37
	v_sub_f32_e32 v22, v22, v38
	v_sub_f32_e32 v23, v23, v39
	v_sub_f32_e32 v24, v24, v40
	v_sub_f32_e32 v25, v25, v41
	v_sub_f32_e32 v26, v26, v42
	v_sub_f32_e32 v27, v27, v43
	v_lshlrev_b32_e32 v28, 16, v124
	v_and_b32_e32 v29, 0xffff0000, v124
	v_lshlrev_b32_e32 v30, 16, v125
	v_and_b32_e32 v31, 0xffff0000, v125
	v_lshlrev_b32_e32 v32, 16, v126
	v_and_b32_e32 v33, 0xffff0000, v126
	v_lshlrev_b32_e32 v34, 16, v127
	v_and_b32_e32 v35, 0xffff0000, v127
	v_add_f32_e32 v20, v20, v28
	v_add_f32_e32 v21, v21, v29
	v_add_f32_e32 v22, v22, v30
	v_add_f32_e32 v23, v23, v31
	v_add_f32_e32 v24, v24, v32
	v_add_f32_e32 v25, v25, v33
	v_add_f32_e32 v26, v26, v34
	v_add_f32_e32 v27, v27, v35
	v_mov_b32_e32 v56, 0x3f000000
	v_mov_b32_e32 v57, 0x3e800000
	v_cndmask_b32_e64 v56, v56, v57, s[2:3]
	s_nop 0
	v_fma_f32 v44, v56, v20, -v28
	v_fma_f32 v45, v56, v21, -v29
	v_fma_f32 v46, v56, v22, -v30
	v_fma_f32 v47, v56, v23, -v31
	v_fma_f32 v48, v56, v24, -v32
	v_fma_f32 v49, v56, v25, -v33
	v_fma_f32 v50, v56, v26, -v34
	v_fma_f32 v51, v56, v27, -v35
	v_cvt_pk_bf16_f32 v52, v44, v45
	v_cvt_pk_bf16_f32 v53, v46, v47
	v_cvt_pk_bf16_f32 v54, v48, v49
	v_cvt_pk_bf16_f32 v55, v50, v51
	global_store_dwordx4 v[8:9], v[52:55], off
	v_lshl_add_u64 v[8:9], v[8:9], 0, s[6:7]
	s_waitcnt vmcnt(15)
	v_lshlrev_b32_e32 v36, 16, v64
	v_and_b32_e32 v37, 0xffff0000, v64
	v_lshlrev_b32_e32 v38, 16, v65
	v_and_b32_e32 v39, 0xffff0000, v65
	v_lshlrev_b32_e32 v40, 16, v66
	v_and_b32_e32 v41, 0xffff0000, v66
	v_lshlrev_b32_e32 v42, 16, v67
	v_and_b32_e32 v43, 0xffff0000, v67
	v_cndmask_b32_e64 v36, 0, v36, s[2:3]
	v_cndmask_b32_e64 v37, 0, v37, s[2:3]
	v_cndmask_b32_e64 v38, 0, v38, s[2:3]
	v_cndmask_b32_e64 v39, 0, v39, s[2:3]
	v_cndmask_b32_e64 v40, 0, v40, s[2:3]
	v_cndmask_b32_e64 v41, 0, v41, s[2:3]
	v_cndmask_b32_e64 v42, 0, v42, s[2:3]
	v_cndmask_b32_e64 v43, 0, v43, s[2:3]
	v_sub_f32_e32 v20, v20, v36
	v_sub_f32_e32 v21, v21, v37
	v_sub_f32_e32 v22, v22, v38
	v_sub_f32_e32 v23, v23, v39
	v_sub_f32_e32 v24, v24, v40
	v_sub_f32_e32 v25, v25, v41
	v_sub_f32_e32 v26, v26, v42
	v_sub_f32_e32 v27, v27, v43
	v_lshlrev_b32_e32 v28, 16, v128
	v_and_b32_e32 v29, 0xffff0000, v128
	v_lshlrev_b32_e32 v30, 16, v129
	v_and_b32_e32 v31, 0xffff0000, v129
	v_lshlrev_b32_e32 v32, 16, v130
	v_and_b32_e32 v33, 0xffff0000, v130
	v_lshlrev_b32_e32 v34, 16, v131
	v_and_b32_e32 v35, 0xffff0000, v131
	v_add_f32_e32 v20, v20, v28
	v_add_f32_e32 v21, v21, v29
	v_add_f32_e32 v22, v22, v30
	v_add_f32_e32 v23, v23, v31
	v_add_f32_e32 v24, v24, v32
	v_add_f32_e32 v25, v25, v33
	v_add_f32_e32 v26, v26, v34
	v_add_f32_e32 v27, v27, v35
	v_mov_b32_e32 v56, 0x3eaaaaab
	v_mov_b32_e32 v57, 0x3e800000
	v_cndmask_b32_e64 v56, v56, v57, s[2:3]
	s_nop 0
	v_fma_f32 v44, v56, v20, -v28
	v_fma_f32 v45, v56, v21, -v29
	v_fma_f32 v46, v56, v22, -v30
	v_fma_f32 v47, v56, v23, -v31
	v_fma_f32 v48, v56, v24, -v32
	v_fma_f32 v49, v56, v25, -v33
	v_fma_f32 v50, v56, v26, -v34
	v_fma_f32 v51, v56, v27, -v35
	v_cvt_pk_bf16_f32 v52, v44, v45
	v_cvt_pk_bf16_f32 v53, v46, v47
	v_cvt_pk_bf16_f32 v54, v48, v49
	v_cvt_pk_bf16_f32 v55, v50, v51
	global_store_dwordx4 v[8:9], v[52:55], off
	v_lshl_add_u64 v[8:9], v[8:9], 0, s[6:7]
	s_waitcnt vmcnt(15)
	v_lshlrev_b32_e32 v36, 16, v60
	v_and_b32_e32 v37, 0xffff0000, v60
	v_lshlrev_b32_e32 v38, 16, v61
	v_and_b32_e32 v39, 0xffff0000, v61
	v_lshlrev_b32_e32 v40, 16, v62
	v_and_b32_e32 v41, 0xffff0000, v62
	v_lshlrev_b32_e32 v42, 16, v63
	v_and_b32_e32 v43, 0xffff0000, v63
	v_cndmask_b32_e64 v36, 0, v36, s[2:3]
	v_cndmask_b32_e64 v37, 0, v37, s[2:3]
	v_cndmask_b32_e64 v38, 0, v38, s[2:3]
	v_cndmask_b32_e64 v39, 0, v39, s[2:3]
	v_cndmask_b32_e64 v40, 0, v40, s[2:3]
	v_cndmask_b32_e64 v41, 0, v41, s[2:3]
	v_cndmask_b32_e64 v42, 0, v42, s[2:3]
	v_cndmask_b32_e64 v43, 0, v43, s[2:3]
	v_sub_f32_e32 v20, v20, v36
	v_sub_f32_e32 v21, v21, v37
	v_sub_f32_e32 v22, v22, v38
	v_sub_f32_e32 v23, v23, v39
	v_sub_f32_e32 v24, v24, v40
	v_sub_f32_e32 v25, v25, v41
	v_sub_f32_e32 v26, v26, v42
	v_sub_f32_e32 v27, v27, v43
	v_lshlrev_b32_e32 v28, 16, v132
	v_and_b32_e32 v29, 0xffff0000, v132
	v_lshlrev_b32_e32 v30, 16, v133
	v_and_b32_e32 v31, 0xffff0000, v133
	v_lshlrev_b32_e32 v32, 16, v134
	v_and_b32_e32 v33, 0xffff0000, v134
	v_lshlrev_b32_e32 v34, 16, v135
	v_and_b32_e32 v35, 0xffff0000, v135
	v_add_f32_e32 v20, v20, v28
	v_add_f32_e32 v21, v21, v29
	v_add_f32_e32 v22, v22, v30
	v_add_f32_e32 v23, v23, v31
	v_add_f32_e32 v24, v24, v32
	v_add_f32_e32 v25, v25, v33
	v_add_f32_e32 v26, v26, v34
	v_add_f32_e32 v27, v27, v35
	v_mov_b32_e32 v56, 0x3e800000
	s_nop 0
	v_fma_f32 v44, v56, v20, -v28
	v_fma_f32 v45, v56, v21, -v29
	v_fma_f32 v46, v56, v22, -v30
	v_fma_f32 v47, v56, v23, -v31
	v_fma_f32 v48, v56, v24, -v32
	v_fma_f32 v49, v56, v25, -v33
	v_fma_f32 v50, v56, v26, -v34
	v_fma_f32 v51, v56, v27, -v35
	v_cvt_pk_bf16_f32 v52, v44, v45
	v_cvt_pk_bf16_f32 v53, v46, v47
	v_cvt_pk_bf16_f32 v54, v48, v49
	v_cvt_pk_bf16_f32 v55, v50, v51
	global_store_dwordx4 v[8:9], v[52:55], off
	v_lshl_add_u64 v[8:9], v[8:9], 0, s[6:7]
	s_waitcnt vmcnt(15)
; __device__ __forceinline__ void phase_pool(const bf16_t* proj, bf16_t* pooled) {
;     ...
;         for (int r = 0; r < 16; ++r) {
;             float f[8]; unpack8(*(const u32x4*)(src + (ptrdiff_t)r * PP), f);
;             const int pos = pos0 + r;
;             if (r >= 1 && pos - w >= 0) { float o[8]; unpack8(*(const u32x4*)(src + (ptrdiff_t)(r - w) * PP), o);
; #pragma unroll
;                 for (int e = 0; e < 8; ++e) sum[e] -= o[e]; }
;             const float rc = 1.0f / (float)(pos + 1 < w ? pos + 1 : w);
;             float out[8];
; #pragma unroll
;             for (int e = 0; e < 8; ++e) { sum[e] += f[e]; out[e] = sum[e] * rc - f[e]; }
;             *(u32x4*)(pooled + (size_t)(r0 + r) * DM + cgi * 8) = pack8(out);
	v_lshlrev_b32_e32 v36, 16, v120
	v_and_b32_e32 v37, 0xffff0000, v120
	v_lshlrev_b32_e32 v38, 16, v121
	v_and_b32_e32 v39, 0xffff0000, v121
	v_lshlrev_b32_e32 v40, 16, v122
	v_and_b32_e32 v41, 0xffff0000, v122
	v_lshlrev_b32_e32 v42, 16, v123
	v_and_b32_e32 v43, 0xffff0000, v123
	v_sub_f32_e32 v20, v20, v36
	v_sub_f32_e32 v21, v21, v37
	v_sub_f32_e32 v22, v22, v38
	v_sub_f32_e32 v23, v23, v39
	v_sub_f32_e32 v24, v24, v40
	v_sub_f32_e32 v25, v25, v41
	v_sub_f32_e32 v26, v26, v42
	v_sub_f32_e32 v27, v27, v43
	v_lshlrev_b32_e32 v28, 16, v136
	v_and_b32_e32 v29, 0xffff0000, v136
	v_lshlrev_b32_e32 v30, 16, v137
	v_and_b32_e32 v31, 0xffff0000, v137
	v_lshlrev_b32_e32 v32, 16, v138
	v_and_b32_e32 v33, 0xffff0000, v138
	v_lshlrev_b32_e32 v34, 16, v139
	v_and_b32_e32 v35, 0xffff0000, v139
	v_add_f32_e32 v20, v20, v28
	v_add_f32_e32 v21, v21, v29
	v_add_f32_e32 v22, v22, v30
	v_add_f32_e32 v23, v23, v31
	v_add_f32_e32 v24, v24, v32
	v_add_f32_e32 v25, v25, v33
	v_add_f32_e32 v26, v26, v34
	v_add_f32_e32 v27, v27, v35
	v_mov_b32_e32 v56, 0x3e800000
	s_nop 0
	v_fma_f32 v44, v56, v20, -v28
	v_fma_f32 v45, v56, v21, -v29
	v_fma_f32 v46, v56, v22, -v30
	v_fma_f32 v47, v56, v23, -v31
	v_fma_f32 v48, v56, v24, -v32
	v_fma_f32 v49, v56, v25, -v33
	v_fma_f32 v50, v56, v26, -v34
	v_fma_f32 v51, v56, v27, -v35
	v_cvt_pk_bf16_f32 v52, v44, v45
	v_cvt_pk_bf16_f32 v53, v46, v47
	v_cvt_pk_bf16_f32 v54, v48, v49
	v_cvt_pk_bf16_f32 v55, v50, v51
	global_store_dwordx4 v[8:9], v[52:55], off
	v_lshl_add_u64 v[8:9], v[8:9], 0, s[6:7]
	s_waitcnt vmcnt(15)
	v_lshlrev_b32_e32 v36, 16, v124
	v_and_b32_e32 v37, 0xffff0000, v124
	v_lshlrev_b32_e32 v38, 16, v125
	v_and_b32_e32 v39, 0xffff0000, v125
	v_lshlrev_b32_e32 v40, 16, v126
	v_and_b32_e32 v41, 0xffff0000, v126
	v_lshlrev_b32_e32 v42, 16, v127
	v_and_b32_e32 v43, 0xffff0000, v127
	v_sub_f32_e32 v20, v20, v36
	v_sub_f32_e32 v21, v21, v37
	v_sub_f32_e32 v22, v22, v38
	v_sub_f32_e32 v23, v23, v39
	v_sub_f32_e32 v24, v24, v40
	v_sub_f32_e32 v25, v25, v41
	v_sub_f32_e32 v26, v26, v42
	v_sub_f32_e32 v27, v27, v43
	v_lshlrev_b32_e32 v28, 16, v140
	v_and_b32_e32 v29, 0xffff0000, v140
	v_lshlrev_b32_e32 v30, 16, v141
	v_and_b32_e32 v31, 0xffff0000, v141
	v_lshlrev_b32_e32 v32, 16, v142
	v_and_b32_e32 v33, 0xffff0000, v142
	v_lshlrev_b32_e32 v34, 16, v143
	v_and_b32_e32 v35, 0xffff0000, v143
	v_add_f32_e32 v20, v20, v28
	v_add_f32_e32 v21, v21, v29
	v_add_f32_e32 v22, v22, v30
	v_add_f32_e32 v23, v23, v31
	v_add_f32_e32 v24, v24, v32
	v_add_f32_e32 v25, v25, v33
	v_add_f32_e32 v26, v26, v34
	v_add_f32_e32 v27, v27, v35
	v_mov_b32_e32 v56, 0x3e800000
	s_nop 0
	v_fma_f32 v44, v56, v20, -v28
	v_fma_f32 v45, v56, v21, -v29
	v_fma_f32 v46, v56, v22, -v30
	v_fma_f32 v47, v56, v23, -v31
	v_fma_f32 v48, v56, v24, -v32
	v_fma_f32 v49, v56, v25, -v33
	v_fma_f32 v50, v56, v26, -v34
	v_fma_f32 v51, v56, v27, -v35
	v_cvt_pk_bf16_f32 v52, v44, v45
	v_cvt_pk_bf16_f32 v53, v46, v47
	v_cvt_pk_bf16_f32 v54, v48, v49
	v_cvt_pk_bf16_f32 v55, v50, v51
	global_store_dwordx4 v[8:9], v[52:55], off
	v_lshl_add_u64 v[8:9], v[8:9], 0, s[6:7]
	s_waitcnt vmcnt(15)
	v_lshlrev_b32_e32 v36, 16, v128
	v_and_b32_e32 v37, 0xffff0000, v128
	v_lshlrev_b32_e32 v38, 16, v129
	v_and_b32_e32 v39, 0xffff0000, v129
	v_lshlrev_b32_e32 v40, 16, v130
	v_and_b32_e32 v41, 0xffff0000, v130
	v_lshlrev_b32_e32 v42, 16, v131
	v_and_b32_e32 v43, 0xffff0000, v131
	v_sub_f32_e32 v20, v20, v36
	v_sub_f32_e32 v21, v21, v37
	v_sub_f32_e32 v22, v22, v38
	v_sub_f32_e32 v23, v23, v39
	v_sub_f32_e32 v24, v24, v40
	v_sub_f32_e32 v25, v25, v41
	v_sub_f32_e32 v26, v26, v42
	v_sub_f32_e32 v27, v27, v43
	v_lshlrev_b32_e32 v28, 16, v144
	v_and_b32_e32 v29, 0xffff0000, v144
	v_lshlrev_b32_e32 v30, 16, v145
	v_and_b32_e32 v31, 0xffff0000, v145
	v_lshlrev_b32_e32 v32, 16, v146
	v_and_b32_e32 v33, 0xffff0000, v146
	v_lshlrev_b32_e32 v34, 16, v147
	v_and_b32_e32 v35, 0xffff0000, v147
	v_add_f32_e32 v20, v20, v28
	v_add_f32_e32 v21, v21, v29
	v_add_f32_e32 v22, v22, v30
	v_add_f32_e32 v23, v23, v31
	v_add_f32_e32 v24, v24, v32
	v_add_f32_e32 v25, v25, v33
	v_add_f32_e32 v26, v26, v34
	v_add_f32_e32 v27, v27, v35
	v_mov_b32_e32 v56, 0x3e800000
	s_nop 0
	v_fma_f32 v44, v56, v20, -v28
	v_fma_f32 v45, v56, v21, -v29
	v_fma_f32 v46, v56, v22, -v30
	v_fma_f32 v47, v56, v23, -v31
	v_fma_f32 v48, v56, v24, -v32
	v_fma_f32 v49, v56, v25, -v33
	v_fma_f32 v50, v56, v26, -v34
	v_fma_f32 v51, v56, v27, -v35
	v_cvt_pk_bf16_f32 v52, v44, v45
	v_cvt_pk_bf16_f32 v53, v46, v47
	v_cvt_pk_bf16_f32 v54, v48, v49
	v_cvt_pk_bf16_f32 v55, v50, v51
	global_store_dwordx4 v[8:9], v[52:55], off
	v_lshl_add_u64 v[8:9], v[8:9], 0, s[6:7]
	s_waitcnt vmcnt(15)
	v_lshlrev_b32_e32 v36, 16, v132
	v_and_b32_e32 v37, 0xffff0000, v132
	v_lshlrev_b32_e32 v38, 16, v133
	v_and_b32_e32 v39, 0xffff0000, v133
	v_lshlrev_b32_e32 v40, 16, v134
	v_and_b32_e32 v41, 0xffff0000, v134
	v_lshlrev_b32_e32 v42, 16, v135
	v_and_b32_e32 v43, 0xffff0000, v135
	v_sub_f32_e32 v20, v20, v36
	v_sub_f32_e32 v21, v21, v37
	v_sub_f32_e32 v22, v22, v38
	v_sub_f32_e32 v23, v23, v39
	v_sub_f32_e32 v24, v24, v40
	v_sub_f32_e32 v25, v25, v41
	v_sub_f32_e32 v26, v26, v42
	v_sub_f32_e32 v27, v27, v43
	v_lshlrev_b32_e32 v28, 16, v148
	v_and_b32_e32 v29, 0xffff0000, v148
	v_lshlrev_b32_e32 v30, 16, v149
	v_and_b32_e32 v31, 0xffff0000, v149
	v_lshlrev_b32_e32 v32, 16, v150
	v_and_b32_e32 v33, 0xffff0000, v150
	v_lshlrev_b32_e32 v34, 16, v151
	v_and_b32_e32 v35, 0xffff0000, v151
	v_add_f32_e32 v20, v20, v28
	v_add_f32_e32 v21, v21, v29
	v_add_f32_e32 v22, v22, v30
	v_add_f32_e32 v23, v23, v31
	v_add_f32_e32 v24, v24, v32
	v_add_f32_e32 v25, v25, v33
	v_add_f32_e32 v26, v26, v34
	v_add_f32_e32 v27, v27, v35
	v_mov_b32_e32 v56, 0x3e800000
	s_nop 0
	v_fma_f32 v44, v56, v20, -v28
	v_fma_f32 v45, v56, v21, -v29
	v_fma_f32 v46, v56, v22, -v30
	v_fma_f32 v47, v56, v23, -v31
	v_fma_f32 v48, v56, v24, -v32
	v_fma_f32 v49, v56, v25, -v33
	v_fma_f32 v50, v56, v26, -v34
	v_fma_f32 v51, v56, v27, -v35
	v_cvt_pk_bf16_f32 v52, v44, v45
	v_cvt_pk_bf16_f32 v53, v46, v47
	v_cvt_pk_bf16_f32 v54, v48, v49
	v_cvt_pk_bf16_f32 v55, v50, v51
	global_store_dwordx4 v[8:9], v[52:55], off
	v_lshl_add_u64 v[8:9], v[8:9], 0, s[6:7]
	s_waitcnt vmcnt(15)
; __device__ __forceinline__ void phase_pool(const bf16_t* proj, bf16_t* pooled) {
;     ...
;         for (int r = 0; r < 16; ++r) {
;             float f[8]; unpack8(*(const u32x4*)(src + (ptrdiff_t)r * PP), f);
;             const int pos = pos0 + r;
;             if (r >= 1 && pos - w >= 0) { float o[8]; unpack8(*(const u32x4*)(src + (ptrdiff_t)(r - w) * PP), o);
; #pragma unroll
;                 for (int e = 0; e < 8; ++e) sum[e] -= o[e]; }
;             const float rc = 1.0f / (float)(pos + 1 < w ? pos + 1 : w);
;             float out[8];
; #pragma unroll
;             for (int e = 0; e < 8; ++e) { sum[e] += f[e]; out[e] = sum[e] * rc - f[e]; }
;             *(u32x4*)(pooled + (size_t)(r0 + r) * DM + cgi * 8) = pack8(out);
	v_lshlrev_b32_e32 v36, 16, v136
	v_and_b32_e32 v37, 0xffff0000, v136
	v_lshlrev_b32_e32 v38, 16, v137
	v_and_b32_e32 v39, 0xffff0000, v137
	v_lshlrev_b32_e32 v40, 16, v138
	v_and_b32_e32 v41, 0xffff0000, v138
	v_lshlrev_b32_e32 v42, 16, v139
	v_and_b32_e32 v43, 0xffff0000, v139
	v_sub_f32_e32 v20, v20, v36
	v_sub_f32_e32 v21, v21, v37
	v_sub_f32_e32 v22, v22, v38
	v_sub_f32_e32 v23, v23, v39
	v_sub_f32_e32 v24, v24, v40
	v_sub_f32_e32 v25, v25, v41
	v_sub_f32_e32 v26, v26, v42
	v_sub_f32_e32 v27, v27, v43
	v_lshlrev_b32_e32 v28, 16, v152
	v_and_b32_e32 v29, 0xffff0000, v152
	v_lshlrev_b32_e32 v30, 16, v153
	v_and_b32_e32 v31, 0xffff0000, v153
	v_lshlrev_b32_e32 v32, 16, v154
	v_and_b32_e32 v33, 0xffff0000, v154
	v_lshlrev_b32_e32 v34, 16, v155
	v_and_b32_e32 v35, 0xffff0000, v155
	v_add_f32_e32 v20, v20, v28
	v_add_f32_e32 v21, v21, v29
	v_add_f32_e32 v22, v22, v30
	v_add_f32_e32 v23, v23, v31
	v_add_f32_e32 v24, v24, v32
	v_add_f32_e32 v25, v25, v33
	v_add_f32_e32 v26, v26, v34
	v_add_f32_e32 v27, v27, v35
	v_mov_b32_e32 v56, 0x3e800000
	s_nop 0
	v_fma_f32 v44, v56, v20, -v28
	v_fma_f32 v45, v56, v21, -v29
	v_fma_f32 v46, v56, v22, -v30
	v_fma_f32 v47, v56, v23, -v31
	v_fma_f32 v48, v56, v24, -v32
	v_fma_f32 v49, v56, v25, -v33
	v_fma_f32 v50, v56, v26, -v34
	v_fma_f32 v51, v56, v27, -v35
	v_cvt_pk_bf16_f32 v52, v44, v45
	v_cvt_pk_bf16_f32 v53, v46, v47
	v_cvt_pk_bf16_f32 v54, v48, v49
	v_cvt_pk_bf16_f32 v55, v50, v51
	global_store_dwordx4 v[8:9], v[52:55], off
	v_lshl_add_u64 v[8:9], v[8:9], 0, s[6:7]
	s_waitcnt vmcnt(15)
	v_lshlrev_b32_e32 v36, 16, v140
	v_and_b32_e32 v37, 0xffff0000, v140
	v_lshlrev_b32_e32 v38, 16, v141
	v_and_b32_e32 v39, 0xffff0000, v141
	v_lshlrev_b32_e32 v40, 16, v142
	v_and_b32_e32 v41, 0xffff0000, v142
	v_lshlrev_b32_e32 v42, 16, v143
	v_and_b32_e32 v43, 0xffff0000, v143
	v_sub_f32_e32 v20, v20, v36
	v_sub_f32_e32 v21, v21, v37
	v_sub_f32_e32 v22, v22, v38
	v_sub_f32_e32 v23, v23, v39
	v_sub_f32_e32 v24, v24, v40
	v_sub_f32_e32 v25, v25, v41
	v_sub_f32_e32 v26, v26, v42
	v_sub_f32_e32 v27, v27, v43
	v_lshlrev_b32_e32 v28, 16, v156
	v_and_b32_e32 v29, 0xffff0000, v156
	v_lshlrev_b32_e32 v30, 16, v157
	v_and_b32_e32 v31, 0xffff0000, v157
	v_lshlrev_b32_e32 v32, 16, v158
	v_and_b32_e32 v33, 0xffff0000, v158
	v_lshlrev_b32_e32 v34, 16, v159
	v_and_b32_e32 v35, 0xffff0000, v159
	v_add_f32_e32 v20, v20, v28
	v_add_f32_e32 v21, v21, v29
	v_add_f32_e32 v22, v22, v30
	v_add_f32_e32 v23, v23, v31
	v_add_f32_e32 v24, v24, v32
	v_add_f32_e32 v25, v25, v33
	v_add_f32_e32 v26, v26, v34
	v_add_f32_e32 v27, v27, v35
	v_mov_b32_e32 v56, 0x3e800000
	s_nop 0
	v_fma_f32 v44, v56, v20, -v28
	v_fma_f32 v45, v56, v21, -v29
	v_fma_f32 v46, v56, v22, -v30
	v_fma_f32 v47, v56, v23, -v31
	v_fma_f32 v48, v56, v24, -v32
	v_fma_f32 v49, v56, v25, -v33
	v_fma_f32 v50, v56, v26, -v34
	v_fma_f32 v51, v56, v27, -v35
	v_cvt_pk_bf16_f32 v52, v44, v45
	v_cvt_pk_bf16_f32 v53, v46, v47
	v_cvt_pk_bf16_f32 v54, v48, v49
	v_cvt_pk_bf16_f32 v55, v50, v51
	global_store_dwordx4 v[8:9], v[52:55], off
	v_lshl_add_u64 v[8:9], v[8:9], 0, s[6:7]
	s_waitcnt vmcnt(15)
	v_lshlrev_b32_e32 v36, 16, v144
	v_and_b32_e32 v37, 0xffff0000, v144
	v_lshlrev_b32_e32 v38, 16, v145
	v_and_b32_e32 v39, 0xffff0000, v145
	v_lshlrev_b32_e32 v40, 16, v146
	v_and_b32_e32 v41, 0xffff0000, v146
	v_lshlrev_b32_e32 v42, 16, v147
	v_and_b32_e32 v43, 0xffff0000, v147
	v_sub_f32_e32 v20, v20, v36
	v_sub_f32_e32 v21, v21, v37
	v_sub_f32_e32 v22, v22, v38
	v_sub_f32_e32 v23, v23, v39
	v_sub_f32_e32 v24, v24, v40
	v_sub_f32_e32 v25, v25, v41
	v_sub_f32_e32 v26, v26, v42
	v_sub_f32_e32 v27, v27, v43
	v_lshlrev_b32_e32 v28, 16, v160
	v_and_b32_e32 v29, 0xffff0000, v160
	v_lshlrev_b32_e32 v30, 16, v161
	v_and_b32_e32 v31, 0xffff0000, v161
	v_lshlrev_b32_e32 v32, 16, v162
	v_and_b32_e32 v33, 0xffff0000, v162
	v_lshlrev_b32_e32 v34, 16, v163
	v_and_b32_e32 v35, 0xffff0000, v163
	v_add_f32_e32 v20, v20, v28
	v_add_f32_e32 v21, v21, v29
	v_add_f32_e32 v22, v22, v30
	v_add_f32_e32 v23, v23, v31
	v_add_f32_e32 v24, v24, v32
	v_add_f32_e32 v25, v25, v33
	v_add_f32_e32 v26, v26, v34
	v_add_f32_e32 v27, v27, v35
	v_mov_b32_e32 v56, 0x3e800000
	s_nop 0
	v_fma_f32 v44, v56, v20, -v28
	v_fma_f32 v45, v56, v21, -v29
	v_fma_f32 v46, v56, v22, -v30
	v_fma_f32 v47, v56, v23, -v31
	v_fma_f32 v48, v56, v24, -v32
	v_fma_f32 v49, v56, v25, -v33
	v_fma_f32 v50, v56, v26, -v34
	v_fma_f32 v51, v56, v27, -v35
	v_cvt_pk_bf16_f32 v52, v44, v45
	v_cvt_pk_bf16_f32 v53, v46, v47
	v_cvt_pk_bf16_f32 v54, v48, v49
	v_cvt_pk_bf16_f32 v55, v50, v51
	global_store_dwordx4 v[8:9], v[52:55], off
	v_lshl_add_u64 v[8:9], v[8:9], 0, s[6:7]
	s_waitcnt vmcnt(15)
	v_lshlrev_b32_e32 v36, 16, v148
	v_and_b32_e32 v37, 0xffff0000, v148
	v_lshlrev_b32_e32 v38, 16, v149
	v_and_b32_e32 v39, 0xffff0000, v149
	v_lshlrev_b32_e32 v40, 16, v150
	v_and_b32_e32 v41, 0xffff0000, v150
	v_lshlrev_b32_e32 v42, 16, v151
	v_and_b32_e32 v43, 0xffff0000, v151
	v_sub_f32_e32 v20, v20, v36
	v_sub_f32_e32 v21, v21, v37
	v_sub_f32_e32 v22, v22, v38
	v_sub_f32_e32 v23, v23, v39
	v_sub_f32_e32 v24, v24, v40
	v_sub_f32_e32 v25, v25, v41
	v_sub_f32_e32 v26, v26, v42
	v_sub_f32_e32 v27, v27, v43
	v_lshlrev_b32_e32 v28, 16, v164
	v_and_b32_e32 v29, 0xffff0000, v164
	v_lshlrev_b32_e32 v30, 16, v165
	v_and_b32_e32 v31, 0xffff0000, v165
	v_lshlrev_b32_e32 v32, 16, v166
	v_and_b32_e32 v33, 0xffff0000, v166
	v_lshlrev_b32_e32 v34, 16, v167
	v_and_b32_e32 v35, 0xffff0000, v167
	v_add_f32_e32 v20, v20, v28
	v_add_f32_e32 v21, v21, v29
	v_add_f32_e32 v22, v22, v30
	v_add_f32_e32 v23, v23, v31
	v_add_f32_e32 v24, v24, v32
	v_add_f32_e32 v25, v25, v33
	v_add_f32_e32 v26, v26, v34
	v_add_f32_e32 v27, v27, v35
	v_mov_b32_e32 v56, 0x3e800000
	s_nop 0
	v_fma_f32 v44, v56, v20, -v28
	v_fma_f32 v45, v56, v21, -v29
	v_fma_f32 v46, v56, v22, -v30
	v_fma_f32 v47, v56, v23, -v31
	v_fma_f32 v48, v56, v24, -v32
	v_fma_f32 v49, v56, v25, -v33
	v_fma_f32 v50, v56, v26, -v34
	v_fma_f32 v51, v56, v27, -v35
	v_cvt_pk_bf16_f32 v52, v44, v45
	v_cvt_pk_bf16_f32 v53, v46, v47
	v_cvt_pk_bf16_f32 v54, v48, v49
	v_cvt_pk_bf16_f32 v55, v50, v51
	global_store_dwordx4 v[8:9], v[52:55], off
	v_lshl_add_u64 v[8:9], v[8:9], 0, s[6:7]
	s_waitcnt vmcnt(15)
; __device__ __forceinline__ void phase_pool(const bf16_t* proj, bf16_t* pooled) {
;     ...
;         for (int r = 0; r < 16; ++r) {
;             float f[8]; unpack8(*(const u32x4*)(src + (ptrdiff_t)r * PP), f);
;             const int pos = pos0 + r;
;             if (r >= 1 && pos - w >= 0) { float o[8]; unpack8(*(const u32x4*)(src + (ptrdiff_t)(r - w) * PP), o);
; #pragma unroll
;                 for (int e = 0; e < 8; ++e) sum[e] -= o[e]; }
;             const float rc = 1.0f / (float)(pos + 1 < w ? pos + 1 : w);
;             float out[8];
; #pragma unroll
;             for (int e = 0; e < 8; ++e) { sum[e] += f[e]; out[e] = sum[e] * rc - f[e]; }
;             *(u32x4*)(pooled + (size_t)(r0 + r) * DM + cgi * 8) = pack8(out);
;         }
	v_lshlrev_b32_e32 v36, 16, v152
	v_and_b32_e32 v37, 0xffff0000, v152
	v_lshlrev_b32_e32 v38, 16, v153
	v_and_b32_e32 v39, 0xffff0000, v153
	v_lshlrev_b32_e32 v40, 16, v154
	v_and_b32_e32 v41, 0xffff0000, v154
	v_lshlrev_b32_e32 v42, 16, v155
	v_and_b32_e32 v43, 0xffff0000, v155
	v_sub_f32_e32 v20, v20, v36
	v_sub_f32_e32 v21, v21, v37
	v_sub_f32_e32 v22, v22, v38
	v_sub_f32_e32 v23, v23, v39
	v_sub_f32_e32 v24, v24, v40
	v_sub_f32_e32 v25, v25, v41
	v_sub_f32_e32 v26, v26, v42
	v_sub_f32_e32 v27, v27, v43
	v_lshlrev_b32_e32 v28, 16, v168
	v_and_b32_e32 v29, 0xffff0000, v168
	v_lshlrev_b32_e32 v30, 16, v169
	v_and_b32_e32 v31, 0xffff0000, v169
	v_lshlrev_b32_e32 v32, 16, v170
	v_and_b32_e32 v33, 0xffff0000, v170
	v_lshlrev_b32_e32 v34, 16, v171
	v_and_b32_e32 v35, 0xffff0000, v171
	v_add_f32_e32 v20, v20, v28
	v_add_f32_e32 v21, v21, v29
	v_add_f32_e32 v22, v22, v30
	v_add_f32_e32 v23, v23, v31
	v_add_f32_e32 v24, v24, v32
	v_add_f32_e32 v25, v25, v33
	v_add_f32_e32 v26, v26, v34
	v_add_f32_e32 v27, v27, v35
	v_mov_b32_e32 v56, 0x3e800000
	s_nop 0
	v_fma_f32 v44, v56, v20, -v28
	v_fma_f32 v45, v56, v21, -v29
	v_fma_f32 v46, v56, v22, -v30
	v_fma_f32 v47, v56, v23, -v31
	v_fma_f32 v48, v56, v24, -v32
	v_fma_f32 v49, v56, v25, -v33
	v_fma_f32 v50, v56, v26, -v34
	v_fma_f32 v51, v56, v27, -v35
	v_cvt_pk_bf16_f32 v52, v44, v45
	v_cvt_pk_bf16_f32 v53, v46, v47
	v_cvt_pk_bf16_f32 v54, v48, v49
	v_cvt_pk_bf16_f32 v55, v50, v51
	global_store_dwordx4 v[8:9], v[52:55], off
	v_lshl_add_u64 v[8:9], v[8:9], 0, s[6:7]
	s_waitcnt vmcnt(15)
	v_lshlrev_b32_e32 v36, 16, v156
	v_and_b32_e32 v37, 0xffff0000, v156
	v_lshlrev_b32_e32 v38, 16, v157
	v_and_b32_e32 v39, 0xffff0000, v157
	v_lshlrev_b32_e32 v40, 16, v158
	v_and_b32_e32 v41, 0xffff0000, v158
	v_lshlrev_b32_e32 v42, 16, v159
	v_and_b32_e32 v43, 0xffff0000, v159
	v_sub_f32_e32 v20, v20, v36
	v_sub_f32_e32 v21, v21, v37
	v_sub_f32_e32 v22, v22, v38
	v_sub_f32_e32 v23, v23, v39
	v_sub_f32_e32 v24, v24, v40
	v_sub_f32_e32 v25, v25, v41
	v_sub_f32_e32 v26, v26, v42
	v_sub_f32_e32 v27, v27, v43
	v_lshlrev_b32_e32 v28, 16, v172
	v_and_b32_e32 v29, 0xffff0000, v172
	v_lshlrev_b32_e32 v30, 16, v173
	v_and_b32_e32 v31, 0xffff0000, v173
	v_lshlrev_b32_e32 v32, 16, v174
	v_and_b32_e32 v33, 0xffff0000, v174
	v_lshlrev_b32_e32 v34, 16, v175
	v_and_b32_e32 v35, 0xffff0000, v175
	v_add_f32_e32 v20, v20, v28
	v_add_f32_e32 v21, v21, v29
	v_add_f32_e32 v22, v22, v30
	v_add_f32_e32 v23, v23, v31
	v_add_f32_e32 v24, v24, v32
	v_add_f32_e32 v25, v25, v33
	v_add_f32_e32 v26, v26, v34
	v_add_f32_e32 v27, v27, v35
	v_mov_b32_e32 v56, 0x3e800000
	s_nop 0
	v_fma_f32 v44, v56, v20, -v28
	v_fma_f32 v45, v56, v21, -v29
	v_fma_f32 v46, v56, v22, -v30
	v_fma_f32 v47, v56, v23, -v31
	v_fma_f32 v48, v56, v24, -v32
	v_fma_f32 v49, v56, v25, -v33
	v_fma_f32 v50, v56, v26, -v34
	v_fma_f32 v51, v56, v27, -v35
	v_cvt_pk_bf16_f32 v52, v44, v45
	v_cvt_pk_bf16_f32 v53, v46, v47
	v_cvt_pk_bf16_f32 v54, v48, v49
	v_cvt_pk_bf16_f32 v55, v50, v51
	global_store_dwordx4 v[8:9], v[52:55], off
	v_lshl_add_u64 v[8:9], v[8:9], 0, s[6:7]
	s_waitcnt vmcnt(15)
	v_lshlrev_b32_e32 v36, 16, v160
	v_and_b32_e32 v37, 0xffff0000, v160
	v_lshlrev_b32_e32 v38, 16, v161
	v_and_b32_e32 v39, 0xffff0000, v161
	v_lshlrev_b32_e32 v40, 16, v162
	v_and_b32_e32 v41, 0xffff0000, v162
	v_lshlrev_b32_e32 v42, 16, v163
	v_and_b32_e32 v43, 0xffff0000, v163
	v_sub_f32_e32 v20, v20, v36
	v_sub_f32_e32 v21, v21, v37
	v_sub_f32_e32 v22, v22, v38
	v_sub_f32_e32 v23, v23, v39
	v_sub_f32_e32 v24, v24, v40
	v_sub_f32_e32 v25, v25, v41
	v_sub_f32_e32 v26, v26, v42
	v_sub_f32_e32 v27, v27, v43
	v_lshlrev_b32_e32 v28, 16, v176
	v_and_b32_e32 v29, 0xffff0000, v176
	v_lshlrev_b32_e32 v30, 16, v177
	v_and_b32_e32 v31, 0xffff0000, v177
	v_lshlrev_b32_e32 v32, 16, v178
	v_and_b32_e32 v33, 0xffff0000, v178
	v_lshlrev_b32_e32 v34, 16, v179
	v_and_b32_e32 v35, 0xffff0000, v179
	v_add_f32_e32 v20, v20, v28
	v_add_f32_e32 v21, v21, v29
	v_add_f32_e32 v22, v22, v30
	v_add_f32_e32 v23, v23, v31
	v_add_f32_e32 v24, v24, v32
	v_add_f32_e32 v25, v25, v33
	v_add_f32_e32 v26, v26, v34
	v_add_f32_e32 v27, v27, v35
	v_mov_b32_e32 v56, 0x3e800000
	s_nop 0
	v_fma_f32 v44, v56, v20, -v28
	v_fma_f32 v45, v56, v21, -v29
	v_fma_f32 v46, v56, v22, -v30
	v_fma_f32 v47, v56, v23, -v31
	v_fma_f32 v48, v56, v24, -v32
	v_fma_f32 v49, v56, v25, -v33
	v_fma_f32 v50, v56, v26, -v34
	v_fma_f32 v51, v56, v27, -v35
	v_cvt_pk_bf16_f32 v52, v44, v45
	v_cvt_pk_bf16_f32 v53, v46, v47
	v_cvt_pk_bf16_f32 v54, v48, v49
	v_cvt_pk_bf16_f32 v55, v50, v51
	global_store_dwordx4 v[8:9], v[52:55], off
	v_lshl_add_u64 v[8:9], v[8:9], 0, s[6:7]
	s_waitcnt vmcnt(15)
	v_lshlrev_b32_e32 v36, 16, v164
	v_and_b32_e32 v37, 0xffff0000, v164
	v_lshlrev_b32_e32 v38, 16, v165
	v_and_b32_e32 v39, 0xffff0000, v165
	v_lshlrev_b32_e32 v40, 16, v166
	v_and_b32_e32 v41, 0xffff0000, v166
	v_lshlrev_b32_e32 v42, 16, v167
	v_and_b32_e32 v43, 0xffff0000, v167
	v_sub_f32_e32 v20, v20, v36
	v_sub_f32_e32 v21, v21, v37
	v_sub_f32_e32 v22, v22, v38
	v_sub_f32_e32 v23, v23, v39
	v_sub_f32_e32 v24, v24, v40
	v_sub_f32_e32 v25, v25, v41
	v_sub_f32_e32 v26, v26, v42
	v_sub_f32_e32 v27, v27, v43
	v_lshlrev_b32_e32 v28, 16, v180
	v_and_b32_e32 v29, 0xffff0000, v180
	v_lshlrev_b32_e32 v30, 16, v181
	v_and_b32_e32 v31, 0xffff0000, v181
	v_lshlrev_b32_e32 v32, 16, v182
	v_and_b32_e32 v33, 0xffff0000, v182
	v_lshlrev_b32_e32 v34, 16, v183
	v_and_b32_e32 v35, 0xffff0000, v183
	v_add_f32_e32 v20, v20, v28
	v_add_f32_e32 v21, v21, v29
	v_add_f32_e32 v22, v22, v30
	v_add_f32_e32 v23, v23, v31
	v_add_f32_e32 v24, v24, v32
	v_add_f32_e32 v25, v25, v33
	v_add_f32_e32 v26, v26, v34
	v_add_f32_e32 v27, v27, v35
	v_mov_b32_e32 v56, 0x3e800000
	s_nop 0
	v_fma_f32 v44, v56, v20, -v28
	v_fma_f32 v45, v56, v21, -v29
	v_fma_f32 v46, v56, v22, -v30
	v_fma_f32 v47, v56, v23, -v31
	v_fma_f32 v48, v56, v24, -v32
	v_fma_f32 v49, v56, v25, -v33
	v_fma_f32 v50, v56, v26, -v34
	v_fma_f32 v51, v56, v27, -v35
	v_cvt_pk_bf16_f32 v52, v44, v45
	v_cvt_pk_bf16_f32 v53, v46, v47
	v_cvt_pk_bf16_f32 v54, v48, v49
	v_cvt_pk_bf16_f32 v55, v50, v51
	global_store_dwordx4 v[8:9], v[52:55], off
	s_branch .Lmy_pool_next
; __device__ __forceinline__ void phase_pool(const bf16_t* proj, bf16_t* pooled) {
;     ...
;         const int cgi = idx & 127, seg = idx >> 7, r0 = seg * 16, pos0 = r0 & (SEQ - 1), w = 2 << (cgi >> 5);
;         const bf16_t* src = proj + SEC(C_PU) + (size_t)r0 * PP + cgi * 8;
;         float sum[8];
; #pragma unroll
;         for (int e = 0; e < 8; ++e) sum[e] = 0.f;
;         if (pos0 > 0) for (int j = 1; j < w; ++j) { float f[8]; unpack8(*(const u32x4*)(src - (ptrdiff_t)j * PP), f);
; #pragma unroll
;             for (int e = 0; e < 8; ++e) sum[e] += f[e]; }
;         for (int r = 0; r < 16; ++r) {
;             float f[8]; unpack8(*(const u32x4*)(src + (ptrdiff_t)r * PP), f);
;             const int pos = pos0 + r;
;             if (r >= 1 && pos - w >= 0) { float o[8]; unpack8(*(const u32x4*)(src + (ptrdiff_t)(r - w) * PP), o);
; #pragma unroll
;                 for (int e = 0; e < 8; ++e) sum[e] -= o[e]; }
;             const float rc = 1.0f / (float)(pos + 1 < w ? pos + 1 : w);
;             float out[8];
; #pragma unroll
;             for (int e = 0; e < 8; ++e) { sum[e] += f[e]; out[e] = sum[e] * rc - f[e]; }
;             *(u32x4*)(pooled + (size_t)(r0 + r) * DM + cgi * 8) = pack8(out);
.Lmy_pool_w2:
	v_lshl_add_u64 v[10:11], v[6:7], 0, s[8:9]
	global_load_dwordx4 v[60:63], v[10:11], off
	v_mov_b32_e32 v10, v6
	v_mov_b32_e32 v11, v7
	global_load_dwordx4 v[120:123], v[10:11], off
	v_lshl_add_u64 v[10:11], v[10:11], 0, s[6:7]
	global_load_dwordx4 v[124:127], v[10:11], off
	v_lshl_add_u64 v[10:11], v[10:11], 0, s[6:7]
	global_load_dwordx4 v[128:131], v[10:11], off
	v_lshl_add_u64 v[10:11], v[10:11], 0, s[6:7]
	global_load_dwordx4 v[132:135], v[10:11], off
	v_lshl_add_u64 v[10:11], v[10:11], 0, s[6:7]
	global_load_dwordx4 v[136:139], v[10:11], off
	v_lshl_add_u64 v[10:11], v[10:11], 0, s[6:7]
	global_load_dwordx4 v[140:143], v[10:11], off
	v_lshl_add_u64 v[10:11], v[10:11], 0, s[6:7]
	global_load_dwordx4 v[144:147], v[10:11], off
	v_lshl_add_u64 v[10:11], v[10:11], 0, s[6:7]
	global_load_dwordx4 v[148:151], v[10:11], off
	v_lshl_add_u64 v[10:11], v[10:11], 0, s[6:7]
	global_load_dwordx4 v[152:155], v[10:11], off
	v_lshl_add_u64 v[10:11], v[10:11], 0, s[6:7]
	global_load_dwordx4 v[156:159], v[10:11], off
	v_lshl_add_u64 v[10:11], v[10:11], 0, s[6:7]
	global_load_dwordx4 v[160:163], v[10:11], off
	v_lshl_add_u64 v[10:11], v[10:11], 0, s[6:7]
	global_load_dwordx4 v[164:167], v[10:11], off
	v_lshl_add_u64 v[10:11], v[10:11], 0, s[6:7]
	global_load_dwordx4 v[168:171], v[10:11], off
	v_lshl_add_u64 v[10:11], v[10:11], 0, s[6:7]
	global_load_dwordx4 v[172:175], v[10:11], off
	v_lshl_add_u64 v[10:11], v[10:11], 0, s[6:7]
	global_load_dwordx4 v[176:179], v[10:11], off
	v_lshl_add_u64 v[10:11], v[10:11], 0, s[6:7]
	global_load_dwordx4 v[180:183], v[10:11], off
	v_mov_b32_e32 v20, 0
	v_mov_b32_e32 v21, 0
	v_mov_b32_e32 v22, 0
	v_mov_b32_e32 v23, 0
	v_mov_b32_e32 v24, 0
	v_mov_b32_e32 v25, 0
	v_mov_b32_e32 v26, 0
	v_mov_b32_e32 v27, 0
	s_waitcnt vmcnt(16)
	v_lshlrev_b32_e32 v28, 16, v60
	v_and_b32_e32 v29, 0xffff0000, v60
	v_lshlrev_b32_e32 v30, 16, v61
	v_and_b32_e32 v31, 0xffff0000, v61
	v_lshlrev_b32_e32 v32, 16, v62
	v_and_b32_e32 v33, 0xffff0000, v62
	v_lshlrev_b32_e32 v34, 16, v63
	v_and_b32_e32 v35, 0xffff0000, v63
	v_cndmask_b32_e64 v28, 0, v28, s[2:3]
	v_cndmask_b32_e64 v29, 0, v29, s[2:3]
	v_cndmask_b32_e64 v30, 0, v30, s[2:3]
	v_cndmask_b32_e64 v31, 0, v31, s[2:3]
	v_cndmask_b32_e64 v32, 0, v32, s[2:3]
	v_cndmask_b32_e64 v33, 0, v33, s[2:3]
	v_cndmask_b32_e64 v34, 0, v34, s[2:3]
	v_cndmask_b32_e64 v35, 0, v35, s[2:3]
	v_add_f32_e32 v20, v20, v28
	v_add_f32_e32 v21, v21, v29
	v_add_f32_e32 v22, v22, v30
	v_add_f32_e32 v23, v23, v31
	v_add_f32_e32 v24, v24, v32
	v_add_f32_e32 v25, v25, v33
	v_add_f32_e32 v26, v26, v34
	v_add_f32_e32 v27, v27, v35
	s_waitcnt vmcnt(15)
	v_lshlrev_b32_e32 v28, 16, v120
	v_and_b32_e32 v29, 0xffff0000, v120
	v_lshlrev_b32_e32 v30, 16, v121
	v_and_b32_e32 v31, 0xffff0000, v121
	v_lshlrev_b32_e32 v32, 16, v122
	v_and_b32_e32 v33, 0xffff0000, v122
	v_lshlrev_b32_e32 v34, 16, v123
	v_and_b32_e32 v35, 0xffff0000, v123
	v_add_f32_e32 v20, v20, v28
	v_add_f32_e32 v21, v21, v29
	v_add_f32_e32 v22, v22, v30
	v_add_f32_e32 v23, v23, v31
	v_add_f32_e32 v24, v24, v32
	v_add_f32_e32 v25, v25, v33
	v_add_f32_e32 v26, v26, v34
	v_add_f32_e32 v27, v27, v35
	v_mov_b32_e32 v56, 0x3f800000
	v_mov_b32_e32 v57, 0x3f000000
	v_cndmask_b32_e64 v56, v56, v57, s[2:3]
	s_nop 0
	v_fma_f32 v44, v56, v20, -v28
	v_fma_f32 v45, v56, v21, -v29
	v_fma_f32 v46, v56, v22, -v30
	v_fma_f32 v47, v56, v23, -v31
	v_fma_f32 v48, v56, v24, -v32
	v_fma_f32 v49, v56, v25, -v33
	v_fma_f32 v50, v56, v26, -v34
	v_fma_f32 v51, v56, v27, -v35
	v_cvt_pk_bf16_f32 v52, v44, v45
	v_cvt_pk_bf16_f32 v53, v46, v47
	v_cvt_pk_bf16_f32 v54, v48, v49
	v_cvt_pk_bf16_f32 v55, v50, v51
	global_store_dwordx4 v[8:9], v[52:55], off
	v_lshl_add_u64 v[8:9], v[8:9], 0, s[6:7]
	s_waitcnt vmcnt(15)
	v_lshlrev_b32_e32 v36, 16, v60
	v_and_b32_e32 v37, 0xffff0000, v60
	v_lshlrev_b32_e32 v38, 16, v61
	v_and_b32_e32 v39, 0xffff0000, v61
	v_lshlrev_b32_e32 v40, 16, v62
	v_and_b32_e32 v41, 0xffff0000, v62
	v_lshlrev_b32_e32 v42, 16, v63
	v_and_b32_e32 v43, 0xffff0000, v63
	v_cndmask_b32_e64 v36, 0, v36, s[2:3]
	v_cndmask_b32_e64 v37, 0, v37, s[2:3]
	v_cndmask_b32_e64 v38, 0, v38, s[2:3]
	v_cndmask_b32_e64 v39, 0, v39, s[2:3]
	v_cndmask_b32_e64 v40, 0, v40, s[2:3]
	v_cndmask_b32_e64 v41, 0, v41, s[2:3]
	v_cndmask_b32_e64 v42, 0, v42, s[2:3]
	v_cndmask_b32_e64 v43, 0, v43, s[2:3]
	v_sub_f32_e32 v20, v20, v36
	v_sub_f32_e32 v21, v21, v37
	v_sub_f32_e32 v22, v22, v38
	v_sub_f32_e32 v23, v23, v39
	v_sub_f32_e32 v24, v24, v40
	v_sub_f32_e32 v25, v25, v41
	v_sub_f32_e32 v26, v26, v42
	v_sub_f32_e32 v27, v27, v43
	v_lshlrev_b32_e32 v28, 16, v124
	v_and_b32_e32 v29, 0xffff0000, v124
	v_lshlrev_b32_e32 v30, 16, v125
	v_and_b32_e32 v31, 0xffff0000, v125
	v_lshlrev_b32_e32 v32, 16, v126
	v_and_b32_e32 v33, 0xffff0000, v126
	v_lshlrev_b32_e32 v34, 16, v127
	v_and_b32_e32 v35, 0xffff0000, v127
	v_add_f32_e32 v20, v20, v28
	v_add_f32_e32 v21, v21, v29
	v_add_f32_e32 v22, v22, v30
	v_add_f32_e32 v23, v23, v31
	v_add_f32_e32 v24, v24, v32
	v_add_f32_e32 v25, v25, v33
	v_add_f32_e32 v26, v26, v34
	v_add_f32_e32 v27, v27, v35
	v_mov_b32_e32 v56, 0x3f000000
	s_nop 0
	v_fma_f32 v44, v56, v20, -v28
	v_fma_f32 v45, v56, v21, -v29
	v_fma_f32 v46, v56, v22, -v30
	v_fma_f32 v47, v56, v23, -v31
	v_fma_f32 v48, v56, v24, -v32
	v_fma_f32 v49, v56, v25, -v33
	v_fma_f32 v50, v56, v26, -v34
	v_fma_f32 v51, v56, v27, -v35
	v_cvt_pk_bf16_f32 v52, v44, v45
	v_cvt_pk_bf16_f32 v53, v46, v47
	v_cvt_pk_bf16_f32 v54, v48, v49
	v_cvt_pk_bf16_f32 v55, v50, v51
	global_store_dwordx4 v[8:9], v[52:55], off
	v_lshl_add_u64 v[8:9], v[8:9], 0, s[6:7]
	s_waitcnt vmcnt(15)
; __device__ __forceinline__ void phase_pool(const bf16_t* proj, bf16_t* pooled) {
;     ...
;         for (int r = 0; r < 16; ++r) {
;             float f[8]; unpack8(*(const u32x4*)(src + (ptrdiff_t)r * PP), f);
;             const int pos = pos0 + r;
;             if (r >= 1 && pos - w >= 0) { float o[8]; unpack8(*(const u32x4*)(src + (ptrdiff_t)(r - w) * PP), o);
; #pragma unroll
;                 for (int e = 0; e < 8; ++e) sum[e] -= o[e]; }
;             const float rc = 1.0f / (float)(pos + 1 < w ? pos + 1 : w);
;             float out[8];
; #pragma unroll
;             for (int e = 0; e < 8; ++e) { sum[e] += f[e]; out[e] = sum[e] * rc - f[e]; }
;             *(u32x4*)(pooled + (size_t)(r0 + r) * DM + cgi * 8) = pack8(out);
	v_lshlrev_b32_e32 v36, 16, v120
	v_and_b32_e32 v37, 0xffff0000, v120
	v_lshlrev_b32_e32 v38, 16, v121
	v_and_b32_e32 v39, 0xffff0000, v121
	v_lshlrev_b32_e32 v40, 16, v122
	v_and_b32_e32 v41, 0xffff0000, v122
	v_lshlrev_b32_e32 v42, 16, v123
	v_and_b32_e32 v43, 0xffff0000, v123
	v_sub_f32_e32 v20, v20, v36
	v_sub_f32_e32 v21, v21, v37
	v_sub_f32_e32 v22, v22, v38
	v_sub_f32_e32 v23, v23, v39
	v_sub_f32_e32 v24, v24, v40
	v_sub_f32_e32 v25, v25, v41
	v_sub_f32_e32 v26, v26, v42
	v_sub_f32_e32 v27, v27, v43
	v_lshlrev_b32_e32 v28, 16, v128
	v_and_b32_e32 v29, 0xffff0000, v128
	v_lshlrev_b32_e32 v30, 16, v129
	v_and_b32_e32 v31, 0xffff0000, v129
	v_lshlrev_b32_e32 v32, 16, v130
	v_and_b32_e32 v33, 0xffff0000, v130
	v_lshlrev_b32_e32 v34, 16, v131
	v_and_b32_e32 v35, 0xffff0000, v131
	v_add_f32_e32 v20, v20, v28
	v_add_f32_e32 v21, v21, v29
	v_add_f32_e32 v22, v22, v30
	v_add_f32_e32 v23, v23, v31
	v_add_f32_e32 v24, v24, v32
	v_add_f32_e32 v25, v25, v33
	v_add_f32_e32 v26, v26, v34
	v_add_f32_e32 v27, v27, v35
	v_mov_b32_e32 v56, 0x3f000000
	s_nop 0
	v_fma_f32 v44, v56, v20, -v28
	v_fma_f32 v45, v56, v21, -v29
	v_fma_f32 v46, v56, v22, -v30
	v_fma_f32 v47, v56, v23, -v31
	v_fma_f32 v48, v56, v24, -v32
	v_fma_f32 v49, v56, v25, -v33
	v_fma_f32 v50, v56, v26, -v34
	v_fma_f32 v51, v56, v27, -v35
	v_cvt_pk_bf16_f32 v52, v44, v45
	v_cvt_pk_bf16_f32 v53, v46, v47
	v_cvt_pk_bf16_f32 v54, v48, v49
	v_cvt_pk_bf16_f32 v55, v50, v51
	global_store_dwordx4 v[8:9], v[52:55], off
	v_lshl_add_u64 v[8:9], v[8:9], 0, s[6:7]
	s_waitcnt vmcnt(15)
	v_lshlrev_b32_e32 v36, 16, v124
	v_and_b32_e32 v37, 0xffff0000, v124
	v_lshlrev_b32_e32 v38, 16, v125
	v_and_b32_e32 v39, 0xffff0000, v125
	v_lshlrev_b32_e32 v40, 16, v126
	v_and_b32_e32 v41, 0xffff0000, v126
	v_lshlrev_b32_e32 v42, 16, v127
	v_and_b32_e32 v43, 0xffff0000, v127
	v_sub_f32_e32 v20, v20, v36
	v_sub_f32_e32 v21, v21, v37
	v_sub_f32_e32 v22, v22, v38
	v_sub_f32_e32 v23, v23, v39
	v_sub_f32_e32 v24, v24, v40
	v_sub_f32_e32 v25, v25, v41
	v_sub_f32_e32 v26, v26, v42
	v_sub_f32_e32 v27, v27, v43
	v_lshlrev_b32_e32 v28, 16, v132
	v_and_b32_e32 v29, 0xffff0000, v132
	v_lshlrev_b32_e32 v30, 16, v133
	v_and_b32_e32 v31, 0xffff0000, v133
	v_lshlrev_b32_e32 v32, 16, v134
	v_and_b32_e32 v33, 0xffff0000, v134
	v_lshlrev_b32_e32 v34, 16, v135
	v_and_b32_e32 v35, 0xffff0000, v135
	v_add_f32_e32 v20, v20, v28
	v_add_f32_e32 v21, v21, v29
	v_add_f32_e32 v22, v22, v30
	v_add_f32_e32 v23, v23, v31
	v_add_f32_e32 v24, v24, v32
	v_add_f32_e32 v25, v25, v33
	v_add_f32_e32 v26, v26, v34
	v_add_f32_e32 v27, v27, v35
	v_mov_b32_e32 v56, 0x3f000000
	s_nop 0
	v_fma_f32 v44, v56, v20, -v28
	v_fma_f32 v45, v56, v21, -v29
	v_fma_f32 v46, v56, v22, -v30
	v_fma_f32 v47, v56, v23, -v31
	v_fma_f32 v48, v56, v24, -v32
	v_fma_f32 v49, v56, v25, -v33
	v_fma_f32 v50, v56, v26, -v34
	v_fma_f32 v51, v56, v27, -v35
	v_cvt_pk_bf16_f32 v52, v44, v45
	v_cvt_pk_bf16_f32 v53, v46, v47
	v_cvt_pk_bf16_f32 v54, v48, v49
	v_cvt_pk_bf16_f32 v55, v50, v51
	global_store_dwordx4 v[8:9], v[52:55], off
	v_lshl_add_u64 v[8:9], v[8:9], 0, s[6:7]
	s_waitcnt vmcnt(15)
	v_lshlrev_b32_e32 v36, 16, v128
	v_and_b32_e32 v37, 0xffff0000, v128
	v_lshlrev_b32_e32 v38, 16, v129
	v_and_b32_e32 v39, 0xffff0000, v129
	v_lshlrev_b32_e32 v40, 16, v130
	v_and_b32_e32 v41, 0xffff0000, v130
	v_lshlrev_b32_e32 v42, 16, v131
	v_and_b32_e32 v43, 0xffff0000, v131
	v_sub_f32_e32 v20, v20, v36
	v_sub_f32_e32 v21, v21, v37
	v_sub_f32_e32 v22, v22, v38
	v_sub_f32_e32 v23, v23, v39
	v_sub_f32_e32 v24, v24, v40
	v_sub_f32_e32 v25, v25, v41
	v_sub_f32_e32 v26, v26, v42
	v_sub_f32_e32 v27, v27, v43
	v_lshlrev_b32_e32 v28, 16, v136
	v_and_b32_e32 v29, 0xffff0000, v136
	v_lshlrev_b32_e32 v30, 16, v137
	v_and_b32_e32 v31, 0xffff0000, v137
	v_lshlrev_b32_e32 v32, 16, v138
	v_and_b32_e32 v33, 0xffff0000, v138
	v_lshlrev_b32_e32 v34, 16, v139
	v_and_b32_e32 v35, 0xffff0000, v139
	v_add_f32_e32 v20, v20, v28
	v_add_f32_e32 v21, v21, v29
	v_add_f32_e32 v22, v22, v30
	v_add_f32_e32 v23, v23, v31
	v_add_f32_e32 v24, v24, v32
	v_add_f32_e32 v25, v25, v33
	v_add_f32_e32 v26, v26, v34
	v_add_f32_e32 v27, v27, v35
	v_mov_b32_e32 v56, 0x3f000000
	s_nop 0
	v_fma_f32 v44, v56, v20, -v28
	v_fma_f32 v45, v56, v21, -v29
	v_fma_f32 v46, v56, v22, -v30
	v_fma_f32 v47, v56, v23, -v31
	v_fma_f32 v48, v56, v24, -v32
	v_fma_f32 v49, v56, v25, -v33
	v_fma_f32 v50, v56, v26, -v34
	v_fma_f32 v51, v56, v27, -v35
	v_cvt_pk_bf16_f32 v52, v44, v45
	v_cvt_pk_bf16_f32 v53, v46, v47
	v_cvt_pk_bf16_f32 v54, v48, v49
	v_cvt_pk_bf16_f32 v55, v50, v51
	global_store_dwordx4 v[8:9], v[52:55], off
	v_lshl_add_u64 v[8:9], v[8:9], 0, s[6:7]
	s_waitcnt vmcnt(15)
	v_lshlrev_b32_e32 v36, 16, v132
	v_and_b32_e32 v37, 0xffff0000, v132
	v_lshlrev_b32_e32 v38, 16, v133
	v_and_b32_e32 v39, 0xffff0000, v133
	v_lshlrev_b32_e32 v40, 16, v134
	v_and_b32_e32 v41, 0xffff0000, v134
	v_lshlrev_b32_e32 v42, 16, v135
	v_and_b32_e32 v43, 0xffff0000, v135
	v_sub_f32_e32 v20, v20, v36
	v_sub_f32_e32 v21, v21, v37
	v_sub_f32_e32 v22, v22, v38
	v_sub_f32_e32 v23, v23, v39
	v_sub_f32_e32 v24, v24, v40
	v_sub_f32_e32 v25, v25, v41
	v_sub_f32_e32 v26, v26, v42
	v_sub_f32_e32 v27, v27, v43
	v_lshlrev_b32_e32 v28, 16, v140
	v_and_b32_e32 v29, 0xffff0000, v140
	v_lshlrev_b32_e32 v30, 16, v141
	v_and_b32_e32 v31, 0xffff0000, v141
	v_lshlrev_b32_e32 v32, 16, v142
	v_and_b32_e32 v33, 0xffff0000, v142
	v_lshlrev_b32_e32 v34, 16, v143
	v_and_b32_e32 v35, 0xffff0000, v143
	v_add_f32_e32 v20, v20, v28
	v_add_f32_e32 v21, v21, v29
	v_add_f32_e32 v22, v22, v30
	v_add_f32_e32 v23, v23, v31
	v_add_f32_e32 v24, v24, v32
	v_add_f32_e32 v25, v25, v33
	v_add_f32_e32 v26, v26, v34
	v_add_f32_e32 v27, v27, v35
	v_mov_b32_e32 v56, 0x3f000000
	s_nop 0
	v_fma_f32 v44, v56, v20, -v28
	v_fma_f32 v45, v56, v21, -v29
	v_fma_f32 v46, v56, v22, -v30
	v_fma_f32 v47, v56, v23, -v31
	v_fma_f32 v48, v56, v24, -v32
	v_fma_f32 v49, v56, v25, -v33
	v_fma_f32 v50, v56, v26, -v34
	v_fma_f32 v51, v56, v27, -v35
	v_cvt_pk_bf16_f32 v52, v44, v45
	v_cvt_pk_bf16_f32 v53, v46, v47
	v_cvt_pk_bf16_f32 v54, v48, v49
	v_cvt_pk_bf16_f32 v55, v50, v51
	global_store_dwordx4 v[8:9], v[52:55], off
	v_lshl_add_u64 v[8:9], v[8:9], 0, s[6:7]
	s_waitcnt vmcnt(15)
; __device__ __forceinline__ void phase_pool(const bf16_t* proj, bf16_t* pooled) {
;     ...
;         for (int r = 0; r < 16; ++r) {
;             float f[8]; unpack8(*(const u32x4*)(src + (ptrdiff_t)r * PP), f);
;             const int pos = pos0 + r;
;             if (r >= 1 && pos - w >= 0) { float o[8]; unpack8(*(const u32x4*)(src + (ptrdiff_t)(r - w) * PP), o);
; #pragma unroll
;                 for (int e = 0; e < 8; ++e) sum[e] -= o[e]; }
;             const float rc = 1.0f / (float)(pos + 1 < w ? pos + 1 : w);
;             float out[8];
; #pragma unroll
;             for (int e = 0; e < 8; ++e) { sum[e] += f[e]; out[e] = sum[e] * rc - f[e]; }
;             *(u32x4*)(pooled + (size_t)(r0 + r) * DM + cgi * 8) = pack8(out);
	v_lshlrev_b32_e32 v36, 16, v136
	v_and_b32_e32 v37, 0xffff0000, v136
	v_lshlrev_b32_e32 v38, 16, v137
	v_and_b32_e32 v39, 0xffff0000, v137
	v_lshlrev_b32_e32 v40, 16, v138
	v_and_b32_e32 v41, 0xffff0000, v138
	v_lshlrev_b32_e32 v42, 16, v139
	v_and_b32_e32 v43, 0xffff0000, v139
	v_sub_f32_e32 v20, v20, v36
	v_sub_f32_e32 v21, v21, v37
	v_sub_f32_e32 v22, v22, v38
	v_sub_f32_e32 v23, v23, v39
	v_sub_f32_e32 v24, v24, v40
	v_sub_f32_e32 v25, v25, v41
	v_sub_f32_e32 v26, v26, v42
	v_sub_f32_e32 v27, v27, v43
	v_lshlrev_b32_e32 v28, 16, v144
	v_and_b32_e32 v29, 0xffff0000, v144
	v_lshlrev_b32_e32 v30, 16, v145
	v_and_b32_e32 v31, 0xffff0000, v145
	v_lshlrev_b32_e32 v32, 16, v146
	v_and_b32_e32 v33, 0xffff0000, v146
	v_lshlrev_b32_e32 v34, 16, v147
	v_and_b32_e32 v35, 0xffff0000, v147
	v_add_f32_e32 v20, v20, v28
	v_add_f32_e32 v21, v21, v29
	v_add_f32_e32 v22, v22, v30
	v_add_f32_e32 v23, v23, v31
	v_add_f32_e32 v24, v24, v32
	v_add_f32_e32 v25, v25, v33
	v_add_f32_e32 v26, v26, v34
	v_add_f32_e32 v27, v27, v35
	v_mov_b32_e32 v56, 0x3f000000
	s_nop 0
	v_fma_f32 v44, v56, v20, -v28
	v_fma_f32 v45, v56, v21, -v29
	v_fma_f32 v46, v56, v22, -v30
	v_fma_f32 v47, v56, v23, -v31
	v_fma_f32 v48, v56, v24, -v32
	v_fma_f32 v49, v56, v25, -v33
	v_fma_f32 v50, v56, v26, -v34
	v_fma_f32 v51, v56, v27, -v35
	v_cvt_pk_bf16_f32 v52, v44, v45
	v_cvt_pk_bf16_f32 v53, v46, v47
	v_cvt_pk_bf16_f32 v54, v48, v49
	v_cvt_pk_bf16_f32 v55, v50, v51
	global_store_dwordx4 v[8:9], v[52:55], off
	v_lshl_add_u64 v[8:9], v[8:9], 0, s[6:7]
	s_waitcnt vmcnt(15)
	v_lshlrev_b32_e32 v36, 16, v140
	v_and_b32_e32 v37, 0xffff0000, v140
	v_lshlrev_b32_e32 v38, 16, v141
	v_and_b32_e32 v39, 0xffff0000, v141
	v_lshlrev_b32_e32 v40, 16, v142
	v_and_b32_e32 v41, 0xffff0000, v142
	v_lshlrev_b32_e32 v42, 16, v143
	v_and_b32_e32 v43, 0xffff0000, v143
	v_sub_f32_e32 v20, v20, v36
	v_sub_f32_e32 v21, v21, v37
	v_sub_f32_e32 v22, v22, v38
	v_sub_f32_e32 v23, v23, v39
	v_sub_f32_e32 v24, v24, v40
	v_sub_f32_e32 v25, v25, v41
	v_sub_f32_e32 v26, v26, v42
	v_sub_f32_e32 v27, v27, v43
	v_lshlrev_b32_e32 v28, 16, v148
	v_and_b32_e32 v29, 0xffff0000, v148
	v_lshlrev_b32_e32 v30, 16, v149
	v_and_b32_e32 v31, 0xffff0000, v149
	v_lshlrev_b32_e32 v32, 16, v150
	v_and_b32_e32 v33, 0xffff0000, v150
	v_lshlrev_b32_e32 v34, 16, v151
	v_and_b32_e32 v35, 0xffff0000, v151
	v_add_f32_e32 v20, v20, v28
	v_add_f32_e32 v21, v21, v29
	v_add_f32_e32 v22, v22, v30
	v_add_f32_e32 v23, v23, v31
	v_add_f32_e32 v24, v24, v32
	v_add_f32_e32 v25, v25, v33
	v_add_f32_e32 v26, v26, v34
	v_add_f32_e32 v27, v27, v35
	v_mov_b32_e32 v56, 0x3f000000
	s_nop 0
	v_fma_f32 v44, v56, v20, -v28
	v_fma_f32 v45, v56, v21, -v29
	v_fma_f32 v46, v56, v22, -v30
	v_fma_f32 v47, v56, v23, -v31
	v_fma_f32 v48, v56, v24, -v32
	v_fma_f32 v49, v56, v25, -v33
	v_fma_f32 v50, v56, v26, -v34
	v_fma_f32 v51, v56, v27, -v35
	v_cvt_pk_bf16_f32 v52, v44, v45
	v_cvt_pk_bf16_f32 v53, v46, v47
	v_cvt_pk_bf16_f32 v54, v48, v49
	v_cvt_pk_bf16_f32 v55, v50, v51
	global_store_dwordx4 v[8:9], v[52:55], off
	v_lshl_add_u64 v[8:9], v[8:9], 0, s[6:7]
	s_waitcnt vmcnt(15)
	v_lshlrev_b32_e32 v36, 16, v144
	v_and_b32_e32 v37, 0xffff0000, v144
	v_lshlrev_b32_e32 v38, 16, v145
	v_and_b32_e32 v39, 0xffff0000, v145
	v_lshlrev_b32_e32 v40, 16, v146
	v_and_b32_e32 v41, 0xffff0000, v146
	v_lshlrev_b32_e32 v42, 16, v147
	v_and_b32_e32 v43, 0xffff0000, v147
	v_sub_f32_e32 v20, v20, v36
	v_sub_f32_e32 v21, v21, v37
	v_sub_f32_e32 v22, v22, v38
	v_sub_f32_e32 v23, v23, v39
	v_sub_f32_e32 v24, v24, v40
	v_sub_f32_e32 v25, v25, v41
	v_sub_f32_e32 v26, v26, v42
	v_sub_f32_e32 v27, v27, v43
	v_lshlrev_b32_e32 v28, 16, v152
	v_and_b32_e32 v29, 0xffff0000, v152
	v_lshlrev_b32_e32 v30, 16, v153
	v_and_b32_e32 v31, 0xffff0000, v153
	v_lshlrev_b32_e32 v32, 16, v154
	v_and_b32_e32 v33, 0xffff0000, v154
	v_lshlrev_b32_e32 v34, 16, v155
	v_and_b32_e32 v35, 0xffff0000, v155
	v_add_f32_e32 v20, v20, v28
	v_add_f32_e32 v21, v21, v29
	v_add_f32_e32 v22, v22, v30
	v_add_f32_e32 v23, v23, v31
	v_add_f32_e32 v24, v24, v32
	v_add_f32_e32 v25, v25, v33
	v_add_f32_e32 v26, v26, v34
	v_add_f32_e32 v27, v27, v35
	v_mov_b32_e32 v56, 0x3f000000
	s_nop 0
	v_fma_f32 v44, v56, v20, -v28
	v_fma_f32 v45, v56, v21, -v29
	v_fma_f32 v46, v56, v22, -v30
	v_fma_f32 v47, v56, v23, -v31
	v_fma_f32 v48, v56, v24, -v32
	v_fma_f32 v49, v56, v25, -v33
	v_fma_f32 v50, v56, v26, -v34
	v_fma_f32 v51, v56, v27, -v35
	v_cvt_pk_bf16_f32 v52, v44, v45
	v_cvt_pk_bf16_f32 v53, v46, v47
	v_cvt_pk_bf16_f32 v54, v48, v49
	v_cvt_pk_bf16_f32 v55, v50, v51
	global_store_dwordx4 v[8:9], v[52:55], off
	v_lshl_add_u64 v[8:9], v[8:9], 0, s[6:7]
	s_waitcnt vmcnt(15)
	v_lshlrev_b32_e32 v36, 16, v148
	v_and_b32_e32 v37, 0xffff0000, v148
	v_lshlrev_b32_e32 v38, 16, v149
	v_and_b32_e32 v39, 0xffff0000, v149
	v_lshlrev_b32_e32 v40, 16, v150
	v_and_b32_e32 v41, 0xffff0000, v150
	v_lshlrev_b32_e32 v42, 16, v151
	v_and_b32_e32 v43, 0xffff0000, v151
	v_sub_f32_e32 v20, v20, v36
	v_sub_f32_e32 v21, v21, v37
	v_sub_f32_e32 v22, v22, v38
	v_sub_f32_e32 v23, v23, v39
	v_sub_f32_e32 v24, v24, v40
	v_sub_f32_e32 v25, v25, v41
	v_sub_f32_e32 v26, v26, v42
	v_sub_f32_e32 v27, v27, v43
	v_lshlrev_b32_e32 v28, 16, v156
	v_and_b32_e32 v29, 0xffff0000, v156
	v_lshlrev_b32_e32 v30, 16, v157
	v_and_b32_e32 v31, 0xffff0000, v157
	v_lshlrev_b32_e32 v32, 16, v158
	v_and_b32_e32 v33, 0xffff0000, v158
	v_lshlrev_b32_e32 v34, 16, v159
	v_and_b32_e32 v35, 0xffff0000, v159
	v_add_f32_e32 v20, v20, v28
	v_add_f32_e32 v21, v21, v29
	v_add_f32_e32 v22, v22, v30
	v_add_f32_e32 v23, v23, v31
	v_add_f32_e32 v24, v24, v32
	v_add_f32_e32 v25, v25, v33
	v_add_f32_e32 v26, v26, v34
	v_add_f32_e32 v27, v27, v35
	v_mov_b32_e32 v56, 0x3f000000
	s_nop 0
	v_fma_f32 v44, v56, v20, -v28
	v_fma_f32 v45, v56, v21, -v29
	v_fma_f32 v46, v56, v22, -v30
	v_fma_f32 v47, v56, v23, -v31
	v_fma_f32 v48, v56, v24, -v32
	v_fma_f32 v49, v56, v25, -v33
	v_fma_f32 v50, v56, v26, -v34
	v_fma_f32 v51, v56, v27, -v35
	v_cvt_pk_bf16_f32 v52, v44, v45
	v_cvt_pk_bf16_f32 v53, v46, v47
	v_cvt_pk_bf16_f32 v54, v48, v49
	v_cvt_pk_bf16_f32 v55, v50, v51
	global_store_dwordx4 v[8:9], v[52:55], off
	v_lshl_add_u64 v[8:9], v[8:9], 0, s[6:7]
	s_waitcnt vmcnt(15)
; __device__ __forceinline__ void phase_pool(const bf16_t* proj, bf16_t* pooled) {
;     ...
;         for (int r = 0; r < 16; ++r) {
;             float f[8]; unpack8(*(const u32x4*)(src + (ptrdiff_t)r * PP), f);
;             const int pos = pos0 + r;
;             if (r >= 1 && pos - w >= 0) { float o[8]; unpack8(*(const u32x4*)(src + (ptrdiff_t)(r - w) * PP), o);
; #pragma unroll
;                 for (int e = 0; e < 8; ++e) sum[e] -= o[e]; }
;             const float rc = 1.0f / (float)(pos + 1 < w ? pos + 1 : w);
;             float out[8];
; #pragma unroll
;             for (int e = 0; e < 8; ++e) { sum[e] += f[e]; out[e] = sum[e] * rc - f[e]; }
;             *(u32x4*)(pooled + (size_t)(r0 + r) * DM + cgi * 8) = pack8(out);
	v_lshlrev_b32_e32 v36, 16, v152
	v_and_b32_e32 v37, 0xffff0000, v152
	v_lshlrev_b32_e32 v38, 16, v153
	v_and_b32_e32 v39, 0xffff0000, v153
	v_lshlrev_b32_e32 v40, 16, v154
	v_and_b32_e32 v41, 0xffff0000, v154
	v_lshlrev_b32_e32 v42, 16, v155
	v_and_b32_e32 v43, 0xffff0000, v155
	v_sub_f32_e32 v20, v20, v36
	v_sub_f32_e32 v21, v21, v37
	v_sub_f32_e32 v22, v22, v38
	v_sub_f32_e32 v23, v23, v39
	v_sub_f32_e32 v24, v24, v40
	v_sub_f32_e32 v25, v25, v41
	v_sub_f32_e32 v26, v26, v42
	v_sub_f32_e32 v27, v27, v43
	v_lshlrev_b32_e32 v28, 16, v160
	v_and_b32_e32 v29, 0xffff0000, v160
	v_lshlrev_b32_e32 v30, 16, v161
	v_and_b32_e32 v31, 0xffff0000, v161
	v_lshlrev_b32_e32 v32, 16, v162
	v_and_b32_e32 v33, 0xffff0000, v162
	v_lshlrev_b32_e32 v34, 16, v163
	v_and_b32_e32 v35, 0xffff0000, v163
	v_add_f32_e32 v20, v20, v28
	v_add_f32_e32 v21, v21, v29
	v_add_f32_e32 v22, v22, v30
	v_add_f32_e32 v23, v23, v31
	v_add_f32_e32 v24, v24, v32
	v_add_f32_e32 v25, v25, v33
	v_add_f32_e32 v26, v26, v34
	v_add_f32_e32 v27, v27, v35
	v_mov_b32_e32 v56, 0x3f000000
	s_nop 0
	v_fma_f32 v44, v56, v20, -v28
	v_fma_f32 v45, v56, v21, -v29
	v_fma_f32 v46, v56, v22, -v30
	v_fma_f32 v47, v56, v23, -v31
	v_fma_f32 v48, v56, v24, -v32
	v_fma_f32 v49, v56, v25, -v33
	v_fma_f32 v50, v56, v26, -v34
	v_fma_f32 v51, v56, v27, -v35
	v_cvt_pk_bf16_f32 v52, v44, v45
	v_cvt_pk_bf16_f32 v53, v46, v47
	v_cvt_pk_bf16_f32 v54, v48, v49
	v_cvt_pk_bf16_f32 v55, v50, v51
	global_store_dwordx4 v[8:9], v[52:55], off
	v_lshl_add_u64 v[8:9], v[8:9], 0, s[6:7]
	s_waitcnt vmcnt(15)
	v_lshlrev_b32_e32 v36, 16, v156
	v_and_b32_e32 v37, 0xffff0000, v156
	v_lshlrev_b32_e32 v38, 16, v157
	v_and_b32_e32 v39, 0xffff0000, v157
	v_lshlrev_b32_e32 v40, 16, v158
	v_and_b32_e32 v41, 0xffff0000, v158
	v_lshlrev_b32_e32 v42, 16, v159
	v_and_b32_e32 v43, 0xffff0000, v159
	v_sub_f32_e32 v20, v20, v36
	v_sub_f32_e32 v21, v21, v37
	v_sub_f32_e32 v22, v22, v38
	v_sub_f32_e32 v23, v23, v39
	v_sub_f32_e32 v24, v24, v40
	v_sub_f32_e32 v25, v25, v41
	v_sub_f32_e32 v26, v26, v42
	v_sub_f32_e32 v27, v27, v43
	v_lshlrev_b32_e32 v28, 16, v164
	v_and_b32_e32 v29, 0xffff0000, v164
	v_lshlrev_b32_e32 v30, 16, v165
	v_and_b32_e32 v31, 0xffff0000, v165
	v_lshlrev_b32_e32 v32, 16, v166
	v_and_b32_e32 v33, 0xffff0000, v166
	v_lshlrev_b32_e32 v34, 16, v167
	v_and_b32_e32 v35, 0xffff0000, v167
	v_add_f32_e32 v20, v20, v28
	v_add_f32_e32 v21, v21, v29
	v_add_f32_e32 v22, v22, v30
	v_add_f32_e32 v23, v23, v31
	v_add_f32_e32 v24, v24, v32
	v_add_f32_e32 v25, v25, v33
	v_add_f32_e32 v26, v26, v34
	v_add_f32_e32 v27, v27, v35
	v_mov_b32_e32 v56, 0x3f000000
	s_nop 0
	v_fma_f32 v44, v56, v20, -v28
	v_fma_f32 v45, v56, v21, -v29
	v_fma_f32 v46, v56, v22, -v30
	v_fma_f32 v47, v56, v23, -v31
	v_fma_f32 v48, v56, v24, -v32
	v_fma_f32 v49, v56, v25, -v33
	v_fma_f32 v50, v56, v26, -v34
	v_fma_f32 v51, v56, v27, -v35
	v_cvt_pk_bf16_f32 v52, v44, v45
	v_cvt_pk_bf16_f32 v53, v46, v47
	v_cvt_pk_bf16_f32 v54, v48, v49
	v_cvt_pk_bf16_f32 v55, v50, v51
	global_store_dwordx4 v[8:9], v[52:55], off
	v_lshl_add_u64 v[8:9], v[8:9], 0, s[6:7]
	s_waitcnt vmcnt(15)
	v_lshlrev_b32_e32 v36, 16, v160
	v_and_b32_e32 v37, 0xffff0000, v160
	v_lshlrev_b32_e32 v38, 16, v161
	v_and_b32_e32 v39, 0xffff0000, v161
	v_lshlrev_b32_e32 v40, 16, v162
	v_and_b32_e32 v41, 0xffff0000, v162
	v_lshlrev_b32_e32 v42, 16, v163
	v_and_b32_e32 v43, 0xffff0000, v163
	v_sub_f32_e32 v20, v20, v36
	v_sub_f32_e32 v21, v21, v37
	v_sub_f32_e32 v22, v22, v38
	v_sub_f32_e32 v23, v23, v39
	v_sub_f32_e32 v24, v24, v40
	v_sub_f32_e32 v25, v25, v41
	v_sub_f32_e32 v26, v26, v42
	v_sub_f32_e32 v27, v27, v43
	v_lshlrev_b32_e32 v28, 16, v168
	v_and_b32_e32 v29, 0xffff0000, v168
	v_lshlrev_b32_e32 v30, 16, v169
	v_and_b32_e32 v31, 0xffff0000, v169
	v_lshlrev_b32_e32 v32, 16, v170
	v_and_b32_e32 v33, 0xffff0000, v170
	v_lshlrev_b32_e32 v34, 16, v171
	v_and_b32_e32 v35, 0xffff0000, v171
	v_add_f32_e32 v20, v20, v28
	v_add_f32_e32 v21, v21, v29
	v_add_f32_e32 v22, v22, v30
	v_add_f32_e32 v23, v23, v31
	v_add_f32_e32 v24, v24, v32
	v_add_f32_e32 v25, v25, v33
	v_add_f32_e32 v26, v26, v34
	v_add_f32_e32 v27, v27, v35
	v_mov_b32_e32 v56, 0x3f000000
	s_nop 0
	v_fma_f32 v44, v56, v20, -v28
	v_fma_f32 v45, v56, v21, -v29
	v_fma_f32 v46, v56, v22, -v30
	v_fma_f32 v47, v56, v23, -v31
	v_fma_f32 v48, v56, v24, -v32
	v_fma_f32 v49, v56, v25, -v33
	v_fma_f32 v50, v56, v26, -v34
	v_fma_f32 v51, v56, v27, -v35
	v_cvt_pk_bf16_f32 v52, v44, v45
	v_cvt_pk_bf16_f32 v53, v46, v47
	v_cvt_pk_bf16_f32 v54, v48, v49
	v_cvt_pk_bf16_f32 v55, v50, v51
	global_store_dwordx4 v[8:9], v[52:55], off
	v_lshl_add_u64 v[8:9], v[8:9], 0, s[6:7]
	s_waitcnt vmcnt(15)
; __device__ __forceinline__ void phase_pool(const bf16_t* proj, bf16_t* pooled) {
;     ...
;         for (int r = 0; r < 16; ++r) {
;             float f[8]; unpack8(*(const u32x4*)(src + (ptrdiff_t)r * PP), f);
;             const int pos = pos0 + r;
;             if (r >= 1 && pos - w >= 0) { float o[8]; unpack8(*(const u32x4*)(src + (ptrdiff_t)(r - w) * PP), o);
; #pragma unroll
;                 for (int e = 0; e < 8; ++e) sum[e] -= o[e]; }
;             const float rc = 1.0f / (float)(pos + 1 < w ? pos + 1 : w);
;             float out[8];
; #pragma unroll
;             for (int e = 0; e < 8; ++e) { sum[e] += f[e]; out[e] = sum[e] * rc - f[e]; }
;             *(u32x4*)(pooled + (size_t)(r0 + r) * DM + cgi * 8) = pack8(out);
;         }
	v_lshlrev_b32_e32 v36, 16, v164
	v_and_b32_e32 v37, 0xffff0000, v164
	v_lshlrev_b32_e32 v38, 16, v165
	v_and_b32_e32 v39, 0xffff0000, v165
	v_lshlrev_b32_e32 v40, 16, v166
	v_and_b32_e32 v41, 0xffff0000, v166
	v_lshlrev_b32_e32 v42, 16, v167
	v_and_b32_e32 v43, 0xffff0000, v167
	v_sub_f32_e32 v20, v20, v36
	v_sub_f32_e32 v21, v21, v37
	v_sub_f32_e32 v22, v22, v38
	v_sub_f32_e32 v23, v23, v39
	v_sub_f32_e32 v24, v24, v40
	v_sub_f32_e32 v25, v25, v41
	v_sub_f32_e32 v26, v26, v42
	v_sub_f32_e32 v27, v27, v43
	v_lshlrev_b32_e32 v28, 16, v172
	v_and_b32_e32 v29, 0xffff0000, v172
	v_lshlrev_b32_e32 v30, 16, v173
	v_and_b32_e32 v31, 0xffff0000, v173
	v_lshlrev_b32_e32 v32, 16, v174
	v_and_b32_e32 v33, 0xffff0000, v174
	v_lshlrev_b32_e32 v34, 16, v175
	v_and_b32_e32 v35, 0xffff0000, v175
	v_add_f32_e32 v20, v20, v28
	v_add_f32_e32 v21, v21, v29
	v_add_f32_e32 v22, v22, v30
	v_add_f32_e32 v23, v23, v31
	v_add_f32_e32 v24, v24, v32
	v_add_f32_e32 v25, v25, v33
	v_add_f32_e32 v26, v26, v34
	v_add_f32_e32 v27, v27, v35
	v_mov_b32_e32 v56, 0x3f000000
	s_nop 0
	v_fma_f32 v44, v56, v20, -v28
	v_fma_f32 v45, v56, v21, -v29
	v_fma_f32 v46, v56, v22, -v30
	v_fma_f32 v47, v56, v23, -v31
	v_fma_f32 v48, v56, v24, -v32
	v_fma_f32 v49, v56, v25, -v33
	v_fma_f32 v50, v56, v26, -v34
	v_fma_f32 v51, v56, v27, -v35
	v_cvt_pk_bf16_f32 v52, v44, v45
	v_cvt_pk_bf16_f32 v53, v46, v47
	v_cvt_pk_bf16_f32 v54, v48, v49
	v_cvt_pk_bf16_f32 v55, v50, v51
	global_store_dwordx4 v[8:9], v[52:55], off
	v_lshl_add_u64 v[8:9], v[8:9], 0, s[6:7]
	s_waitcnt vmcnt(15)
	v_lshlrev_b32_e32 v36, 16, v168
	v_and_b32_e32 v37, 0xffff0000, v168
	v_lshlrev_b32_e32 v38, 16, v169
	v_and_b32_e32 v39, 0xffff0000, v169
	v_lshlrev_b32_e32 v40, 16, v170
	v_and_b32_e32 v41, 0xffff0000, v170
	v_lshlrev_b32_e32 v42, 16, v171
	v_and_b32_e32 v43, 0xffff0000, v171
	v_sub_f32_e32 v20, v20, v36
	v_sub_f32_e32 v21, v21, v37
	v_sub_f32_e32 v22, v22, v38
	v_sub_f32_e32 v23, v23, v39
	v_sub_f32_e32 v24, v24, v40
	v_sub_f32_e32 v25, v25, v41
	v_sub_f32_e32 v26, v26, v42
	v_sub_f32_e32 v27, v27, v43
	v_lshlrev_b32_e32 v28, 16, v176
	v_and_b32_e32 v29, 0xffff0000, v176
	v_lshlrev_b32_e32 v30, 16, v177
	v_and_b32_e32 v31, 0xffff0000, v177
	v_lshlrev_b32_e32 v32, 16, v178
	v_and_b32_e32 v33, 0xffff0000, v178
	v_lshlrev_b32_e32 v34, 16, v179
	v_and_b32_e32 v35, 0xffff0000, v179
	v_add_f32_e32 v20, v20, v28
	v_add_f32_e32 v21, v21, v29
	v_add_f32_e32 v22, v22, v30
	v_add_f32_e32 v23, v23, v31
	v_add_f32_e32 v24, v24, v32
	v_add_f32_e32 v25, v25, v33
	v_add_f32_e32 v26, v26, v34
	v_add_f32_e32 v27, v27, v35
	v_mov_b32_e32 v56, 0x3f000000
	s_nop 0
	v_fma_f32 v44, v56, v20, -v28
	v_fma_f32 v45, v56, v21, -v29
	v_fma_f32 v46, v56, v22, -v30
	v_fma_f32 v47, v56, v23, -v31
	v_fma_f32 v48, v56, v24, -v32
	v_fma_f32 v49, v56, v25, -v33
	v_fma_f32 v50, v56, v26, -v34
	v_fma_f32 v51, v56, v27, -v35
	v_cvt_pk_bf16_f32 v52, v44, v45
	v_cvt_pk_bf16_f32 v53, v46, v47
	v_cvt_pk_bf16_f32 v54, v48, v49
	v_cvt_pk_bf16_f32 v55, v50, v51
	global_store_dwordx4 v[8:9], v[52:55], off
	v_lshl_add_u64 v[8:9], v[8:9], 0, s[6:7]
	s_waitcnt vmcnt(15)
	v_lshlrev_b32_e32 v36, 16, v172
	v_and_b32_e32 v37, 0xffff0000, v172
	v_lshlrev_b32_e32 v38, 16, v173
	v_and_b32_e32 v39, 0xffff0000, v173
	v_lshlrev_b32_e32 v40, 16, v174
	v_and_b32_e32 v41, 0xffff0000, v174
	v_lshlrev_b32_e32 v42, 16, v175
	v_and_b32_e32 v43, 0xffff0000, v175
	v_sub_f32_e32 v20, v20, v36
	v_sub_f32_e32 v21, v21, v37
	v_sub_f32_e32 v22, v22, v38
	v_sub_f32_e32 v23, v23, v39
	v_sub_f32_e32 v24, v24, v40
	v_sub_f32_e32 v25, v25, v41
	v_sub_f32_e32 v26, v26, v42
	v_sub_f32_e32 v27, v27, v43
	v_lshlrev_b32_e32 v28, 16, v180
	v_and_b32_e32 v29, 0xffff0000, v180
	v_lshlrev_b32_e32 v30, 16, v181
	v_and_b32_e32 v31, 0xffff0000, v181
	v_lshlrev_b32_e32 v32, 16, v182
	v_and_b32_e32 v33, 0xffff0000, v182
	v_lshlrev_b32_e32 v34, 16, v183
	v_and_b32_e32 v35, 0xffff0000, v183
	v_add_f32_e32 v20, v20, v28
	v_add_f32_e32 v21, v21, v29
	v_add_f32_e32 v22, v22, v30
	v_add_f32_e32 v23, v23, v31
	v_add_f32_e32 v24, v24, v32
	v_add_f32_e32 v25, v25, v33
	v_add_f32_e32 v26, v26, v34
	v_add_f32_e32 v27, v27, v35
	v_mov_b32_e32 v56, 0x3f000000
	s_nop 0
	v_fma_f32 v44, v56, v20, -v28
	v_fma_f32 v45, v56, v21, -v29
	v_fma_f32 v46, v56, v22, -v30
	v_fma_f32 v47, v56, v23, -v31
	v_fma_f32 v48, v56, v24, -v32
	v_fma_f32 v49, v56, v25, -v33
	v_fma_f32 v50, v56, v26, -v34
	v_fma_f32 v51, v56, v27, -v35
	v_cvt_pk_bf16_f32 v52, v44, v45
	v_cvt_pk_bf16_f32 v53, v46, v47
	v_cvt_pk_bf16_f32 v54, v48, v49
	v_cvt_pk_bf16_f32 v55, v50, v51
	global_store_dwordx4 v[8:9], v[52:55], off
.Lmy_pool_next:
	s_add_u32 s10, s10, s94
	s_branch .Lmy_pool_item
.Lmy_pool_done:
.LBB0_322:
	s_or_b64 exec, exec, s[0:1]
	s_mov_b64 s[0:1], 0

; __global__ void __launch_bounds__(NTHR, 2) fwd_kernel(Args a) {
;     ...
;         if (ph + 1 < a.ph_hi) {
;             if (!xb_ready) { grid.sync(); xb = xcd_barrier_post(barw, bst); xb_ready = true; }
;             else { xcd_barrier(xb); if (DUP_K == 100) { xcd_barrier(xb); xcd_barrier(xb); } }
;         }
.LBB0_475:
	s_add_i32 s92, s92, 1
	s_mov_b64 s[4:5], -1
	s_cmp_ge_i32 s92, s93
	s_mov_b64 s[0:1], -1
	s_cbranch_scc1 .Lhop_15
	s_cmp_eq_u32 s92, 1
	s_cbranch_scc1 .Lmy_skipbar
	s_cmp_eq_u32 s92, 19
	s_cbranch_scc0 .Lmy_noskip
.Lmy_skipbar:
	v_readlane_b32 s4, v255, 5
	v_readlane_b32 s5, v255, 6
	s_waitcnt lgkmcnt(0)
	s_barrier
	s_mov_b64 s[0:1], 0
	s_branch .Lhop_15
.Lmy_noskip:
	v_readlane_b32 s0, v255, 5
	v_readlane_b32 s1, v255, 6
	s_xor_b64 s[0:1], s[0:1], -1
	s_andn2_b64 vcc, exec, s[0:1]
	s_mov_b64 s[0:1], -1
	s_cbranch_vccnz .LBB0_492
	s_waitcnt vmcnt(0)
	s_barrier
	s_mov_b64 s[0:1], exec
	v_readlane_b32 s6, v254, 41
	v_readlane_b32 s7, v254, 42
	s_and_b64 s[6:7], s[0:1], s[6:7]
	s_mov_b64 exec, s[6:7]
	s_cbranch_execz .LBB0_487
	buffer_wbl2 sc1
	s_load_dwordx2 s[6:7], s[74:75], 0x58
	s_mov_b64 s[8:9], exec
	v_mbcnt_lo_u32_b32 v2, s8, 0
	v_mbcnt_hi_u32_b32 v2, s9, v2
	v_cmp_eq_u32_e32 vcc, 0, v2
	s_waitcnt lgkmcnt(0)
	global_load_dword v0, v1, s[6:7] offset:40
	s_and_saveexec_b64 s[10:11], vcc
	s_cbranch_execz .LBB0_480
	s_bcnt1_i32_b64 s8, s[8:9]
	v_mov_b32_e32 v3, s8
	global_atomic_add v3, v1, v3, s[6:7] offset:32 sc0
